# SO1 + f32->bf16 pack: hipcc's integer RNE bit trick (6 instr) replaced by v_cvt_pk_bf16_f32 at 315 sites (bit-identical for finite values; RNE, denormals kept)
# speedup vs baseline: 1.0030x; 1.0030x over previous
.LBB0_14:
	s_cmpk_gt_i32 s72, 0xbf
	s_mov_b64 s[8:9], -1
	s_cbranch_scc0 .LBB0_30
	s_add_i32 s8, s72, 0xffffff40
	s_lshl_b32 s9, s72, 6
	s_lshr_b32 s10, s8, 4
	s_and_b32 s9, s9, 0x3c0
	v_lshl_or_b32 v74, s10, 8, v81
	s_lshl_b32 s18, s9, 2
	v_lshlrev_b64 v[66:67], 12, v[74:75]
	s_cmp_lt_u32 s8, 32
	s_waitcnt lgkmcnt(0)
	v_lshl_add_u64 v[66:67], s[24:25], 0, v[66:67]
	s_cselect_b32 s11, s35, 0x88
	v_readlane_b32 s14, v255, 11
	v_lshl_add_u64 v[66:67], v[66:67], 0, s[18:19]
	v_mov_b32_e32 v87, v75
	v_readlane_b32 s15, v255, 12
	s_add_u32 s14, s14, s11
	v_lshl_add_u64 v[128:129], v[66:67], 0, v[86:87]
	s_addc_u32 s15, s15, 0
	global_load_dwordx4 v[66:69], v[128:129], off offset:48
	global_load_dwordx4 v[70:73], v[128:129], off offset:32
	s_load_dwordx2 s[14:15], s[14:15], 0x0
	s_lshl_b32 s11, s8, 14
	s_and_b32 s11, s11, 0x40000
	v_or_b32_e32 v74, s9, v1
	v_lshlrev_b32_e32 v74, 2, v74
	s_waitcnt lgkmcnt(0)
	s_add_u32 s14, s14, s11
	s_addc_u32 s15, s15, 0
	v_lshl_add_u64 v[116:117], s[14:15], 0, v[76:77]
	v_lshl_add_u64 v[116:117], v[116:117], 0, v[74:75]
	v_add_co_u32_e32 v118, vcc, s38, v116
	global_load_dwordx4 v[108:111], v[128:129], off offset:16
	global_load_dwordx4 v[112:115], v[128:129], off
	v_addc_co_u32_e32 v119, vcc, 0, v117, vcc
	v_add_co_u32_e32 v120, vcc, s0, v116
	v_add_u32_e32 v138, 0x8000, v91
	s_nop 0
	v_addc_co_u32_e32 v121, vcc, 0, v117, vcc
	v_add_co_u32_e32 v122, vcc, s39, v116
	s_mov_b32 s11, s19
	s_nop 0
	v_addc_co_u32_e32 v123, vcc, 0, v117, vcc
	v_add_co_u32_e32 v124, vcc, s40, v116
	s_lshl_b64 s[10:11], s[10:11], 17
	s_nop 0
	v_addc_co_u32_e32 v125, vcc, 0, v117, vcc
	v_add_co_u32_e32 v126, vcc, s41, v116
	s_waitcnt vmcnt(3)
	v_mul_f32_e32 v67, v67, v67
	v_addc_co_u32_e32 v127, vcc, 0, v117, vcc
	v_add_co_u32_e32 v130, vcc, s42, v116
	s_waitcnt vmcnt(2)
	v_mul_f32_e32 v139, v71, v71
	v_addc_co_u32_e32 v131, vcc, 0, v117, vcc
	v_add_co_u32_e32 v132, vcc, s43, v116
	v_fmac_f32_e32 v139, v70, v70
	s_nop 0
	v_addc_co_u32_e32 v133, vcc, 0, v117, vcc
	global_load_dword v74, v[116:117], off
	global_load_dword v87, v[118:119], off
	global_load_dword v89, v[120:121], off
	global_load_dword v107, v[122:123], off
	global_load_dword v134, v[124:125], off
	global_load_dword v135, v[126:127], off
	global_load_dword v136, v[130:131], off
	global_load_dword v137, v[132:133], off
	global_load_dwordx4 v[116:119], v[128:129], off offset:64
	global_load_dwordx4 v[120:123], v[128:129], off offset:80
	s_nop 0
	global_load_dwordx4 v[124:127], v[128:129], off offset:96
	s_nop 0
	global_load_dwordx4 v[128:131], v[128:129], off offset:112
	s_waitcnt vmcnt(12)
	v_mul_f32_e32 v113, v113, v113
	v_mul_f32_e32 v109, v109, v109
	v_fmac_f32_e32 v113, v112, v112
	v_fmac_f32_e32 v109, v108, v108
	v_fmac_f32_e32 v113, v114, v114
	v_fmac_f32_e32 v109, v110, v110
	v_fmac_f32_e32 v139, v72, v72
	v_fmac_f32_e32 v113, v115, v115
	v_fmac_f32_e32 v109, v111, v111
	v_fmac_f32_e32 v67, v66, v66
	v_fmac_f32_e32 v139, v73, v73
	v_add_f32_e32 v72, v113, v109
	v_fmac_f32_e32 v67, v68, v68
	s_waitcnt vmcnt(11)
	ds_write_b32 v98, v74 offset:32768
	s_waitcnt vmcnt(10)
	ds_write_b32 v98, v87 offset:34848
	s_waitcnt vmcnt(9)
	ds_write_b32 v98, v89 offset:36928
	s_waitcnt vmcnt(8)
	ds_write_b32 v98, v107 offset:39008
	s_waitcnt vmcnt(7)
	ds_write_b32 v98, v134 offset:41088
	s_waitcnt vmcnt(6)
	ds_write_b32 v98, v135 offset:43168
	s_waitcnt vmcnt(5)
	ds_write_b32 v98, v136 offset:45248
	s_waitcnt vmcnt(4)
	ds_write_b32 v98, v137 offset:47328
	v_add_f32_e32 v74, v72, v139
	v_fmac_f32_e32 v67, v69, v69
	v_add_f32_e32 v66, v74, v67
	s_waitcnt vmcnt(3)
	v_mul_f32_e32 v67, v117, v117
	v_fmac_f32_e32 v67, v116, v116
	v_fmac_f32_e32 v67, v118, v118
	v_fmac_f32_e32 v67, v119, v119
	v_add_f32_e32 v66, v66, v67
	s_waitcnt vmcnt(2)
	v_mul_f32_e32 v67, v121, v121
	v_fmac_f32_e32 v67, v120, v120
	v_fmac_f32_e32 v67, v122, v122
	v_fmac_f32_e32 v67, v123, v123
	v_add_f32_e32 v66, v66, v67
	s_waitcnt vmcnt(1)
	v_mul_f32_e32 v67, v125, v125
	v_fmac_f32_e32 v67, v124, v124
	v_fmac_f32_e32 v67, v126, v126
	v_fmac_f32_e32 v67, v127, v127
	v_add_f32_e32 v66, v66, v67
	s_waitcnt vmcnt(0)
	v_mul_f32_e32 v67, v129, v129
	s_waitcnt lgkmcnt(0)
	s_barrier
	ds_read2_b32 v[70:71], v138 offset1:65
	v_fmac_f32_e32 v67, v128, v128
	v_fmac_f32_e32 v67, v130, v130
	v_fmac_f32_e32 v67, v131, v131
	v_and_b32_e32 v68, 64, v102
	v_add_f32_e32 v66, v66, v67
	v_xor_b32_e32 v67, 32, v102
	v_add_u32_e32 v74, 64, v68
	v_cmp_lt_i32_e32 vcc, v67, v74
	s_waitcnt lgkmcnt(0)
	ds_read2_b32 v[72:73], v138 offset0:130 offset1:195
	v_cndmask_b32_e32 v67, v102, v67, vcc
	v_lshlrev_b32_e32 v87, 2, v67
	ds_bpermute_b32 v67, v87, v66
	s_waitcnt lgkmcnt(1)
	v_bfe_u32 v68, v72, 16, 1
	v_add3_u32 v68, v72, v68, s44
	s_waitcnt lgkmcnt(0)
	v_add_f32_e32 v72, v66, v67
	v_xor_b32_e32 v66, 1, v102
	v_cmp_lt_i32_e32 vcc, v66, v74
	v_bfe_u32 v69, v73, 16, 1
	s_nop 0
	v_cndmask_b32_e32 v66, v102, v66, vcc
	v_lshlrev_b32_e32 v66, 2, v66
	ds_bpermute_b32 v89, v66, v72
	v_add3_u32 v66, v73, v69, s44
	v_lshrrev_b32_e32 v68, 16, v68
	v_cvt_pk_bf16_f32 v70, v70, v71
	v_and_or_b32 v71, v66, s45, v68
	s_waitcnt lgkmcnt(0)
	v_max_f32_e32 v69, v89, v89
	v_max_f32_e32 v72, v72, v69
	v_xor_b32_e32 v69, 2, v102
	v_cmp_lt_i32_e32 vcc, v69, v74
	v_add_u32_e32 v68, 0x8400, v91
	ds_read2_b32 v[66:67], v68 offset0:4 offset1:69
	v_cndmask_b32_e32 v69, v102, v69, vcc
	v_lshlrev_b32_e32 v69, 2, v69
	ds_bpermute_b32 v73, v69, v72
	v_lshl_add_u64 v[132:133], v[82:83], 0, s[10:11]
	s_waitcnt lgkmcnt(1)
	s_waitcnt lgkmcnt(0)
	v_max_f32_e32 v73, v73, v73
	v_max_f32_e32 v73, v72, v73
	v_xor_b32_e32 v72, 4, v102
	v_cmp_lt_i32_e32 vcc, v72, v74
	ds_read2_b32 v[68:69], v68 offset0:134 offset1:199
	s_nop 0
	v_cndmask_b32_e32 v72, v102, v72, vcc
	v_lshlrev_b32_e32 v72, 2, v72
	ds_bpermute_b32 v89, v72, v73
	v_cvt_pk_bf16_f32 v72, v66, v67
	s_waitcnt lgkmcnt(1)
	v_bfe_u32 v66, v68, 16, 1
	s_waitcnt lgkmcnt(0)
	v_max_f32_e32 v67, v89, v89
	v_max_f32_e32 v67, v73, v67
	v_xor_b32_e32 v73, 8, v102
	v_cmp_lt_i32_e32 vcc, v73, v74
	v_add3_u32 v66, v68, v66, s44
	v_bfe_u32 v68, v69, 16, 1
	v_cndmask_b32_e32 v73, v102, v73, vcc
	v_lshlrev_b32_e32 v73, 2, v73
	ds_bpermute_b32 v73, v73, v67
	v_add3_u32 v68, v69, v68, s44
	v_lshrrev_b32_e32 v66, 16, v66
	s_waitcnt lgkmcnt(0)
	v_max_f32_e32 v69, v73, v73
	v_max_f32_e32 v67, v67, v69
	v_xor_b32_e32 v69, 16, v102
	v_cmp_lt_i32_e32 vcc, v69, v74
	v_and_or_b32 v73, v68, s45, v66
	v_or_b32_e32 v66, s9, v90
	v_cndmask_b32_e32 v69, v102, v69, vcc
	v_lshlrev_b32_e32 v69, 2, v69
	ds_bpermute_b32 v89, v69, v67
	v_lshlrev_b32_e32 v74, 7, v66
	v_lshl_add_u64 v[68:69], v[132:133], 0, v[74:75]
	global_store_dwordx4 v[68:69], v[70:73], off
	s_waitcnt lgkmcnt(0)
	v_max_f32_e32 v66, v89, v89
	v_max_f32_e32 v66, v67, v66
	ds_bpermute_b32 v67, v87, v66
	s_barrier
	s_waitcnt lgkmcnt(0)
	s_and_saveexec_b64 s[10:11], s[4:5]
	v_max_f32_e32 v67, v67, v67
	v_max_f32_e32 v66, v66, v66
	v_max_f32_e32 v66, v66, v67
	ds_write_b32 v92, v66
	s_or_b64 exec, exec, s[10:11]
	s_waitcnt lgkmcnt(0)
	s_barrier
	s_mov_b64 s[10:11], exec
	v_readlane_b32 s14, v255, 7
	v_readlane_b32 s15, v255, 8
	s_and_b64 s[14:15], s[10:11], s[14:15]
	s_mov_b64 exec, s[14:15]
	s_cbranch_execz .LBB0_19
	v_mov_b32_e32 v66, s1
	ds_read_b128 v[66:69], v66
	v_mov_b32_e32 v70, s46
	ds_read_b128 v[70:73], v70
	s_mov_b32 s9, s19
	s_lshl_b64 s[14:15], s[8:9], 2
	s_waitcnt lgkmcnt(1)
	v_max_f32_e32 v67, v67, v67
	v_max_f32_e32 v66, v66, v66
	v_max_f32_e32 v66, v66, v67
	v_max3_f32 v66, v66, v68, v69
	s_waitcnt lgkmcnt(0)
	v_max3_f32 v66, v66, v70, v71
	s_add_u32 s14, s2, s14
	v_max3_f32 v66, v66, v72, v73
	s_addc_u32 s15, s3, s15
	global_store_dword v75, v66, s[14:15]

.LBB0_107:
	v_add_u32_e32 v19, 0x8000, v9
	s_waitcnt lgkmcnt(0)
	s_barrier
	ds_read2_b32 v[20:21], v19 offset1:65
	s_ashr_i32 s14, s24, 31
	s_lshr_b32 s14, s14, 28
	s_add_i32 s14, s24, s14
	s_ashr_i32 s15, s14, 4
	s_waitcnt lgkmcnt(0)
	ds_read2_b32 v[22:23], v19 offset0:130 offset1:195
	v_cvt_pk_bf16_f32 v20, v20, v21
	s_waitcnt lgkmcnt(0)
	v_bfe_u32 v19, v22, 16, 1
	v_add3_u32 v19, v22, v19, s21
	v_add_u32_e32 v22, 0x8400, v9
	ds_read2_b32 v[24:25], v22 offset0:4 offset1:69
	v_bfe_u32 v21, v23, 16, 1
	ds_read2_b32 v[26:27], v22 offset0:134 offset1:199
	v_lshrrev_b32_e32 v19, 16, v19
	v_add3_u32 v21, v23, v21, s21
	v_and_or_b32 v21, v21, s22, v19
	s_waitcnt lgkmcnt(1)
	v_bfe_u32 v19, v24, 16, 1
	v_add3_u32 v19, v24, v19, s21
	v_bfe_u32 v22, v25, 16, 1
	v_lshl_or_b32 v24, s15, 6, v8
	s_lshl_b32 s14, s15, 10
	v_lshrrev_b32_e32 v19, 16, v19
	v_add3_u32 v22, v25, v22, s21
	v_ashrrev_i32_e32 v25, 31, v24
	s_sub_i32 s14, s0, s14
	v_and_or_b32 v22, v22, s22, v19
	s_waitcnt lgkmcnt(0)
	v_lshlrev_b64 v[24:25], 11, v[24:25]
	v_lshl_add_u64 v[24:25], s[6:7], 0, v[24:25]
	s_ashr_i32 s15, s14, 31
	v_lshl_add_u64 v[24:25], s[14:15], 1, v[24:25]
	v_cvt_pk_bf16_f32 v23, v26, v27
	v_lshl_add_u64 v[24:25], v[24:25], 0, v[2:3]
	global_store_dwordx4 v[24:25], v[20:23], off
	s_add_i32 s0, s0, s1
	v_add_u32_e32 v11, s2, v11
	s_andn2_b64 vcc, exec, s[12:13]
	s_mov_b32 s24, s23
	s_waitcnt vmcnt(8)
	v_mov_b32_e32 v19, v17
	s_waitcnt vmcnt(7)
	v_mov_b32_e32 v20, v16
	s_waitcnt vmcnt(6)
	v_mov_b32_e32 v21, v15
	s_waitcnt vmcnt(5)
	v_mov_b32_e32 v22, v14
	s_waitcnt vmcnt(4)
	v_mov_b32_e32 v23, v13
	s_waitcnt vmcnt(3)
	v_mov_b32_e32 v24, v5
	s_waitcnt vmcnt(2)
	v_mov_b32_e32 v25, v4
	s_waitcnt vmcnt(1)
	v_mov_b32_e32 v26, v18
	s_barrier
	s_cbranch_vccz .LBB0_117

.LBB0_119:
	s_waitcnt lgkmcnt(0)
	s_barrier
	ds_read2_b32 v[18:19], v7 offset1:65
	ds_read2_b32 v[20:21], v7 offset0:130 offset1:195
	ds_read2_b32 v[22:23], v8 offset0:4 offset1:69
	s_ashr_i32 s21, s15, 31
	s_lshr_b32 s21, s21, 27
	s_waitcnt lgkmcnt(2)
	v_cvt_pk_bf16_f32 v18, v18, v19
	s_waitcnt lgkmcnt(1)
	ds_read2_b32 v[24:25], v8 offset0:134 offset1:199
	s_add_i32 s15, s15, s21
	s_ashr_i32 s15, s15, 5
	v_cvt_pk_bf16_f32 v19, v20, v21
	s_waitcnt lgkmcnt(1)
	v_bfe_u32 v17, v22, 16, 1
	v_add3_u32 v17, v22, v17, s18
	v_bfe_u32 v20, v23, 16, 1
	v_lshl_or_b32 v22, s15, 6, v4
	s_lshl_b32 s21, s15, 11
	v_lshrrev_b32_e32 v17, 16, v17
	v_add3_u32 v20, v23, v20, s18
	v_ashrrev_i32_e32 v23, 31, v22
	s_sub_i32 s22, s16, s21
	v_and_or_b32 v20, v20, s19, v17
	s_waitcnt lgkmcnt(0)
	v_lshlrev_b64 v[22:23], 12, v[22:23]
	v_lshl_add_u64 v[22:23], s[6:7], 0, v[22:23]
	s_ashr_i32 s23, s22, 31
	v_lshl_add_u64 v[22:23], s[22:23], 1, v[22:23]
	v_cvt_pk_bf16_f32 v21, v24, v25
	v_lshl_add_u64 v[22:23], v[22:23], 0, v[2:3]
	global_store_dwordx4 v[22:23], v[18:21], off
	s_add_i32 s16, s16, s17
	s_andn2_b64 vcc, exec, s[12:13]
	s_mov_b32 s15, s20
	s_waitcnt vmcnt(8)
	v_mov_b32_e32 v17, v9
	s_waitcnt vmcnt(7)
	v_mov_b32_e32 v18, v10
	s_waitcnt vmcnt(6)
	v_mov_b32_e32 v19, v11
	s_waitcnt vmcnt(5)
	v_mov_b32_e32 v20, v12
	s_waitcnt vmcnt(4)
	v_mov_b32_e32 v21, v13
	s_waitcnt vmcnt(3)
	v_mov_b32_e32 v22, v14
	s_waitcnt vmcnt(2)
	v_mov_b32_e32 v23, v15
	s_waitcnt vmcnt(1)
	v_mov_b32_e32 v24, v16
	s_barrier
	s_cbranch_vccz .LBB0_122

.LBB0_126:
	s_waitcnt lgkmcnt(0)
	s_barrier
	ds_read2_b32 v[18:19], v8 offset1:65
	ds_read2_b32 v[24:25], v9 offset0:134 offset1:199
	s_ashr_i32 s19, s3, 31
	s_lshr_b32 s19, s19, 27
	s_add_i32 s3, s3, s19
	s_waitcnt lgkmcnt(1)
	ds_read2_b32 v[20:21], v8 offset0:130 offset1:195
	ds_read2_b32 v[22:23], v9 offset0:4 offset1:69
	v_cvt_pk_bf16_f32 v18, v18, v19
	s_waitcnt lgkmcnt(1)
	v_cvt_pk_bf16_f32 v19, v20, v21
	s_waitcnt lgkmcnt(0)
	v_cvt_pk_bf16_f32 v20, v22, v23
	s_ashr_i32 s3, s3, 5
	v_cvt_pk_bf16_f32 v21, v24, v25
	v_lshl_or_b32 v22, s3, 6, v5
	s_lshl_b32 s19, s3, 11
	v_ashrrev_i32_e32 v23, 31, v22
	s_sub_i32 s20, s14, s19
	v_lshlrev_b64 v[22:23], 12, v[22:23]
	v_lshl_add_u64 v[22:23], s[6:7], 0, v[22:23]
	s_ashr_i32 s21, s20, 31
	v_lshl_add_u64 v[22:23], s[20:21], 1, v[22:23]
	v_lshl_add_u64 v[22:23], v[22:23], 0, v[2:3]
	global_store_dwordx4 v[22:23], v[18:21], off
	s_add_i32 s14, s14, s15
	s_andn2_b64 vcc, exec, s[12:13]
	s_mov_b32 s3, s18
	s_waitcnt vmcnt(8)
	v_mov_b32_e32 v18, v10
	s_waitcnt vmcnt(7)
	v_mov_b32_e32 v19, v11
	s_waitcnt vmcnt(6)
	v_mov_b32_e32 v20, v12
	s_waitcnt vmcnt(5)
	v_mov_b32_e32 v21, v13
	s_waitcnt vmcnt(4)
	v_mov_b32_e32 v22, v14
	s_waitcnt vmcnt(3)
	v_mov_b32_e32 v23, v15
	s_waitcnt vmcnt(2)
	v_mov_b32_e32 v24, v16
	s_waitcnt vmcnt(1)
	v_mov_b32_e32 v25, v17
	s_barrier
	s_cbranch_vccz .LBB0_129

.LBB0_135:
	s_or_b64 exec, exec, s[22:23]
	v_mov_b32_e32 v112, v51
	v_mov_b32_e32 v113, v55
	v_mov_b32_e32 v100, v50
	v_mov_b32_e32 v101, v54
	v_pk_mul_f32 v[112:113], v[112:113], v[112:113]
	v_mov_b32_e32 v114, v35
	v_pk_fma_f32 v[100:101], v[100:101], v[100:101], v[112:113]
	v_mov_b32_e32 v112, v52
	v_mov_b32_e32 v113, v56
	v_pk_fma_f32 v[100:101], v[112:113], v[112:113], v[100:101]
	v_mov_b32_e32 v112, v53
	v_mov_b32_e32 v113, v57
	v_mov_b32_e32 v115, v39
	v_pk_fma_f32 v[100:101], v[112:113], v[112:113], v[100:101]
	v_mov_b32_e32 v112, v34
	v_mov_b32_e32 v113, v38
	v_pk_mul_f32 v[114:115], v[114:115], v[114:115]
	v_add_f32_e32 v98, v100, v101
	v_pk_fma_f32 v[112:113], v[112:113], v[112:113], v[114:115]
	v_mov_b32_e32 v114, v36
	v_mov_b32_e32 v115, v40
	v_pk_fma_f32 v[112:113], v[114:115], v[114:115], v[112:113]
	v_mov_b32_e32 v114, v37
	v_mov_b32_e32 v115, v41
	v_pk_fma_f32 v[112:113], v[114:115], v[114:115], v[112:113]
	s_nop 0
	v_add_f32_e32 v98, v98, v113
	v_add_f32_e32 v98, v112, v98
	ds_bpermute_b32 v100, v103, v98
	s_waitcnt lgkmcnt(0)
	v_add_f32_e32 v98, v98, v100
	ds_bpermute_b32 v100, v104, v98
	s_waitcnt lgkmcnt(0)
	v_add_f32_e32 v98, v98, v100
	ds_bpermute_b32 v100, v105, v98
	s_waitcnt lgkmcnt(0)
	v_add_f32_e32 v98, v98, v100
	ds_bpermute_b32 v100, v106, v98
	s_waitcnt lgkmcnt(0)
	v_add_f32_e32 v98, v98, v100
	ds_bpermute_b32 v100, v107, v98
	s_waitcnt lgkmcnt(0)
	v_add_f32_e32 v98, v98, v100
	ds_bpermute_b32 v100, v108, v98
	s_waitcnt lgkmcnt(0)
	v_add_f32_e32 v98, v98, v100
	v_fmamk_f32 v98, v98, 0x3a800000, v99
	v_mul_f32_e32 v100, 0x4b800000, v98
	v_cmp_gt_f32_e32 vcc, s2, v98
	s_nop 1
	v_cndmask_b32_e32 v98, v98, v100, vcc
	v_rsq_f32_e32 v98, v98
	v_lshl_add_u64 v[100:101], v[96:97], 0, v[92:93]
	v_mul_f32_e32 v111, 0x45800000, v98
	v_cndmask_b32_e32 v98, v98, v111, vcc
	v_pk_mul_f32 v[54:55], v[54:55], v[98:99] op_sel_hi:[1,0]
	v_pk_mul_f32 v[50:51], v[50:51], v[98:99] op_sel_hi:[1,0]
	v_pk_mul_f32 v[52:53], v[52:53], v[98:99] op_sel_hi:[1,0]
	s_waitcnt vmcnt(2)
	v_pk_fma_f32 v[54:55], v[66:67], v[54:55], v[46:47]
	v_pk_fma_f32 v[112:113], v[72:73], v[52:53], v[44:45]
	v_pk_fma_f32 v[52:53], v[70:71], v[50:51], v[42:43]
	v_pk_mul_f32 v[56:57], v[56:57], v[98:99] op_sel_hi:[1,0]
	v_pk_fma_f32 v[56:57], v[68:69], v[56:57], v[48:49]
	v_cvt_pk_bf16_f32 v50, v54, v55
	v_cvt_pk_bf16_f32 v51, v56, v57
	v_cvt_pk_bf16_f32 v52, v52, v53
	v_cvt_pk_bf16_f32 v53, v112, v113
	v_add_co_u32_e32 v54, vcc, s25, v100
	v_pk_mul_f32 v[38:39], v[38:39], v[98:99] op_sel_hi:[1,0]
	s_nop 0
	v_addc_co_u32_e32 v55, vcc, 0, v101, vcc
	s_waitcnt vmcnt(0)
	v_pk_fma_f32 v[38:39], v[74:75], v[38:39], v[62:63]
	v_pk_mul_f32 v[34:35], v[34:35], v[98:99] op_sel_hi:[1,0]
	v_pk_mul_f32 v[36:37], v[36:37], v[98:99] op_sel_hi:[1,0]
	global_store_dwordx4 v[54:55], v[50:53], off
	v_pk_mul_f32 v[40:41], v[40:41], v[98:99] op_sel_hi:[1,0]
	s_nop 0
	v_pk_fma_f32 v[50:51], v[80:81], v[36:37], v[60:61]
	v_pk_fma_f32 v[36:37], v[78:79], v[34:35], v[58:59]
	v_pk_fma_f32 v[40:41], v[76:77], v[40:41], v[64:65]
	v_cvt_pk_bf16_f32 v34, v38, v39
	v_cvt_pk_bf16_f32 v35, v40, v41
	v_cvt_pk_bf16_f32 v36, v36, v37
	v_cvt_pk_bf16_f32 v37, v50, v51
	global_store_dwordx4 v[54:55], v[34:37], off offset:1024

.LBB0_139:
	s_or_b64 exec, exec, s[20:21]
	s_waitcnt vmcnt(11)
	v_mov_b32_e32 v112, v3
	s_waitcnt vmcnt(10)
	v_mov_b32_e32 v113, v7
	v_mov_b32_e32 v100, v2
	v_mov_b32_e32 v101, v6
	v_pk_mul_f32 v[112:113], v[112:113], v[112:113]
	s_waitcnt vmcnt(9)
	v_mov_b32_e32 v114, v11
	v_pk_fma_f32 v[100:101], v[100:101], v[100:101], v[112:113]
	v_mov_b32_e32 v112, v4
	v_mov_b32_e32 v113, v8
	v_pk_fma_f32 v[100:101], v[112:113], v[112:113], v[100:101]
	v_mov_b32_e32 v112, v5
	v_mov_b32_e32 v113, v9
	s_waitcnt vmcnt(8)
	v_mov_b32_e32 v115, v15
	v_pk_fma_f32 v[100:101], v[112:113], v[112:113], v[100:101]
	v_mov_b32_e32 v112, v10
	v_mov_b32_e32 v113, v14
	v_pk_mul_f32 v[114:115], v[114:115], v[114:115]
	v_add_f32_e32 v100, v100, v101
	v_pk_fma_f32 v[112:113], v[112:113], v[112:113], v[114:115]
	v_mov_b32_e32 v114, v12
	v_mov_b32_e32 v115, v16
	v_pk_fma_f32 v[112:113], v[114:115], v[114:115], v[112:113]
	v_mov_b32_e32 v114, v13
	v_mov_b32_e32 v115, v17
	v_pk_fma_f32 v[112:113], v[114:115], v[114:115], v[112:113]
	s_nop 0
	v_add_f32_e32 v100, v113, v100
	v_add_f32_e32 v100, v112, v100
	ds_bpermute_b32 v101, v103, v100
	s_waitcnt lgkmcnt(0)
	v_add_f32_e32 v100, v100, v101
	ds_bpermute_b32 v101, v104, v100
	s_waitcnt lgkmcnt(0)
	v_add_f32_e32 v100, v100, v101
	ds_bpermute_b32 v101, v105, v100
	s_waitcnt lgkmcnt(0)
	v_add_f32_e32 v100, v100, v101
	ds_bpermute_b32 v101, v106, v100
	s_waitcnt lgkmcnt(0)
	v_add_f32_e32 v100, v100, v101
	ds_bpermute_b32 v101, v107, v100
	s_waitcnt lgkmcnt(0)
	v_add_f32_e32 v100, v100, v101
	ds_bpermute_b32 v101, v108, v100
	s_waitcnt lgkmcnt(0)
	v_add_f32_e32 v100, v100, v101
	v_fmamk_f32 v100, v100, 0x3a800000, v99
	v_mul_f32_e32 v101, 0x4b800000, v100
	v_cmp_gt_f32_e32 vcc, s2, v100
	s_nop 1
	v_cndmask_b32_e32 v100, v100, v101, vcc
	v_rsq_f32_e32 v110, v100
	v_lshl_add_u64 v[100:101], v[94:95], 0, v[92:93]
	v_mul_f32_e32 v112, 0x45800000, v110
	v_cndmask_b32_e32 v110, v110, v112, vcc
	v_pk_mul_f32 v[112:113], v[6:7], v[110:111] op_sel_hi:[1,0]
	v_pk_mul_f32 v[114:115], v[8:9], v[110:111] op_sel_hi:[1,0]
	s_waitcnt vmcnt(2)
	v_pk_fma_f32 v[112:113], v[66:67], v[112:113], v[46:47]
	v_pk_fma_f32 v[114:115], v[68:69], v[114:115], v[48:49]
	v_cvt_pk_bf16_f32 v112, v112, v113
	v_pk_mul_f32 v[116:117], v[2:3], v[110:111] op_sel_hi:[1,0]
	v_pk_fma_f32 v[116:117], v[70:71], v[116:117], v[42:43]
	v_cvt_pk_bf16_f32 v113, v114, v115
	v_pk_mul_f32 v[118:119], v[4:5], v[110:111] op_sel_hi:[1,0]
	v_pk_fma_f32 v[118:119], v[72:73], v[118:119], v[44:45]
	v_cvt_pk_bf16_f32 v114, v116, v117
	v_add_co_u32_e32 v100, vcc, s25, v100
	v_cvt_pk_bf16_f32 v115, v118, v119
	s_nop 0
	v_addc_co_u32_e32 v101, vcc, 0, v101, vcc
	global_store_dwordx4 v[100:101], v[112:115], off
	v_pk_mul_f32 v[116:117], v[10:11], v[110:111] op_sel_hi:[1,0]
	v_pk_mul_f32 v[118:119], v[12:13], v[110:111] op_sel_hi:[1,0]
	v_pk_mul_f32 v[112:113], v[14:15], v[110:111] op_sel_hi:[1,0]
	v_pk_mul_f32 v[114:115], v[16:17], v[110:111] op_sel_hi:[1,0]
	s_waitcnt vmcnt(1)
	v_pk_fma_f32 v[112:113], v[74:75], v[112:113], v[62:63]
	v_pk_fma_f32 v[114:115], v[76:77], v[114:115], v[64:65]
	v_cvt_pk_bf16_f32 v112, v112, v113
	v_pk_fma_f32 v[116:117], v[78:79], v[116:117], v[58:59]
	v_cvt_pk_bf16_f32 v113, v114, v115
	v_pk_fma_f32 v[118:119], v[80:81], v[118:119], v[60:61]
	v_cvt_pk_bf16_f32 v114, v116, v117
	v_cvt_pk_bf16_f32 v115, v118, v119
	global_store_dwordx4 v[100:101], v[112:115], off offset:1024
	v_add_u32_e32 v100, 1, v98
	v_cmp_lt_i32_e32 vcc, v100, v1
	v_add_u32_e32 v110, 3, v98
	s_and_saveexec_b64 s[20:21], vcc
	s_cbranch_execz .LBB0_143
	v_add_u32_e32 v2, 3, v98
	v_min_i32_e32 v2, v2, v102
	v_add_u32_e32 v4, 0xfffff000, v2
	v_cmp_gt_i32_e32 vcc, s0, v2
	v_ashrrev_i32_e32 v3, 31, v2
	v_mov_b32_e32 v5, s5
	v_cndmask_b32_e32 v2, v4, v2, vcc
	v_mov_b32_e32 v4, s7
	v_cndmask_b32_e32 v3, 0, v3, vcc
	v_cndmask_b32_e32 v5, v4, v5, vcc
	v_mov_b32_e32 v4, s6
	v_mov_b32_e32 v6, s4
	v_cndmask_b32_e32 v4, v4, v6, vcc
	v_lshlrev_b64 v[2:3], 12, v[2:3]
	v_lshl_add_u64 v[2:3], v[4:5], 0, v[2:3]
	v_lshl_add_u64 v[112:113], v[82:83], 2, v[2:3]
	global_load_dwordx4 v[2:5], v[112:113], off offset:16
	global_load_dwordx4 v[6:9], v[112:113], off
	global_load_dwordx4 v[10:13], v[112:113], off offset:2064
	global_load_dwordx4 v[14:17], v[112:113], off offset:2048
	v_add_u32_e32 v101, 0xfffff001, v98
	v_ashrrev_i32_e32 v101, 12, v101
	v_add_u32_e32 v101, 1, v101
	v_cmp_lt_i32_e32 vcc, s26, v98
	s_nop 1
	v_cndmask_b32_e32 v101, 0, v101, vcc
	v_cmp_ne_u32_e32 vcc, v101, v109
	s_and_saveexec_b64 s[22:23], vcc
	s_cbranch_execz .LBB0_142
	v_mul_hi_i32_i24_e32 v43, 0x3000, v101
	v_mul_i32_i24_e32 v42, 0x3000, v101
	v_lshl_add_u64 v[42:43], s[14:15], 0, v[42:43]
	v_lshl_add_u64 v[44:45], v[42:43], 0, s[16:17]
	v_lshl_add_u64 v[46:47], v[44:45], 0, v[84:85]
	v_lshl_add_u64 v[44:45], v[86:87], 2, v[44:45]
	v_lshl_add_u64 v[62:63], v[42:43], 0, v[84:85]
	global_load_dwordx4 v[66:69], v[46:47], off
	global_load_dwordx4 v[70:73], v[46:47], off offset:16
	global_load_dwordx4 v[74:77], v[44:45], off
	global_load_dwordx4 v[78:81], v[44:45], off offset:16
	global_load_dwordx4 v[112:115], v[90:91], off
	global_load_dwordx4 v[116:119], v[90:91], off offset:16
	global_load_dwordx4 v[120:123], v[90:91], off offset:2064
	global_load_dwordx4 v[124:127], v[90:91], off offset:2048
	s_nop 0
	global_load_dwordx4 v[42:45], v[62:63], off offset:16
	global_load_dwordx4 v[46:49], v[62:63], off
	global_load_dwordx4 v[58:61], v[62:63], off offset:2064
	s_nop 0
	global_load_dwordx4 v[62:65], v[62:63], off offset:2048
	v_mov_b32_e32 v109, v101
	s_waitcnt vmcnt(9)
	v_pk_add_f32 v[76:77], v[76:77], 1.0 op_sel_hi:[1,0]
	v_pk_add_f32 v[74:75], v[74:75], 1.0 op_sel_hi:[1,0]
	s_waitcnt vmcnt(8)
	v_pk_add_f32 v[80:81], v[80:81], 1.0 op_sel_hi:[1,0]
	v_pk_add_f32 v[68:69], v[68:69], 1.0 op_sel_hi:[1,0]
	v_pk_add_f32 v[66:67], v[66:67], 1.0 op_sel_hi:[1,0]
	v_pk_add_f32 v[72:73], v[72:73], 1.0 op_sel_hi:[1,0]
	v_pk_add_f32 v[70:71], v[70:71], 1.0 op_sel_hi:[1,0]
	v_pk_add_f32 v[78:79], v[78:79], 1.0 op_sel_hi:[1,0]
	s_waitcnt vmcnt(7)
	v_pk_mul_f32 v[68:69], v[114:115], v[68:69]
	v_pk_mul_f32 v[66:67], v[112:113], v[66:67]
	s_waitcnt vmcnt(6)
	v_pk_mul_f32 v[72:73], v[118:119], v[72:73]
	v_pk_mul_f32 v[70:71], v[116:117], v[70:71]
	s_waitcnt vmcnt(4)
	v_pk_mul_f32 v[76:77], v[126:127], v[76:77]
	v_pk_mul_f32 v[74:75], v[124:125], v[74:75]
	v_pk_mul_f32 v[80:81], v[122:123], v[80:81]
	v_pk_mul_f32 v[78:79], v[120:121], v[78:79]
.LBB0_142:
	s_or_b64 exec, exec, s[22:23]
	v_mov_b32_e32 v114, v27
	v_mov_b32_e32 v115, v31
	v_mov_b32_e32 v112, v26
	v_mov_b32_e32 v113, v30
	v_pk_mul_f32 v[114:115], v[114:115], v[114:115]
	v_mov_b32_e32 v116, v19
	v_pk_fma_f32 v[112:113], v[112:113], v[112:113], v[114:115]
	v_mov_b32_e32 v114, v28
	v_mov_b32_e32 v115, v32
	v_pk_fma_f32 v[112:113], v[114:115], v[114:115], v[112:113]
	v_mov_b32_e32 v114, v29
	v_mov_b32_e32 v115, v33
	v_mov_b32_e32 v117, v23
	v_pk_fma_f32 v[112:113], v[114:115], v[114:115], v[112:113]
	v_mov_b32_e32 v114, v18
	v_mov_b32_e32 v115, v22
	v_pk_mul_f32 v[116:117], v[116:117], v[116:117]
	v_add_f32_e32 v101, v112, v113
	v_pk_fma_f32 v[114:115], v[114:115], v[114:115], v[116:117]
	v_mov_b32_e32 v116, v20
	v_mov_b32_e32 v117, v24
	v_pk_fma_f32 v[114:115], v[116:117], v[116:117], v[114:115]
	v_mov_b32_e32 v116, v21
	v_mov_b32_e32 v117, v25
	v_pk_fma_f32 v[114:115], v[116:117], v[116:117], v[114:115]
	s_nop 0
	v_add_f32_e32 v101, v115, v101
	v_add_f32_e32 v101, v114, v101
	ds_bpermute_b32 v112, v103, v101
	s_waitcnt lgkmcnt(0)
	v_add_f32_e32 v101, v101, v112
	ds_bpermute_b32 v112, v104, v101
	s_waitcnt lgkmcnt(0)
	v_add_f32_e32 v101, v101, v112
	ds_bpermute_b32 v112, v105, v101
	s_waitcnt lgkmcnt(0)
	v_add_f32_e32 v101, v101, v112
	ds_bpermute_b32 v112, v106, v101
	s_waitcnt lgkmcnt(0)
	v_add_f32_e32 v101, v101, v112
	ds_bpermute_b32 v112, v107, v101
	s_waitcnt lgkmcnt(0)
	v_add_f32_e32 v101, v101, v112
	ds_bpermute_b32 v112, v108, v101
	s_waitcnt lgkmcnt(0)
	v_add_f32_e32 v101, v101, v112
	v_fmamk_f32 v101, v101, 0x3a800000, v99
	v_mul_f32_e32 v112, 0x4b800000, v101
	v_cmp_gt_f32_e32 vcc, s2, v101
	s_nop 1
	v_cndmask_b32_e32 v101, v101, v112, vcc
	v_rsq_f32_e32 v112, v101
	v_ashrrev_i32_e32 v101, 31, v100
	v_lshlrev_b64 v[100:101], 11, v[100:101]
	v_lshl_add_u64 v[100:101], v[88:89], 0, v[100:101]
	v_mul_f32_e32 v113, 0x45800000, v112
	v_cndmask_b32_e32 v116, v112, v113, vcc
	v_pk_mul_f32 v[112:113], v[30:31], v[116:117] op_sel_hi:[1,0]
	v_pk_mul_f32 v[114:115], v[32:33], v[116:117] op_sel_hi:[1,0]
	s_waitcnt vmcnt(2)
	v_pk_fma_f32 v[112:113], v[66:67], v[112:113], v[46:47]
	v_pk_mul_f32 v[118:119], v[26:27], v[116:117] op_sel_hi:[1,0]
	v_pk_mul_f32 v[120:121], v[28:29], v[116:117] op_sel_hi:[1,0]
	v_pk_fma_f32 v[114:115], v[68:69], v[114:115], v[48:49]
	v_cvt_pk_bf16_f32 v112, v112, v113
	v_pk_fma_f32 v[118:119], v[70:71], v[118:119], v[42:43]
	v_cvt_pk_bf16_f32 v113, v114, v115
	v_pk_fma_f32 v[120:121], v[72:73], v[120:121], v[44:45]
	v_cvt_pk_bf16_f32 v114, v118, v119
	v_bfe_u32 v115, v120, 16, 1
	v_add3_u32 v115, v120, v115, s3
	v_bfe_u32 v117, v121, 16, 1
	v_lshrrev_b32_e32 v115, 16, v115
	v_add3_u32 v117, v121, v117, s3
	v_and_or_b32 v115, v117, s24, v115
	global_store_dwordx4 v[100:101], v[112:115], off
	v_pk_mul_f32 v[118:119], v[18:19], v[116:117] op_sel_hi:[1,0]
	s_nop 0
	v_pk_mul_f32 v[112:113], v[22:23], v[116:117] op_sel_hi:[1,0]
	v_pk_mul_f32 v[114:115], v[24:25], v[116:117] op_sel_hi:[1,0]
	s_waitcnt vmcnt(1)
	v_pk_fma_f32 v[112:113], v[74:75], v[112:113], v[62:63]
	v_pk_fma_f32 v[114:115], v[76:77], v[114:115], v[64:65]
	v_cvt_pk_bf16_f32 v112, v112, v113
	v_pk_fma_f32 v[118:119], v[78:79], v[118:119], v[58:59]
	v_cvt_pk_bf16_f32 v113, v114, v115
	v_pk_mul_f32 v[116:117], v[20:21], v[116:117] op_sel_hi:[1,0]
	v_pk_fma_f32 v[116:117], v[80:81], v[116:117], v[60:61]
	v_cvt_pk_bf16_f32 v114, v118, v119
	v_cvt_pk_bf16_f32 v115, v116, v117
	global_store_dwordx4 v[100:101], v[112:115], off offset:1024

.LBB0_229:
	s_lshl_b32 s28, s28, 8
	v_lshlrev_b32_e32 v138, 6, v138
	v_lshlrev_b32_e32 v154, 5, v154
	v_lshlrev_b32_e32 v156, 3, v1
	v_add3_u32 v1, v155, s28, v138
	v_add3_u32 v154, v156, v154, s53
	v_mad_u64_u32 v[156:157], s[30:31], s27, v1, v[154:155]
	v_lshl_add_u32 v138, v156, 1, s25
	v_lshl_add_u64 v[156:157], v[152:153], 0, v[138:139]
	v_cvt_pk_bf16_f32 v126, v126, v127
	v_cvt_pk_bf16_f32 v127, v128, v129
	v_cvt_pk_bf16_f32 v128, v122, v123
	v_cvt_pk_bf16_f32 v129, v124, v125
	s_and_b64 vcc, exec, s[6:7]
	global_store_dwordx4 v[156:157], v[126:129], off
	s_cbranch_vccnz .LBB0_231
	v_mul_f32_e32 v122, 0xbfb8aa3b, v118
	v_mul_f32_e32 v123, 0xbfb8aa3b, v119
	v_mul_f32_e32 v124, 0xbfb8aa3b, v120
	v_mul_f32_e32 v125, 0xbfb8aa3b, v121
	v_mul_f32_e32 v126, 0xbfb8aa3b, v114
	v_mul_f32_e32 v127, 0xbfb8aa3b, v115
	v_mul_f32_e32 v128, 0xbfb8aa3b, v116
	v_mul_f32_e32 v129, 0xbfb8aa3b, v117
	v_exp_f32_e32 v122, v122
	v_exp_f32_e32 v123, v123
	v_exp_f32_e32 v124, v124
	v_exp_f32_e32 v125, v125
	v_exp_f32_e32 v126, v126
	v_exp_f32_e32 v127, v127
	v_exp_f32_e32 v128, v128
	v_exp_f32_e32 v129, v129
	v_add_f32_e32 v122, 1.0, v122
	v_add_f32_e32 v123, 1.0, v123
	v_add_f32_e32 v124, 1.0, v124
	v_add_f32_e32 v125, 1.0, v125
	v_add_f32_e32 v126, 1.0, v126
	v_add_f32_e32 v127, 1.0, v127
	v_add_f32_e32 v128, 1.0, v128
	v_add_f32_e32 v129, 1.0, v129
	v_rcp_f32_e32 v122, v122
	v_rcp_f32_e32 v123, v123
	v_rcp_f32_e32 v124, v124
	v_rcp_f32_e32 v125, v125
	v_rcp_f32_e32 v126, v126
	v_rcp_f32_e32 v128, v128
	v_rcp_f32_e32 v129, v129
	v_rcp_f32_e32 v127, v127
	v_pk_mul_f32 v[120:121], v[120:121], v[124:125]
	v_pk_mul_f32 v[118:119], v[118:119], v[122:123]
	v_pk_mul_f32 v[116:117], v[116:117], v[128:129]
	v_pk_mul_f32 v[114:115], v[114:115], v[126:127]
.LBB0_231:
	v_cvt_pk_bf16_f32 v118, v118, v119
	v_cvt_pk_bf16_f32 v119, v120, v121
	v_cvt_pk_bf16_f32 v120, v114, v115
	v_cvt_pk_bf16_f32 v121, v116, v117
	s_and_b64 vcc, exec, s[6:7]
	global_store_dwordx4 v[156:157], v[118:121], off offset:256
	s_cbranch_vccnz .LBB0_233
	v_mul_f32_e32 v114, 0xbfb8aa3b, v110
	v_mul_f32_e32 v115, 0xbfb8aa3b, v111
	v_mul_f32_e32 v116, 0xbfb8aa3b, v112
	v_mul_f32_e32 v117, 0xbfb8aa3b, v113
	v_mul_f32_e32 v118, 0xbfb8aa3b, v106
	v_mul_f32_e32 v119, 0xbfb8aa3b, v107
	v_mul_f32_e32 v120, 0xbfb8aa3b, v108
	v_mul_f32_e32 v121, 0xbfb8aa3b, v109
	v_exp_f32_e32 v114, v114
	v_exp_f32_e32 v115, v115
	v_exp_f32_e32 v116, v116
	v_exp_f32_e32 v117, v117
	v_exp_f32_e32 v118, v118
	v_exp_f32_e32 v119, v119
	v_exp_f32_e32 v120, v120
	v_exp_f32_e32 v121, v121
	v_add_f32_e32 v114, 1.0, v114
	v_add_f32_e32 v115, 1.0, v115
	v_add_f32_e32 v116, 1.0, v116
	v_add_f32_e32 v117, 1.0, v117
	v_add_f32_e32 v118, 1.0, v118
	v_add_f32_e32 v119, 1.0, v119
	v_add_f32_e32 v120, 1.0, v120
	v_add_f32_e32 v121, 1.0, v121
	v_rcp_f32_e32 v114, v114
	v_rcp_f32_e32 v115, v115
	v_rcp_f32_e32 v116, v116
	v_rcp_f32_e32 v117, v117
	v_rcp_f32_e32 v118, v118
	v_rcp_f32_e32 v120, v120
	v_rcp_f32_e32 v121, v121
	v_rcp_f32_e32 v119, v119
	v_pk_mul_f32 v[112:113], v[112:113], v[116:117]
	v_pk_mul_f32 v[110:111], v[110:111], v[114:115]
	v_pk_mul_f32 v[108:109], v[108:109], v[120:121]
	v_pk_mul_f32 v[106:107], v[106:107], v[118:119]
.LBB0_233:
	v_cvt_pk_bf16_f32 v110, v110, v111
	v_cvt_pk_bf16_f32 v111, v112, v113
	v_add_u32_e32 v114, 16, v1
	v_cvt_pk_bf16_f32 v112, v106, v107
	v_mad_u64_u32 v[114:115], s[30:31], s27, v114, v[154:155]
	v_lshl_add_u32 v138, v114, 1, s25
	v_lshl_add_u64 v[114:115], v[152:153], 0, v[138:139]
	v_cvt_pk_bf16_f32 v113, v108, v109
	s_and_b64 vcc, exec, s[6:7]
	global_store_dwordx4 v[114:115], v[110:113], off
	s_cbranch_vccnz .LBB0_235
	v_mul_f32_e32 v106, 0xbfb8aa3b, v102
	v_mul_f32_e32 v107, 0xbfb8aa3b, v103
	v_mul_f32_e32 v108, 0xbfb8aa3b, v104
	v_mul_f32_e32 v109, 0xbfb8aa3b, v105
	v_mul_f32_e32 v110, 0xbfb8aa3b, v98
	v_mul_f32_e32 v111, 0xbfb8aa3b, v99
	v_mul_f32_e32 v112, 0xbfb8aa3b, v100
	v_mul_f32_e32 v113, 0xbfb8aa3b, v101
	v_exp_f32_e32 v106, v106
	v_exp_f32_e32 v107, v107
	v_exp_f32_e32 v108, v108
	v_exp_f32_e32 v109, v109
	v_exp_f32_e32 v110, v110
	v_exp_f32_e32 v111, v111
	v_exp_f32_e32 v112, v112
	v_exp_f32_e32 v113, v113
	v_add_f32_e32 v106, 1.0, v106
	v_add_f32_e32 v107, 1.0, v107
	v_add_f32_e32 v108, 1.0, v108
	v_add_f32_e32 v109, 1.0, v109
	v_add_f32_e32 v110, 1.0, v110
	v_add_f32_e32 v111, 1.0, v111
	v_add_f32_e32 v112, 1.0, v112
	v_add_f32_e32 v113, 1.0, v113
	v_rcp_f32_e32 v106, v106
	v_rcp_f32_e32 v107, v107
	v_rcp_f32_e32 v108, v108
	v_rcp_f32_e32 v109, v109
	v_rcp_f32_e32 v110, v110
	v_rcp_f32_e32 v112, v112
	v_rcp_f32_e32 v113, v113
	v_rcp_f32_e32 v111, v111
	v_pk_mul_f32 v[104:105], v[104:105], v[108:109]
	v_pk_mul_f32 v[102:103], v[102:103], v[106:107]
	v_pk_mul_f32 v[100:101], v[100:101], v[112:113]
	v_pk_mul_f32 v[98:99], v[98:99], v[110:111]
.LBB0_235:
	v_cvt_pk_bf16_f32 v102, v102, v103
	v_cvt_pk_bf16_f32 v103, v104, v105
	v_cvt_pk_bf16_f32 v104, v98, v99
	v_cvt_pk_bf16_f32 v105, v100, v101
	s_and_b64 vcc, exec, s[6:7]
	global_store_dwordx4 v[114:115], v[102:105], off offset:256
	s_cbranch_vccnz .LBB0_237
	v_mul_f32_e32 v98, 0xbfb8aa3b, v94
	v_mul_f32_e32 v99, 0xbfb8aa3b, v95
	v_mul_f32_e32 v100, 0xbfb8aa3b, v96
	v_mul_f32_e32 v101, 0xbfb8aa3b, v97
	v_mul_f32_e32 v102, 0xbfb8aa3b, v90
	v_mul_f32_e32 v103, 0xbfb8aa3b, v91
	v_mul_f32_e32 v104, 0xbfb8aa3b, v92
	v_mul_f32_e32 v105, 0xbfb8aa3b, v93
	v_exp_f32_e32 v98, v98
	v_exp_f32_e32 v99, v99
	v_exp_f32_e32 v100, v100
	v_exp_f32_e32 v101, v101
	v_exp_f32_e32 v102, v102
	v_exp_f32_e32 v103, v103
	v_exp_f32_e32 v104, v104
	v_exp_f32_e32 v105, v105
	v_add_f32_e32 v98, 1.0, v98
	v_add_f32_e32 v99, 1.0, v99
	v_add_f32_e32 v100, 1.0, v100
	v_add_f32_e32 v101, 1.0, v101
	v_add_f32_e32 v102, 1.0, v102
	v_add_f32_e32 v103, 1.0, v103
	v_add_f32_e32 v104, 1.0, v104
	v_add_f32_e32 v105, 1.0, v105
	v_rcp_f32_e32 v98, v98
	v_rcp_f32_e32 v99, v99
	v_rcp_f32_e32 v100, v100
	v_rcp_f32_e32 v101, v101
	v_rcp_f32_e32 v102, v102
	v_rcp_f32_e32 v104, v104
	v_rcp_f32_e32 v105, v105
	v_rcp_f32_e32 v103, v103
	v_pk_mul_f32 v[96:97], v[96:97], v[100:101]
	v_pk_mul_f32 v[94:95], v[94:95], v[98:99]
	v_pk_mul_f32 v[92:93], v[92:93], v[104:105]
	v_pk_mul_f32 v[90:91], v[90:91], v[102:103]
.LBB0_237:
	v_cvt_pk_bf16_f32 v94, v94, v95
	v_cvt_pk_bf16_f32 v95, v96, v97
	v_add_u32_e32 v98, 32, v1
	v_cvt_pk_bf16_f32 v96, v90, v91
	v_bfe_u32 v90, v92, 16, 1
	v_mad_u64_u32 v[98:99], s[30:31], s27, v98, v[154:155]
	v_add3_u32 v90, v92, v90, s49
	v_bfe_u32 v91, v93, 16, 1
	v_lshl_add_u32 v138, v98, 1, s25
	v_lshrrev_b32_e32 v90, 16, v90
	v_add3_u32 v91, v93, v91, s49
	v_lshl_add_u64 v[98:99], v[152:153], 0, v[138:139]
	v_and_or_b32 v97, v91, s50, v90
	s_and_b64 vcc, exec, s[6:7]
	global_store_dwordx4 v[98:99], v[94:97], off
	s_cbranch_vccnz .LBB0_239
	v_mul_f32_e32 v90, 0xbfb8aa3b, v86
	v_mul_f32_e32 v91, 0xbfb8aa3b, v87
	v_mul_f32_e32 v92, 0xbfb8aa3b, v88
	v_mul_f32_e32 v93, 0xbfb8aa3b, v89
	v_mul_f32_e32 v94, 0xbfb8aa3b, v82
	v_mul_f32_e32 v95, 0xbfb8aa3b, v83
	v_mul_f32_e32 v96, 0xbfb8aa3b, v84
	v_mul_f32_e32 v97, 0xbfb8aa3b, v85
	v_exp_f32_e32 v90, v90
	v_exp_f32_e32 v91, v91
	v_exp_f32_e32 v92, v92
	v_exp_f32_e32 v93, v93
	v_exp_f32_e32 v94, v94
	v_exp_f32_e32 v95, v95
	v_exp_f32_e32 v96, v96
	v_exp_f32_e32 v97, v97
	v_add_f32_e32 v90, 1.0, v90
	v_add_f32_e32 v91, 1.0, v91
	v_add_f32_e32 v92, 1.0, v92
	v_add_f32_e32 v93, 1.0, v93
	v_add_f32_e32 v94, 1.0, v94
	v_add_f32_e32 v95, 1.0, v95
	v_add_f32_e32 v96, 1.0, v96
	v_add_f32_e32 v97, 1.0, v97
	v_rcp_f32_e32 v90, v90
	v_rcp_f32_e32 v91, v91
	v_rcp_f32_e32 v92, v92
	v_rcp_f32_e32 v93, v93
	v_rcp_f32_e32 v94, v94
	v_rcp_f32_e32 v96, v96
	v_rcp_f32_e32 v97, v97
	v_rcp_f32_e32 v95, v95
	v_pk_mul_f32 v[88:89], v[88:89], v[92:93]
	v_pk_mul_f32 v[86:87], v[86:87], v[90:91]
	v_pk_mul_f32 v[84:85], v[84:85], v[96:97]
	v_pk_mul_f32 v[82:83], v[82:83], v[94:95]
.LBB0_239:
	v_bfe_u32 v90, v86, 16, 1
	v_add3_u32 v86, v86, v90, s49
	v_bfe_u32 v90, v87, 16, 1
	v_lshrrev_b32_e32 v86, 16, v86
	v_add3_u32 v87, v87, v90, s49
	v_and_or_b32 v86, v87, s50, v86
	v_cvt_pk_bf16_f32 v87, v88, v89
	v_cvt_pk_bf16_f32 v88, v82, v83
	v_cvt_pk_bf16_f32 v89, v84, v85
	s_and_b64 vcc, exec, s[6:7]
	global_store_dwordx4 v[98:99], v[86:89], off offset:256
	s_cbranch_vccnz .LBB0_241
	v_mul_f32_e32 v82, 0xbfb8aa3b, v78
	v_mul_f32_e32 v83, 0xbfb8aa3b, v79
	v_mul_f32_e32 v84, 0xbfb8aa3b, v80
	v_mul_f32_e32 v85, 0xbfb8aa3b, v81
	v_mul_f32_e32 v86, 0xbfb8aa3b, v74
	v_mul_f32_e32 v87, 0xbfb8aa3b, v75
	v_mul_f32_e32 v88, 0xbfb8aa3b, v76
	v_mul_f32_e32 v89, 0xbfb8aa3b, v77
	v_exp_f32_e32 v82, v82
	v_exp_f32_e32 v83, v83
	v_exp_f32_e32 v84, v84
	v_exp_f32_e32 v85, v85
	v_exp_f32_e32 v86, v86
	v_exp_f32_e32 v87, v87
	v_exp_f32_e32 v88, v88
	v_exp_f32_e32 v89, v89
	v_add_f32_e32 v82, 1.0, v82
	v_add_f32_e32 v83, 1.0, v83
	v_add_f32_e32 v84, 1.0, v84
	v_add_f32_e32 v85, 1.0, v85
	v_add_f32_e32 v86, 1.0, v86
	v_add_f32_e32 v87, 1.0, v87
	v_add_f32_e32 v88, 1.0, v88
	v_add_f32_e32 v89, 1.0, v89
	v_rcp_f32_e32 v82, v82
	v_rcp_f32_e32 v83, v83
	v_rcp_f32_e32 v84, v84
	v_rcp_f32_e32 v85, v85
	v_rcp_f32_e32 v86, v86
	v_rcp_f32_e32 v88, v88
	v_rcp_f32_e32 v89, v89
	v_rcp_f32_e32 v87, v87
	v_pk_mul_f32 v[80:81], v[80:81], v[84:85]
	v_pk_mul_f32 v[78:79], v[78:79], v[82:83]
	v_pk_mul_f32 v[76:77], v[76:77], v[88:89]
	v_pk_mul_f32 v[74:75], v[74:75], v[86:87]
.LBB0_241:
	v_bfe_u32 v84, v78, 16, 1
	v_add3_u32 v78, v78, v84, s49
	v_bfe_u32 v84, v79, 16, 1
	v_lshrrev_b32_e32 v78, 16, v78
	v_add3_u32 v79, v79, v84, s49
	v_and_or_b32 v78, v79, s50, v78
	v_cvt_pk_bf16_f32 v79, v80, v81
	v_add_u32_e32 v82, 48, v1
	v_cvt_pk_bf16_f32 v80, v74, v75
	v_mad_u64_u32 v[82:83], s[30:31], s27, v82, v[154:155]
	v_lshl_add_u32 v138, v82, 1, s25
	v_lshl_add_u64 v[82:83], v[152:153], 0, v[138:139]
	v_cvt_pk_bf16_f32 v81, v76, v77
	s_and_b64 vcc, exec, s[6:7]
	global_store_dwordx4 v[82:83], v[78:81], off
	s_cbranch_vccnz .LBB0_243
	v_mul_f32_e32 v74, 0xbfb8aa3b, v70
	v_mul_f32_e32 v75, 0xbfb8aa3b, v71
	v_mul_f32_e32 v76, 0xbfb8aa3b, v72
	v_mul_f32_e32 v77, 0xbfb8aa3b, v73
	v_mul_f32_e32 v78, 0xbfb8aa3b, v66
	v_mul_f32_e32 v79, 0xbfb8aa3b, v67
	v_mul_f32_e32 v80, 0xbfb8aa3b, v68
	v_mul_f32_e32 v81, 0xbfb8aa3b, v69
	v_exp_f32_e32 v74, v74
	v_exp_f32_e32 v75, v75
	v_exp_f32_e32 v76, v76
	v_exp_f32_e32 v77, v77
	v_exp_f32_e32 v78, v78
	v_exp_f32_e32 v79, v79
	v_exp_f32_e32 v80, v80
	v_exp_f32_e32 v81, v81
	v_add_f32_e32 v74, 1.0, v74
	v_add_f32_e32 v75, 1.0, v75
	v_add_f32_e32 v76, 1.0, v76
	v_add_f32_e32 v77, 1.0, v77
	v_add_f32_e32 v78, 1.0, v78
	v_add_f32_e32 v79, 1.0, v79
	v_add_f32_e32 v80, 1.0, v80
	v_add_f32_e32 v81, 1.0, v81
	v_rcp_f32_e32 v74, v74
	v_rcp_f32_e32 v75, v75
	v_rcp_f32_e32 v76, v76
	v_rcp_f32_e32 v77, v77
	v_rcp_f32_e32 v78, v78
	v_rcp_f32_e32 v80, v80
	v_rcp_f32_e32 v81, v81
	v_rcp_f32_e32 v79, v79
	v_pk_mul_f32 v[72:73], v[72:73], v[76:77]
	v_pk_mul_f32 v[70:71], v[70:71], v[74:75]
	v_pk_mul_f32 v[68:69], v[68:69], v[80:81]
	v_pk_mul_f32 v[66:67], v[66:67], v[78:79]
.LBB0_243:
	v_cvt_pk_bf16_f32 v70, v70, v71
	v_cvt_pk_bf16_f32 v71, v72, v73
	v_cvt_pk_bf16_f32 v72, v66, v67
	v_cvt_pk_bf16_f32 v73, v68, v69
	s_and_b64 vcc, exec, s[6:7]
	global_store_dwordx4 v[82:83], v[70:73], off offset:256
	s_cbranch_vccnz .LBB0_245
	v_mul_f32_e32 v66, 0xbfb8aa3b, v62
	v_mul_f32_e32 v67, 0xbfb8aa3b, v63
	v_mul_f32_e32 v68, 0xbfb8aa3b, v64
	v_mul_f32_e32 v69, 0xbfb8aa3b, v65
	v_mul_f32_e32 v70, 0xbfb8aa3b, v58
	v_mul_f32_e32 v71, 0xbfb8aa3b, v59
	v_mul_f32_e32 v72, 0xbfb8aa3b, v60
	v_mul_f32_e32 v73, 0xbfb8aa3b, v61
	v_exp_f32_e32 v66, v66
	v_exp_f32_e32 v67, v67
	v_exp_f32_e32 v68, v68
	v_exp_f32_e32 v69, v69
	v_exp_f32_e32 v70, v70
	v_exp_f32_e32 v71, v71
	v_exp_f32_e32 v72, v72
	v_exp_f32_e32 v73, v73
	v_add_f32_e32 v66, 1.0, v66
	v_add_f32_e32 v67, 1.0, v67
	v_add_f32_e32 v68, 1.0, v68
	v_add_f32_e32 v69, 1.0, v69
	v_add_f32_e32 v70, 1.0, v70
	v_add_f32_e32 v71, 1.0, v71
	v_add_f32_e32 v72, 1.0, v72
	v_add_f32_e32 v73, 1.0, v73
	v_rcp_f32_e32 v66, v66
	v_rcp_f32_e32 v67, v67
	v_rcp_f32_e32 v68, v68
	v_rcp_f32_e32 v69, v69
	v_rcp_f32_e32 v70, v70
	v_rcp_f32_e32 v72, v72
	v_rcp_f32_e32 v73, v73
	v_rcp_f32_e32 v71, v71
	v_pk_mul_f32 v[64:65], v[64:65], v[68:69]
	v_pk_mul_f32 v[62:63], v[62:63], v[66:67]
	v_pk_mul_f32 v[60:61], v[60:61], v[72:73]
	v_pk_mul_f32 v[58:59], v[58:59], v[70:71]
.LBB0_245:
	v_cvt_pk_bf16_f32 v62, v62, v63
	v_cvt_pk_bf16_f32 v63, v64, v65
	v_add_u32_e32 v66, 0x80, v1
	v_cvt_pk_bf16_f32 v64, v58, v59
	v_bfe_u32 v58, v60, 16, 1
	v_mad_u64_u32 v[66:67], s[30:31], s27, v66, v[154:155]
	v_add3_u32 v58, v60, v58, s49
	v_bfe_u32 v59, v61, 16, 1
	v_lshl_add_u32 v138, v66, 1, s25
	v_lshrrev_b32_e32 v58, 16, v58
	v_add3_u32 v59, v61, v59, s49
	v_lshl_add_u64 v[66:67], v[152:153], 0, v[138:139]
	v_and_or_b32 v65, v59, s50, v58
	s_and_b64 vcc, exec, s[6:7]
	global_store_dwordx4 v[66:67], v[62:65], off
	s_cbranch_vccnz .LBB0_247
	v_mul_f32_e32 v58, 0xbfb8aa3b, v54
	v_mul_f32_e32 v59, 0xbfb8aa3b, v55
	v_mul_f32_e32 v60, 0xbfb8aa3b, v56
	v_mul_f32_e32 v61, 0xbfb8aa3b, v57
	v_mul_f32_e32 v62, 0xbfb8aa3b, v50
	v_mul_f32_e32 v63, 0xbfb8aa3b, v51
	v_mul_f32_e32 v64, 0xbfb8aa3b, v52
	v_mul_f32_e32 v65, 0xbfb8aa3b, v53
	v_exp_f32_e32 v58, v58
	v_exp_f32_e32 v59, v59
	v_exp_f32_e32 v60, v60
	v_exp_f32_e32 v61, v61
	v_exp_f32_e32 v62, v62
	v_exp_f32_e32 v63, v63
	v_exp_f32_e32 v64, v64
	v_exp_f32_e32 v65, v65
	v_add_f32_e32 v58, 1.0, v58
	v_add_f32_e32 v59, 1.0, v59
	v_add_f32_e32 v60, 1.0, v60
	v_add_f32_e32 v61, 1.0, v61
	v_add_f32_e32 v62, 1.0, v62
	v_add_f32_e32 v63, 1.0, v63
	v_add_f32_e32 v64, 1.0, v64
	v_add_f32_e32 v65, 1.0, v65
	v_rcp_f32_e32 v58, v58
	v_rcp_f32_e32 v59, v59
	v_rcp_f32_e32 v60, v60
	v_rcp_f32_e32 v61, v61
	v_rcp_f32_e32 v62, v62
	v_rcp_f32_e32 v64, v64
	v_rcp_f32_e32 v65, v65
	v_rcp_f32_e32 v63, v63
	v_pk_mul_f32 v[56:57], v[56:57], v[60:61]
	v_pk_mul_f32 v[54:55], v[54:55], v[58:59]
	v_pk_mul_f32 v[52:53], v[52:53], v[64:65]
	v_pk_mul_f32 v[50:51], v[50:51], v[62:63]
.LBB0_247:
	v_bfe_u32 v58, v54, 16, 1
	v_add3_u32 v54, v54, v58, s49
	v_bfe_u32 v58, v55, 16, 1
	v_lshrrev_b32_e32 v54, 16, v54
	v_add3_u32 v55, v55, v58, s49
	v_and_or_b32 v54, v55, s50, v54
	v_cvt_pk_bf16_f32 v55, v56, v57
	v_cvt_pk_bf16_f32 v56, v50, v51
	v_cvt_pk_bf16_f32 v57, v52, v53
	s_and_b64 vcc, exec, s[6:7]
	global_store_dwordx4 v[66:67], v[54:57], off offset:256
	s_cbranch_vccnz .LBB0_249
	v_mul_f32_e32 v50, 0xbfb8aa3b, v46
	v_mul_f32_e32 v51, 0xbfb8aa3b, v47
	v_mul_f32_e32 v52, 0xbfb8aa3b, v48
	v_mul_f32_e32 v53, 0xbfb8aa3b, v49
	v_mul_f32_e32 v54, 0xbfb8aa3b, v42
	v_mul_f32_e32 v55, 0xbfb8aa3b, v43
	v_mul_f32_e32 v56, 0xbfb8aa3b, v44
	v_mul_f32_e32 v57, 0xbfb8aa3b, v45
	v_exp_f32_e32 v50, v50
	v_exp_f32_e32 v51, v51
	v_exp_f32_e32 v52, v52
	v_exp_f32_e32 v53, v53
	v_exp_f32_e32 v54, v54
	v_exp_f32_e32 v55, v55
	v_exp_f32_e32 v56, v56
	v_exp_f32_e32 v57, v57
	v_add_f32_e32 v50, 1.0, v50
	v_add_f32_e32 v51, 1.0, v51
	v_add_f32_e32 v52, 1.0, v52
	v_add_f32_e32 v53, 1.0, v53
	v_add_f32_e32 v54, 1.0, v54
	v_add_f32_e32 v55, 1.0, v55
	v_add_f32_e32 v56, 1.0, v56
	v_add_f32_e32 v57, 1.0, v57
	v_rcp_f32_e32 v50, v50
	v_rcp_f32_e32 v51, v51
	v_rcp_f32_e32 v52, v52
	v_rcp_f32_e32 v53, v53
	v_rcp_f32_e32 v54, v54
	v_rcp_f32_e32 v56, v56
	v_rcp_f32_e32 v57, v57
	v_rcp_f32_e32 v55, v55
	v_pk_mul_f32 v[48:49], v[48:49], v[52:53]
	v_pk_mul_f32 v[46:47], v[46:47], v[50:51]
	v_pk_mul_f32 v[44:45], v[44:45], v[56:57]
	v_pk_mul_f32 v[42:43], v[42:43], v[54:55]
.LBB0_249:
	v_bfe_u32 v52, v46, 16, 1
	v_add3_u32 v46, v46, v52, s49
	v_bfe_u32 v52, v47, 16, 1
	v_lshrrev_b32_e32 v46, 16, v46
	v_add3_u32 v47, v47, v52, s49
	v_and_or_b32 v46, v47, s50, v46
	v_cvt_pk_bf16_f32 v47, v48, v49
	v_add_u32_e32 v50, 0x90, v1
	v_cvt_pk_bf16_f32 v48, v42, v43
	v_bfe_u32 v42, v44, 16, 1
	v_mad_u64_u32 v[50:51], s[30:31], s27, v50, v[154:155]
	v_add3_u32 v42, v44, v42, s49
	v_bfe_u32 v43, v45, 16, 1
	v_lshl_add_u32 v138, v50, 1, s25
	v_lshrrev_b32_e32 v42, 16, v42
	v_add3_u32 v43, v45, v43, s49
	v_lshl_add_u64 v[50:51], v[152:153], 0, v[138:139]
	v_and_or_b32 v49, v43, s50, v42
	s_and_b64 vcc, exec, s[6:7]
	global_store_dwordx4 v[50:51], v[46:49], off
	s_cbranch_vccnz .LBB0_251
	v_mul_f32_e32 v42, 0xbfb8aa3b, v38
	v_mul_f32_e32 v43, 0xbfb8aa3b, v39
	v_mul_f32_e32 v44, 0xbfb8aa3b, v40
	v_mul_f32_e32 v45, 0xbfb8aa3b, v41
	v_mul_f32_e32 v46, 0xbfb8aa3b, v34
	v_mul_f32_e32 v47, 0xbfb8aa3b, v35
	v_mul_f32_e32 v48, 0xbfb8aa3b, v36
	v_mul_f32_e32 v49, 0xbfb8aa3b, v37
	v_exp_f32_e32 v42, v42
	v_exp_f32_e32 v43, v43
	v_exp_f32_e32 v44, v44
	v_exp_f32_e32 v45, v45
	v_exp_f32_e32 v46, v46
	v_exp_f32_e32 v47, v47
	v_exp_f32_e32 v48, v48
	v_exp_f32_e32 v49, v49
	v_add_f32_e32 v42, 1.0, v42
	v_add_f32_e32 v43, 1.0, v43
	v_add_f32_e32 v44, 1.0, v44
	v_add_f32_e32 v45, 1.0, v45
	v_add_f32_e32 v46, 1.0, v46
	v_add_f32_e32 v47, 1.0, v47
	v_add_f32_e32 v48, 1.0, v48
	v_add_f32_e32 v49, 1.0, v49
	v_rcp_f32_e32 v42, v42
	v_rcp_f32_e32 v43, v43
	v_rcp_f32_e32 v44, v44
	v_rcp_f32_e32 v45, v45
	v_rcp_f32_e32 v46, v46
	v_rcp_f32_e32 v48, v48
	v_rcp_f32_e32 v49, v49
	v_rcp_f32_e32 v47, v47
	v_pk_mul_f32 v[40:41], v[40:41], v[44:45]
	v_pk_mul_f32 v[38:39], v[38:39], v[42:43]
	v_pk_mul_f32 v[36:37], v[36:37], v[48:49]
	v_pk_mul_f32 v[34:35], v[34:35], v[46:47]
.LBB0_251:
	v_bfe_u32 v42, v38, 16, 1
	v_add3_u32 v38, v38, v42, s49
	v_bfe_u32 v42, v39, 16, 1
	v_lshrrev_b32_e32 v38, 16, v38
	v_add3_u32 v39, v39, v42, s49
	v_and_or_b32 v38, v39, s50, v38
	v_cvt_pk_bf16_f32 v39, v40, v41
	v_cvt_pk_bf16_f32 v40, v34, v35
	v_cvt_pk_bf16_f32 v41, v36, v37
	s_and_b64 vcc, exec, s[6:7]
	global_store_dwordx4 v[50:51], v[38:41], off offset:256
	s_cbranch_vccnz .LBB0_253
	v_mul_f32_e32 v34, 0xbfb8aa3b, v30
	v_mul_f32_e32 v35, 0xbfb8aa3b, v31
	v_mul_f32_e32 v36, 0xbfb8aa3b, v32
	v_mul_f32_e32 v37, 0xbfb8aa3b, v33
	v_mul_f32_e32 v38, 0xbfb8aa3b, v26
	v_mul_f32_e32 v39, 0xbfb8aa3b, v27
	v_mul_f32_e32 v40, 0xbfb8aa3b, v28
	v_mul_f32_e32 v41, 0xbfb8aa3b, v29
	v_exp_f32_e32 v34, v34
	v_exp_f32_e32 v35, v35
	v_exp_f32_e32 v36, v36
	v_exp_f32_e32 v37, v37
	v_exp_f32_e32 v38, v38
	v_exp_f32_e32 v39, v39
	v_exp_f32_e32 v40, v40
	v_exp_f32_e32 v41, v41
	v_add_f32_e32 v34, 1.0, v34
	v_add_f32_e32 v35, 1.0, v35
	v_add_f32_e32 v36, 1.0, v36
	v_add_f32_e32 v37, 1.0, v37
	v_add_f32_e32 v38, 1.0, v38
	v_add_f32_e32 v39, 1.0, v39
	v_add_f32_e32 v40, 1.0, v40
	v_add_f32_e32 v41, 1.0, v41
	v_rcp_f32_e32 v34, v34
	v_rcp_f32_e32 v35, v35
	v_rcp_f32_e32 v36, v36
	v_rcp_f32_e32 v37, v37
	v_rcp_f32_e32 v38, v38
	v_rcp_f32_e32 v40, v40
	v_rcp_f32_e32 v41, v41
	v_rcp_f32_e32 v39, v39
	v_pk_mul_f32 v[32:33], v[32:33], v[36:37]
	v_pk_mul_f32 v[30:31], v[30:31], v[34:35]
	v_pk_mul_f32 v[28:29], v[28:29], v[40:41]
	v_pk_mul_f32 v[26:27], v[26:27], v[38:39]
.LBB0_253:
	v_bfe_u32 v36, v30, 16, 1
	v_add3_u32 v30, v30, v36, s49
	v_bfe_u32 v36, v31, 16, 1
	v_lshrrev_b32_e32 v30, 16, v30
	v_add3_u32 v31, v31, v36, s49
	v_and_or_b32 v30, v31, s50, v30
	v_cvt_pk_bf16_f32 v31, v32, v33
	v_add_u32_e32 v34, 0xa0, v1
	v_cvt_pk_bf16_f32 v32, v26, v27
	v_mad_u64_u32 v[34:35], s[30:31], s27, v34, v[154:155]
	v_lshl_add_u32 v138, v34, 1, s25
	v_lshl_add_u64 v[34:35], v[152:153], 0, v[138:139]
	v_cvt_pk_bf16_f32 v33, v28, v29
	s_and_b64 vcc, exec, s[6:7]
	global_store_dwordx4 v[34:35], v[30:33], off
	s_cbranch_vccnz .LBB0_255
	v_mul_f32_e32 v26, 0xbfb8aa3b, v22
	v_mul_f32_e32 v27, 0xbfb8aa3b, v23
	v_mul_f32_e32 v28, 0xbfb8aa3b, v24
	v_mul_f32_e32 v29, 0xbfb8aa3b, v25
	v_mul_f32_e32 v30, 0xbfb8aa3b, v18
	v_mul_f32_e32 v31, 0xbfb8aa3b, v19
	v_mul_f32_e32 v32, 0xbfb8aa3b, v20
	v_mul_f32_e32 v33, 0xbfb8aa3b, v21
	v_exp_f32_e32 v26, v26
	v_exp_f32_e32 v27, v27
	v_exp_f32_e32 v28, v28
	v_exp_f32_e32 v29, v29
	v_exp_f32_e32 v30, v30
	v_exp_f32_e32 v31, v31
	v_exp_f32_e32 v32, v32
	v_exp_f32_e32 v33, v33
	v_add_f32_e32 v26, 1.0, v26
	v_add_f32_e32 v27, 1.0, v27
	v_add_f32_e32 v28, 1.0, v28
	v_add_f32_e32 v29, 1.0, v29
	v_add_f32_e32 v30, 1.0, v30
	v_add_f32_e32 v31, 1.0, v31
	v_add_f32_e32 v32, 1.0, v32
	v_add_f32_e32 v33, 1.0, v33
	v_rcp_f32_e32 v26, v26
	v_rcp_f32_e32 v27, v27
	v_rcp_f32_e32 v28, v28
	v_rcp_f32_e32 v29, v29
	v_rcp_f32_e32 v30, v30
	v_rcp_f32_e32 v32, v32
	v_rcp_f32_e32 v33, v33
	v_rcp_f32_e32 v31, v31
	v_pk_mul_f32 v[24:25], v[24:25], v[28:29]
	v_pk_mul_f32 v[22:23], v[22:23], v[26:27]
	v_pk_mul_f32 v[20:21], v[20:21], v[32:33]
	v_pk_mul_f32 v[18:19], v[18:19], v[30:31]
.LBB0_255:
	v_cvt_pk_bf16_f32 v22, v22, v23
	v_cvt_pk_bf16_f32 v23, v24, v25
	v_cvt_pk_bf16_f32 v24, v18, v19
	v_cvt_pk_bf16_f32 v25, v20, v21
	s_and_b64 vcc, exec, s[6:7]
	global_store_dwordx4 v[34:35], v[22:25], off offset:256
	s_cbranch_vccnz .LBB0_257
	v_mul_f32_e32 v18, 0xbfb8aa3b, v14
	v_mul_f32_e32 v19, 0xbfb8aa3b, v15
	v_mul_f32_e32 v20, 0xbfb8aa3b, v16
	v_mul_f32_e32 v21, 0xbfb8aa3b, v17
	v_mul_f32_e32 v22, 0xbfb8aa3b, v10
	v_mul_f32_e32 v23, 0xbfb8aa3b, v11
	v_mul_f32_e32 v24, 0xbfb8aa3b, v12
	v_mul_f32_e32 v25, 0xbfb8aa3b, v13
	v_exp_f32_e32 v18, v18
	v_exp_f32_e32 v19, v19
	v_exp_f32_e32 v20, v20
	v_exp_f32_e32 v21, v21
	v_exp_f32_e32 v22, v22
	v_exp_f32_e32 v23, v23
	v_exp_f32_e32 v24, v24
	v_exp_f32_e32 v25, v25
	v_add_f32_e32 v18, 1.0, v18
	v_add_f32_e32 v19, 1.0, v19
	v_add_f32_e32 v20, 1.0, v20
	v_add_f32_e32 v21, 1.0, v21
	v_add_f32_e32 v22, 1.0, v22
	v_add_f32_e32 v23, 1.0, v23
	v_add_f32_e32 v24, 1.0, v24
	v_add_f32_e32 v25, 1.0, v25
	v_rcp_f32_e32 v18, v18
	v_rcp_f32_e32 v19, v19
	v_rcp_f32_e32 v20, v20
	v_rcp_f32_e32 v21, v21
	v_rcp_f32_e32 v22, v22
	v_rcp_f32_e32 v24, v24
	v_rcp_f32_e32 v25, v25
	v_rcp_f32_e32 v23, v23
	v_pk_mul_f32 v[16:17], v[16:17], v[20:21]
	v_pk_mul_f32 v[14:15], v[14:15], v[18:19]
	v_pk_mul_f32 v[12:13], v[12:13], v[24:25]
	v_pk_mul_f32 v[10:11], v[10:11], v[22:23]
.LBB0_257:
	v_add_u32_e32 v1, 0xb0, v1
	v_mad_u64_u32 v[18:19], s[30:31], s27, v1, v[154:155]
	v_cvt_pk_bf16_f32 v14, v14, v15
	v_cvt_pk_bf16_f32 v15, v16, v17
	v_cvt_pk_bf16_f32 v16, v10, v11
	v_lshl_add_u32 v138, v18, 1, s25
	v_lshl_add_u64 v[18:19], v[152:153], 0, v[138:139]
	v_cvt_pk_bf16_f32 v17, v12, v13
	s_and_b64 vcc, exec, s[6:7]
	global_store_dwordx4 v[18:19], v[14:17], off
	s_cbranch_vccnz .LBB0_259
	v_mul_f32_e32 v1, 0xbfb8aa3b, v6
	v_exp_f32_e32 v1, v1
	v_mul_f32_e32 v10, 0xbfb8aa3b, v7
	v_mul_f32_e32 v11, 0xbfb8aa3b, v8
	v_exp_f32_e32 v12, v10
	v_exp_f32_e32 v13, v11
	v_add_f32_e32 v1, 1.0, v1
	v_rcp_f32_e32 v10, v1
	v_add_f32_e32 v1, 1.0, v12
	v_mul_f32_e32 v12, 0xbfb8aa3b, v9
	v_rcp_f32_e32 v11, v1
	v_add_f32_e32 v1, 1.0, v13
	v_exp_f32_e32 v13, v12
	v_mul_f32_e32 v12, 0xbfb8aa3b, v2
	v_exp_f32_e32 v14, v12
	v_rcp_f32_e32 v12, v1
	v_add_f32_e32 v1, 1.0, v13
	v_rcp_f32_e32 v13, v1
	v_add_f32_e32 v1, 1.0, v14
	v_mul_f32_e32 v15, 0xbfb8aa3b, v4
	v_rcp_f32_e32 v14, v1
	v_mul_f32_e32 v1, 0xbfb8aa3b, v3
	v_exp_f32_e32 v15, v15
	v_mul_f32_e32 v16, 0xbfb8aa3b, v5
	v_exp_f32_e32 v1, v1
	v_exp_f32_e32 v17, v16
	v_add_f32_e32 v15, 1.0, v15
	v_rcp_f32_e32 v16, v15
	v_add_f32_e32 v1, 1.0, v1
	v_add_f32_e32 v15, 1.0, v17
	v_rcp_f32_e32 v17, v15
	v_rcp_f32_e32 v15, v1
	v_pk_mul_f32 v[8:9], v[8:9], v[12:13]
	v_pk_mul_f32 v[6:7], v[6:7], v[10:11]
	v_pk_mul_f32 v[4:5], v[4:5], v[16:17]
	v_pk_mul_f32 v[2:3], v[2:3], v[14:15]
.LBB0_259:
	v_cvt_pk_bf16_f32 v6, v6, v7
	v_cvt_pk_bf16_f32 v7, v8, v9
	v_cvt_pk_bf16_f32 v8, v2, v3
	v_cvt_pk_bf16_f32 v9, v4, v5
	s_andn2_b64 vcc, exec, s[4:5]
	s_mov_b64 s[4:5], -1
	global_store_dwordx4 v[18:19], v[6:9], off offset:256
	s_cbranch_vccnz .LBB0_209
	s_andn2_b64 vcc, exec, s[12:13]
	s_cbranch_vccnz .LBB0_208
	s_barrier
	s_branch .LBB0_208

.LBB0_514:
	s_waitcnt vmcnt(0)
	v_mfma_f32_32x32x16_f16 v[2:17], v[58:61], v[18:21], 0
	s_and_b32 s6, s1, 0x700
	v_add_u32_e32 v22, s6, v1
	s_bitcmp0_b32 s25, 3
	v_sub_u32_e32 v23, 0x7ff, v22
	v_add_u32_e32 v22, 0x800, v22
	s_cselect_b64 vcc, -1, 0
	v_cndmask_b32_e32 v22, v23, v22, vcc
	v_mfma_f32_32x32x16_f16 v[2:17], v[54:57], v[42:45], v[2:17]
	s_and_b32 s6, s2, 0xfffff000
	v_add_u32_e32 v22, s6, v22
	v_ashrrev_i32_e32 v23, 31, v22
	v_lshlrev_b64 v[22:23], 11, v[22:23]
	s_and_b32 s6, s3, 0x3c0
	v_lshl_add_u64 v[22:23], s[10:11], 0, v[22:23]
	s_lshl_b32 s6, s6, 1
	v_mfma_f32_32x32x16_f16 v[2:17], v[50:53], v[38:41], v[2:17]
	v_lshl_add_u64 v[22:23], v[22:23], 0, s[6:7]
	v_lshl_add_u64 v[100:101], v[22:23], 0, v[94:95]
	s_add_i32 s3, s3, 4
	s_add_i32 s2, s2, 16
	s_addk_i32 s1, 0x100
	s_cmp_lt_i32 s26, s0
	s_mov_b32 s25, s26
	v_mfma_f32_32x32x16_f16 v[2:17], v[46:49], v[34:37], v[2:17]
	s_nop 11
	v_cvt_pk_bf16_f32 v2, v2, v3
	v_cvt_pk_bf16_f32 v3, v4, v5
	v_mfma_f32_32x32x16_f16 v[18:33], v[70:73], v[18:21], 0
	v_cvt_pk_bf16_f32 v4, v6, v7
	v_mfma_f32_32x32x16_f16 v[18:33], v[82:85], v[42:45], v[18:33]
	v_cvt_pk_bf16_f32 v5, v8, v9
	v_permlane32_swap_b32_e32 v2, v4
	s_nop 0
	v_permlane32_swap_b32_e32 v3, v5
	global_store_dwordx4 v[100:101], v[2:5], off
	v_mfma_f32_32x32x16_f16 v[18:33], v[86:89], v[38:41], v[18:33]
	s_nop 0
	v_cvt_pk_bf16_f32 v2, v10, v11
	v_cvt_pk_bf16_f32 v4, v14, v15
	v_mfma_f32_32x32x16_f16 v[18:33], v[90:93], v[34:37], v[18:33]
	v_cvt_pk_bf16_f32 v3, v12, v13
	v_cvt_pk_bf16_f32 v5, v16, v17
	v_permlane32_swap_b32_e32 v2, v4
	s_nop 0
	v_permlane32_swap_b32_e32 v3, v5
	global_store_dwordx4 v[100:101], v[2:5], off offset:32
	s_nop 5
	v_cvt_pk_bf16_f32 v2, v18, v19
	v_cvt_pk_bf16_f32 v4, v22, v23
	v_cvt_pk_bf16_f32 v3, v20, v21
	v_cvt_pk_bf16_f32 v5, v24, v25
	v_permlane32_swap_b32_e32 v2, v4
	s_nop 0
	v_permlane32_swap_b32_e32 v3, v5
	global_store_dwordx4 v[100:101], v[2:5], off offset:64
	s_nop 1
	v_cvt_pk_bf16_f32 v2, v26, v27
	v_cvt_pk_bf16_f32 v4, v30, v31
	v_cvt_pk_bf16_f32 v3, v28, v29
	v_cvt_pk_bf16_f32 v5, v32, v33
	v_permlane32_swap_b32_e32 v2, v4
	s_nop 0
	v_permlane32_swap_b32_e32 v3, v5
	v_mov_b32_e32 v18, v78
	v_mov_b32_e32 v19, v79
	v_mov_b32_e32 v20, v80
	v_mov_b32_e32 v21, v81
	v_mov_b32_e32 v42, v74
	v_mov_b32_e32 v43, v75
	v_mov_b32_e32 v44, v76
	v_mov_b32_e32 v45, v77
	v_mov_b32_e32 v38, v66
	v_mov_b32_e32 v39, v67
	v_mov_b32_e32 v40, v68
	v_mov_b32_e32 v41, v69
	v_mov_b32_e32 v34, v62
	v_mov_b32_e32 v35, v63
	v_mov_b32_e32 v36, v64
	v_mov_b32_e32 v37, v65
	global_store_dwordx4 v[100:101], v[2:5], off offset:96
	s_cbranch_scc0 .LBB0_517

.LBB0_582:
	s_or_b64 exec, exec, s[4:5]
	v_cndmask_b32_e32 v57, v1, v138, vcc
	v_lshl_add_u64 v[54:55], v[54:55], 0, v[110:111]
	v_and_b32_e32 v57, v57, v128
	global_load_dwordx4 v[62:65], v[54:55], off
	v_lshlrev_b64 v[54:55], 11, v[128:129]
	v_lshl_add_u64 v[58:59], v[114:115], 0, v[54:55]
	v_lshl_add_u64 v[54:55], v[116:117], 0, v[54:55]
	v_cmp_ne_u32_e32 vcc, 0, v57
	global_load_dwordx4 v[70:73], v[58:59], off
	global_load_dwordx4 v[66:69], v[54:55], off
	v_subbrev_co_u32_e32 v54, vcc, 0, v128, vcc
	v_cmp_lt_u32_e32 vcc, v57, v56
	v_ashrrev_i32_e32 v55, 31, v54
	v_lshlrev_b64 v[54:55], 11, v[54:55]
	v_addc_co_u32_e32 v56, vcc, 0, v128, vcc
	v_ashrrev_i32_e32 v57, 31, v56
	v_lshlrev_b64 v[56:57], 11, v[56:57]
	v_lshl_add_u64 v[54:55], v[116:117], 0, v[54:55]
	v_lshl_add_u64 v[56:57], v[116:117], 0, v[56:57]
	global_load_dwordx4 v[78:81], v[54:55], off
	global_load_dwordx4 v[74:77], v[56:57], off
	v_max_i32_e32 v56, 0x1000, v128
	v_add_u32_e32 v56, 0xfffff000, v56
	v_mov_b32_e32 v57, v111
	v_lshlrev_b64 v[54:55], 12, v[128:129]
	v_lshlrev_b64 v[56:57], 11, v[56:57]
	v_lshlrev_b64 v[128:129], 7, v[128:129]
	v_lshl_add_u64 v[54:55], v[118:119], 0, v[54:55]
	v_lshl_add_u64 v[56:57], v[120:121], 0, v[56:57]
	v_lshl_add_u64 v[128:129], v[122:123], 0, v[128:129]
	global_load_dwordx4 v[58:61], v[54:55], off
	s_nop 0
	global_load_dwordx4 v[54:57], v[56:57], off
	v_cmp_lt_i32_e64 s[6:7], s1, v139
	global_load_dwordx2 v[128:129], v[128:129], off
	s_waitcnt vmcnt(22)
	v_lshlrev_b32_e32 v137, 16, v98
	v_cndmask_b32_e64 v132, v138, v1, s[6:7]
	v_and_b32_e32 v136, v132, v139
	v_cmp_eq_u32_e32 vcc, 0, v136
	s_waitcnt vmcnt(21)
	v_lshlrev_b32_e32 v139, 16, v102
	v_cmp_eq_u32_e64 s[4:5], v136, v132
	v_cndmask_b32_e64 v137, v137, 0, vcc
	v_and_b32_e32 v98, 0xffff0000, v98
	v_cndmask_b32_e64 v132, v139, 0, s[4:5]
	v_and_b32_e32 v102, 0xffff0000, v102
	v_add_f32_e32 v132, v137, v132
	v_cndmask_b32_e64 v98, v98, 0, vcc
	v_cndmask_b32_e64 v102, v102, 0, s[4:5]
	v_lshlrev_b32_e32 v137, 16, v91
	v_lshlrev_b32_e32 v136, 16, v90
	v_lshlrev_b32_e32 v143, 16, v95
	v_lshlrev_b32_e32 v142, 16, v94
	v_and_b32_e32 v91, 0xffff0000, v91
	v_and_b32_e32 v90, 0xffff0000, v90
	v_and_b32_e32 v95, 0xffff0000, v95
	v_and_b32_e32 v94, 0xffff0000, v94
	v_add_f32_e32 v102, v98, v102
	v_mul_f32_e32 v98, 0.5, v132
	s_waitcnt vmcnt(19)
	v_lshlrev_b32_e32 v132, 16, v106
	v_lshlrev_b32_e32 v139, 16, v107
	v_pk_add_f32 v[90:91], v[90:91], v[94:95]
	v_and_b32_e32 v94, 0xffff0000, v107
	v_and_b32_e32 v106, 0xffff0000, v106
	v_pk_add_f32 v[136:137], v[136:137], v[142:143]
	v_cndmask_b32_e64 v143, 0, v139, s[6:7]
	v_cndmask_b32_e64 v142, 0, v132, s[6:7]
	v_cndmask_b32_e64 v95, 0, v94, s[6:7]
	v_cndmask_b32_e64 v94, 0, v106, s[6:7]
	v_pk_add_f32 v[136:137], v[136:137], v[142:143]
	v_pk_add_f32 v[90:91], v[90:91], v[94:95]
	v_lshlrev_b32_e32 v106, 16, v103
	v_pk_add_f32 v[94:95], v[136:137], v[90:91]
	v_cndmask_b32_e64 v106, v106, 0, s[4:5]
	v_add_f32_e32 v94, 0, v94
	v_add_f32_e32 v95, v95, v94
	v_lshlrev_b32_e32 v94, 16, v99
	v_cndmask_b32_e64 v94, v94, 0, vcc
	v_and_b32_e32 v99, 0xffff0000, v99
	v_and_b32_e32 v103, 0xffff0000, v103
	v_add_f32_e32 v94, v94, v106
	v_cndmask_b32_e64 v99, v99, 0, vcc
	v_cndmask_b32_e64 v103, v103, 0, s[4:5]
	v_add_f32_e32 v103, v99, v103
	v_mul_f32_e32 v99, 0.5, v94
	v_lshlrev_b32_e32 v94, 16, v100
	v_lshlrev_b32_e32 v106, 16, v104
	v_and_b32_e32 v100, 0xffff0000, v100
	v_and_b32_e32 v104, 0xffff0000, v104
	v_cndmask_b32_e64 v94, v94, 0, vcc
	v_cndmask_b32_e64 v106, v106, 0, s[4:5]
	v_cndmask_b32_e64 v100, v100, 0, vcc
	v_cndmask_b32_e64 v104, v104, 0, s[4:5]
	v_add_f32_e32 v94, v94, v106
	v_add_f32_e32 v100, v100, v104
	v_lshlrev_b32_e32 v107, 16, v93
	v_lshlrev_b32_e32 v106, 16, v92
	v_lshlrev_b32_e32 v143, 16, v97
	v_lshlrev_b32_e32 v142, 16, v96
	v_lshlrev_b32_e32 v104, 16, v108
	v_and_b32_e32 v93, 0xffff0000, v93
	v_and_b32_e32 v92, 0xffff0000, v92
	v_and_b32_e32 v97, 0xffff0000, v97
	v_and_b32_e32 v96, 0xffff0000, v96
	v_pk_add_f32 v[106:107], v[106:107], v[142:143]
	v_lshlrev_b32_e32 v132, 16, v109
	v_cndmask_b32_e64 v142, 0, v104, s[6:7]
	v_pk_add_f32 v[92:93], v[92:93], v[96:97]
	v_and_b32_e32 v96, 0xffff0000, v109
	v_and_b32_e32 v104, 0xffff0000, v108
	v_cndmask_b32_e64 v143, 0, v132, s[6:7]
	v_cndmask_b32_e64 v97, 0, v96, s[6:7]
	v_cndmask_b32_e64 v96, 0, v104, s[6:7]
	v_pk_add_f32 v[106:107], v[106:107], v[142:143]
	v_pk_add_f32 v[92:93], v[92:93], v[96:97]
	v_lshlrev_b32_e32 v109, 16, v87
	v_pk_add_f32 v[96:97], v[106:107], v[92:93]
	v_lshlrev_b32_e32 v108, 16, v86
	v_add_f32_e32 v95, v96, v95
	v_add_f32_e32 v96, v97, v95
	v_lshlrev_b32_e32 v95, 16, v101
	v_lshlrev_b32_e32 v97, 16, v105
	v_cndmask_b32_e64 v95, v95, 0, vcc
	v_cndmask_b32_e64 v97, v97, 0, s[4:5]
	v_add_f32_dpp v96, v96, v96 quad_perm:[1,0,3,2] row_mask:0xf bank_mask:0xf bound_ctrl:1
	v_add_f32_e32 v95, v95, v97
	v_and_b32_e32 v97, 0xffff0000, v101
	v_and_b32_e32 v101, 0xffff0000, v105
	v_add_f32_dpp v96, v96, v96 quad_perm:[2,3,0,1] row_mask:0xf bank_mask:0xf bound_ctrl:1
	v_cndmask_b32_e64 v97, v97, 0, vcc
	v_cndmask_b32_e64 v101, v101, 0, s[4:5]
	v_add_f32_dpp v96, v96, v96 row_half_mirror row_mask:0xf bank_mask:0xf bound_ctrl:1
	v_add_f32_e32 v97, v97, v101
	v_mul_f32_e32 v96, 0x3c800000, v96
	v_pk_add_f32 v[98:99], v[98:99], v[108:109] neg_lo:[0,1] neg_hi:[0,1]
	v_pk_add_f32 v[90:91], v[90:91], v[96:97] op_sel_hi:[1,0] neg_lo:[0,1] neg_hi:[0,1]
	v_pk_fma_f32 v[98:99], v[2:3], v[98:99], v[108:109]
	v_pk_add_f32 v[108:109], v[136:137], v[96:97] op_sel_hi:[1,0] neg_lo:[0,1] neg_hi:[0,1]
	v_mul_f32_e32 v100, 0.5, v100
	v_mul_f32_e32 v101, 0.5, v97
	s_waitcnt vmcnt(18)
	v_add_f32_e32 v104, v134, v135
	v_mov_b32_e32 v134, v108
	v_mov_b32_e32 v135, v90
	v_lshlrev_b32_e32 v143, 16, v89
	v_lshlrev_b32_e32 v142, 16, v88
	v_and_b32_e32 v89, 0xffff0000, v89
	v_and_b32_e32 v88, 0xffff0000, v88
	v_pk_mul_f32 v[134:135], v[134:135], v[134:135]
	v_mov_b32_e32 v136, v91
	v_mov_b32_e32 v137, v109
	v_pk_add_f32 v[100:101], v[100:101], v[88:89] neg_lo:[0,1] neg_hi:[0,1]
	v_lshlrev_b32_e32 v97, 16, v85
	v_pk_mul_f32 v[136:137], v[136:137], v[136:137]
	v_pk_fma_f32 v[88:89], v[8:9], v[100:101], v[88:89]
	v_pk_add_f32 v[100:101], v[106:107], v[96:97] op_sel_hi:[1,0] neg_lo:[0,1] neg_hi:[0,1]
	v_pk_add_f32 v[92:93], v[92:93], v[96:97] op_sel_hi:[1,0] neg_lo:[0,1] neg_hi:[0,1]
	v_add_f32_e32 v96, v134, v135
	v_mul_f32_e32 v94, 0.5, v94
	v_mul_f32_e32 v95, 0.5, v95
	v_mov_b32_e32 v106, v92
	v_mov_b32_e32 v107, v100
	v_add_f32_e32 v96, v137, v96
	v_pk_add_f32 v[94:95], v[94:95], v[142:143] neg_lo:[0,1] neg_hi:[0,1]
	v_pk_mul_f32 v[106:107], v[106:107], v[106:107]
	v_add_f32_e32 v96, v136, v96
	v_pk_fma_f32 v[94:95], v[6:7], v[94:95], v[142:143]
	v_mov_b32_e32 v142, v93
	v_mov_b32_e32 v143, v101
	v_add_f32_e32 v96, v107, v96
	v_pk_mul_f32 v[142:143], v[142:143], v[142:143]
	v_add_f32_e32 v96, v106, v96
	v_add_f32_e32 v96, v143, v96
	v_add_f32_e32 v96, v142, v96
	v_mul_f32_e32 v102, 0.5, v102
	v_mul_f32_e32 v103, 0.5, v103
	v_add_f32_dpp v96, v96, v96 quad_perm:[1,0,3,2] row_mask:0xf bank_mask:0xf bound_ctrl:1
	v_and_b32_e32 v87, 0xffff0000, v87
	v_and_b32_e32 v86, 0xffff0000, v86
	v_add_f32_dpp v96, v96, v96 quad_perm:[2,3,0,1] row_mask:0xf bank_mask:0xf bound_ctrl:1
	v_pk_add_f32 v[102:103], v[102:103], v[86:87] neg_lo:[0,1] neg_hi:[0,1]
	v_and_b32_e32 v85, 0xffff0000, v85
	v_add_f32_dpp v96, v96, v96 row_half_mirror row_mask:0xf bank_mask:0xf bound_ctrl:1
	v_fmamk_f32 v96, v96, 0x3c800000, v133
	v_mul_f32_e32 v105, 0x4b800000, v96
	v_cmp_gt_f32_e32 vcc, s28, v96
	v_pk_fma_f32 v[86:87], v[4:5], v[102:103], v[86:87]
	v_lshlrev_b32_e32 v103, 16, v83
	v_cndmask_b32_e32 v96, v96, v105, vcc
	v_rsq_f32_e32 v105, v96
	v_lshlrev_b32_e32 v102, 16, v82
	v_and_b32_e32 v83, 0xffff0000, v83
	v_and_b32_e32 v82, 0xffff0000, v82
	v_mul_f32_e32 v106, 0x45800000, v105
	v_cndmask_b32_e32 v106, v105, v106, vcc
	v_pk_mul_f32 v[90:91], v[90:91], v[106:107] op_sel_hi:[1,0]
	v_pk_mul_f32 v[108:109], v[108:109], v[106:107] op_sel_hi:[1,0]
	v_pk_fma_f32 v[90:91], v[20:21], v[90:91], v[24:25]
	v_lshlrev_b32_e32 v96, 16, v84
	v_pk_fma_f32 v[86:87], v[104:105], v[86:87], v[90:91] op_sel_hi:[0,1,1]
	v_pk_mul_f32 v[90:91], v[92:93], v[106:107] op_sel_hi:[1,0]
	v_pk_mul_f32 v[82:83], v[86:87], v[82:83]
	v_pk_mul_f32 v[86:87], v[100:101], v[106:107] op_sel_hi:[1,0]
	v_pk_fma_f32 v[90:91], v[12:13], v[90:91], v[16:17]
	v_and_b32_e32 v84, 0xffff0000, v84
	v_pk_fma_f32 v[108:109], v[18:19], v[108:109], v[22:23]
	v_pk_fma_f32 v[86:87], v[10:11], v[86:87], v[14:15]
	v_pk_fma_f32 v[88:89], v[104:105], v[88:89], v[90:91] op_sel_hi:[0,1,1]
	v_pk_fma_f32 v[98:99], v[104:105], v[98:99], v[108:109] op_sel_hi:[0,1,1]
	v_pk_fma_f32 v[86:87], v[104:105], v[94:95], v[86:87] op_sel_hi:[0,1,1]
	v_pk_mul_f32 v[84:85], v[88:89], v[84:85]
	v_pk_mul_f32 v[98:99], v[98:99], v[102:103]
	v_pk_mul_f32 v[86:87], v[86:87], v[96:97]
	v_cvt_pk_bf16_f32 v85, v87, v85
	v_cvt_pk_bf16_f32 v84, v86, v84
	v_cvt_pk_bf16_f32 v83, v99, v83
	v_cvt_pk_bf16_f32 v82, v98, v82
	v_lshl_add_u64 v[86:87], v[130:131], 0, v[126:127]
	global_store_dwordx4 v[86:87], v[82:85], off

.LBB0_585:
	v_add_u32_e32 v139, s2, v132
	s_waitcnt vmcnt(1)
	v_min_i32_e32 v134, 0x4fff, v139
	v_cmp_gt_i32_e32 vcc, s26, v139
	v_cmp_lt_i32_e64 s[4:5], s1, v139
	s_and_saveexec_b64 s[6:7], s[4:5]
	s_xor_b64 s[4:5], exec, s[6:7]
	v_add_u32_e32 v82, 0xfffff000, v134
	v_mov_b32_e32 v83, v111
	v_lshlrev_b64 v[82:83], 11, v[82:83]
	v_lshl_add_u64 v[82:83], s[18:19], 0, v[82:83]
	v_mov_b32_e32 v135, v111
	s_or_saveexec_b64 s[4:5], s[4:5]
	v_mov_b32_e32 v84, 0xfff
	s_xor_b64 exec, exec, s[4:5]
	v_ashrrev_i32_e32 v135, 31, v134
	v_lshlrev_b64 v[82:83], 11, v[134:135]
	v_lshl_add_u64 v[82:83], s[16:17], 0, v[82:83]
	v_mov_b32_e32 v84, 0xff
	s_or_b64 exec, exec, s[4:5]
	v_cndmask_b32_e32 v85, v1, v138, vcc
	v_lshl_add_u64 v[82:83], v[82:83], 0, v[110:111]
	v_and_b32_e32 v85, v85, v134
	global_load_dwordx4 v[90:93], v[82:83], off
	v_lshlrev_b64 v[82:83], 11, v[134:135]
	v_lshl_add_u64 v[86:87], v[114:115], 0, v[82:83]
	v_lshl_add_u64 v[82:83], v[116:117], 0, v[82:83]
	v_cmp_ne_u32_e32 vcc, 0, v85
	global_load_dwordx4 v[94:97], v[86:87], off
	s_nop 0
	global_load_dwordx4 v[86:89], v[82:83], off
	v_subbrev_co_u32_e32 v82, vcc, 0, v134, vcc
	v_cmp_lt_u32_e32 vcc, v85, v84
	v_ashrrev_i32_e32 v83, 31, v82
	v_lshlrev_b64 v[82:83], 11, v[82:83]
	v_addc_co_u32_e32 v84, vcc, 0, v134, vcc
	v_ashrrev_i32_e32 v85, 31, v84
	v_lshlrev_b64 v[84:85], 11, v[84:85]
	v_lshl_add_u64 v[82:83], v[116:117], 0, v[82:83]
	v_lshl_add_u64 v[84:85], v[116:117], 0, v[84:85]
	global_load_dwordx4 v[98:101], v[82:83], off
	global_load_dwordx4 v[102:105], v[84:85], off
	v_max_i32_e32 v84, 0x1000, v134
	v_add_u32_e32 v84, 0xfffff000, v84
	v_mov_b32_e32 v85, v111
	v_lshlrev_b64 v[82:83], 12, v[134:135]
	v_lshlrev_b64 v[84:85], 11, v[84:85]
	v_lshlrev_b64 v[134:135], 7, v[134:135]
	v_lshl_add_u64 v[82:83], v[118:119], 0, v[82:83]
	v_lshl_add_u64 v[106:107], v[120:121], 0, v[84:85]
	v_lshl_add_u64 v[134:135], v[122:123], 0, v[134:135]
	global_load_dwordx4 v[82:85], v[82:83], off
	s_nop 0
	global_load_dwordx4 v[106:109], v[106:107], off
	v_cmp_lt_i32_e64 s[6:7], s1, v132
	global_load_dwordx2 v[134:135], v[134:135], off
	s_waitcnt vmcnt(20)
	v_lshlrev_b32_e32 v140, 16, v38
	v_cndmask_b32_e64 v136, v138, v1, s[6:7]
	v_and_b32_e32 v137, v136, v132
	v_cmp_eq_u32_e32 vcc, 0, v137
	s_waitcnt vmcnt(19)
	v_lshlrev_b32_e32 v141, 16, v42
	v_cmp_eq_u32_e64 s[4:5], v137, v136
	v_cndmask_b32_e64 v140, v140, 0, vcc
	v_and_b32_e32 v137, 0xffff0000, v38
	v_cndmask_b32_e64 v136, v141, 0, s[4:5]
	v_add_f32_e32 v136, v140, v136
	v_and_b32_e32 v140, 0xffff0000, v42
	v_cndmask_b32_e64 v137, v137, 0, vcc
	v_cndmask_b32_e64 v140, v140, 0, s[4:5]
	v_add_f32_e32 v137, v137, v140
	v_mul_f32_e32 v140, 0.5, v137
	v_lshlrev_b32_e32 v143, 16, v27
	v_lshlrev_b32_e32 v142, 16, v26
	v_lshlrev_b32_e32 v145, 16, v31
	v_lshlrev_b32_e32 v144, 16, v30
	s_waitcnt vmcnt(17)
	v_lshlrev_b32_e32 v137, 16, v50
	v_lshlrev_b32_e32 v141, 16, v51
	v_pk_add_f32 v[142:143], v[144:145], v[142:143]
	v_cndmask_b32_e64 v145, 0, v141, s[6:7]
	v_cndmask_b32_e64 v144, 0, v137, s[6:7]
	v_pk_add_f32 v[142:143], v[144:145], v[142:143]
	v_and_b32_e32 v145, 0xffff0000, v27
	v_and_b32_e32 v144, 0xffff0000, v26
	v_and_b32_e32 v147, 0xffff0000, v31
	v_and_b32_e32 v146, 0xffff0000, v30
	v_and_b32_e32 v137, 0xffff0000, v51
	v_and_b32_e32 v141, 0xffff0000, v50
	v_pk_add_f32 v[144:145], v[146:147], v[144:145]
	v_cndmask_b32_e64 v147, 0, v137, s[6:7]
	v_cndmask_b32_e64 v146, 0, v141, s[6:7]
	v_pk_add_f32 v[144:145], v[146:147], v[144:145]
	v_lshlrev_b32_e32 v141, 16, v43
	v_pk_add_f32 v[146:147], v[142:143], v[144:145]
	v_cndmask_b32_e64 v141, v141, 0, s[4:5]
	v_add_f32_e32 v137, 0, v146
	v_add_f32_e32 v147, v147, v137
	v_lshlrev_b32_e32 v137, 16, v39
	v_cndmask_b32_e64 v137, v137, 0, vcc
	v_add_f32_e32 v137, v137, v141
	v_and_b32_e32 v141, 0xffff0000, v39
	v_and_b32_e32 v146, 0xffff0000, v43
	v_cndmask_b32_e64 v141, v141, 0, vcc
	v_cndmask_b32_e64 v146, v146, 0, s[4:5]
	v_add_f32_e32 v141, v141, v146
	v_lshlrev_b32_e32 v146, 16, v40
	v_lshlrev_b32_e32 v148, 16, v44
	v_cndmask_b32_e64 v146, v146, 0, vcc
	v_cndmask_b32_e64 v148, v148, 0, s[4:5]
	v_add_f32_e32 v146, v146, v148
	v_and_b32_e32 v148, 0xffff0000, v40
	v_and_b32_e32 v149, 0xffff0000, v44
	v_cndmask_b32_e64 v148, v148, 0, vcc
	v_cndmask_b32_e64 v149, v149, 0, s[4:5]
	v_lshlrev_b32_e32 v151, 16, v29
	v_lshlrev_b32_e32 v150, 16, v28
	v_lshlrev_b32_e32 v153, 16, v33
	v_lshlrev_b32_e32 v152, 16, v32
	v_add_f32_e32 v148, v148, v149
	v_pk_add_f32 v[150:151], v[152:153], v[150:151]
	v_lshlrev_b32_e32 v149, 16, v52
	v_lshlrev_b32_e32 v152, 16, v53
	v_cndmask_b32_e64 v153, 0, v152, s[6:7]
	v_cndmask_b32_e64 v152, 0, v149, s[6:7]
	v_pk_add_f32 v[150:151], v[152:153], v[150:151]
	v_and_b32_e32 v153, 0xffff0000, v29
	v_and_b32_e32 v152, 0xffff0000, v28
	v_and_b32_e32 v155, 0xffff0000, v33
	v_and_b32_e32 v154, 0xffff0000, v32
	v_pk_add_f32 v[152:153], v[154:155], v[152:153]
	v_and_b32_e32 v149, 0xffff0000, v53
	v_and_b32_e32 v154, 0xffff0000, v52
	v_cndmask_b32_e64 v155, 0, v149, s[6:7]
	v_cndmask_b32_e64 v154, 0, v154, s[6:7]
	v_pk_add_f32 v[152:153], v[154:155], v[152:153]
	v_lshlrev_b32_e32 v149, 16, v45
	v_pk_add_f32 v[154:155], v[150:151], v[152:153]
	v_cndmask_b32_e64 v149, v149, 0, s[4:5]
	v_add_f32_e32 v147, v154, v147
	v_add_f32_e32 v154, v155, v147
	v_lshlrev_b32_e32 v147, 16, v41
	v_and_b32_e32 v155, 0xffff0000, v45
	v_add_f32_dpp v154, v154, v154 quad_perm:[1,0,3,2] row_mask:0xf bank_mask:0xf bound_ctrl:1
	v_cndmask_b32_e64 v147, v147, 0, vcc
	v_cndmask_b32_e64 v155, v155, 0, s[4:5]
	v_add_f32_dpp v154, v154, v154 quad_perm:[2,3,0,1] row_mask:0xf bank_mask:0xf bound_ctrl:1
	v_add_f32_e32 v147, v147, v149
	v_and_b32_e32 v149, 0xffff0000, v41
	v_add_f32_dpp v154, v154, v154 row_half_mirror row_mask:0xf bank_mask:0xf bound_ctrl:1
	v_mul_f32_e32 v154, 0x3c800000, v154
	v_pk_add_f32 v[142:143], v[142:143], v[154:155] op_sel_hi:[1,0] neg_lo:[0,1] neg_hi:[0,1]
	v_pk_add_f32 v[144:145], v[144:145], v[154:155] op_sel_hi:[1,0] neg_lo:[0,1] neg_hi:[0,1]
	v_cndmask_b32_e64 v149, v149, 0, vcc
	v_mov_b32_e32 v160, v142
	v_mov_b32_e32 v161, v144
	v_mul_f32_e32 v146, 0.5, v146
	v_add_f32_e32 v149, v149, v155
	v_mul_f32_e32 v147, 0.5, v147
	v_pk_mul_f32 v[160:161], v[160:161], v[160:161]
	v_mov_b32_e32 v162, v145
	v_mov_b32_e32 v163, v143
	v_lshlrev_b32_e32 v169, 16, v37
	v_lshlrev_b32_e32 v168, 16, v36
	v_lshlrev_b32_e32 v155, 16, v49
	v_pk_mul_f32 v[162:163], v[162:163], v[162:163]
	v_pk_add_f32 v[146:147], v[146:147], v[168:169] neg_lo:[0,1] neg_hi:[0,1]
	v_pk_add_f32 v[150:151], v[150:151], v[154:155] op_sel_hi:[1,0] neg_lo:[0,1] neg_hi:[0,1]
	v_pk_add_f32 v[152:153], v[152:153], v[154:155] op_sel_hi:[1,0] neg_lo:[0,1] neg_hi:[0,1]
	v_add_f32_e32 v154, v160, v161
	v_mul_f32_e32 v148, 0.5, v148
	v_mul_f32_e32 v149, 0.5, v149
	v_and_b32_e32 v171, 0xffff0000, v37
	v_and_b32_e32 v170, 0xffff0000, v36
	v_pk_fma_f32 v[146:147], v[6:7], v[146:147], v[168:169]
	v_mov_b32_e32 v168, v152
	v_mov_b32_e32 v169, v150
	v_add_f32_e32 v154, v163, v154
	v_pk_add_f32 v[148:149], v[148:149], v[170:171] neg_lo:[0,1] neg_hi:[0,1]
	v_pk_mul_f32 v[168:169], v[168:169], v[168:169]
	v_add_f32_e32 v154, v162, v154
	v_pk_fma_f32 v[148:149], v[8:9], v[148:149], v[170:171]
	v_mov_b32_e32 v170, v153
	v_mov_b32_e32 v171, v151
	v_add_f32_e32 v154, v169, v154
	v_pk_mul_f32 v[170:171], v[170:171], v[170:171]
	v_add_f32_e32 v154, v168, v154
	v_add_f32_e32 v154, v171, v154
	v_add_f32_e32 v154, v170, v154
	v_mul_f32_e32 v136, 0.5, v136
	v_mul_f32_e32 v137, 0.5, v137
	v_add_f32_dpp v154, v154, v154 quad_perm:[1,0,3,2] row_mask:0xf bank_mask:0xf bound_ctrl:1
	v_lshlrev_b32_e32 v157, 16, v35
	v_lshlrev_b32_e32 v156, 16, v34
	v_add_f32_dpp v154, v154, v154 quad_perm:[2,3,0,1] row_mask:0xf bank_mask:0xf bound_ctrl:1
	v_pk_add_f32 v[136:137], v[136:137], v[156:157] neg_lo:[0,1] neg_hi:[0,1]
	v_mul_f32_e32 v141, 0.5, v141
	v_add_f32_dpp v154, v154, v154 row_half_mirror row_mask:0xf bank_mask:0xf bound_ctrl:1
	v_fmamk_f32 v154, v154, 0x3c800000, v133
	v_mul_f32_e32 v160, 0x4b800000, v154
	v_cmp_gt_f32_e32 vcc, s28, v154
	v_and_b32_e32 v159, 0xffff0000, v35
	v_and_b32_e32 v158, 0xffff0000, v34
	v_cndmask_b32_e32 v154, v154, v160, vcc
	v_rsq_f32_e32 v162, v154
	v_pk_fma_f32 v[136:137], v[2:3], v[136:137], v[156:157]
	s_waitcnt vmcnt(16)
	v_pk_add_f32 v[164:165], v[112:113], v[112:113] op_sel:[1,0] op_sel_hi:[1,0]
	v_pk_add_f32 v[140:141], v[140:141], v[158:159] neg_lo:[0,1] neg_hi:[0,1]
	v_mul_f32_e32 v163, 0x45800000, v162
	v_cndmask_b32_e32 v162, v162, v163, vcc
	v_pk_mul_f32 v[142:143], v[142:143], v[162:163] op_sel_hi:[1,0]
	v_pk_fma_f32 v[140:141], v[4:5], v[140:141], v[158:159]
	v_pk_fma_f32 v[142:143], v[18:19], v[142:143], v[22:23]
	v_and_b32_e32 v159, 0xffff0000, v47
	v_pk_fma_f32 v[136:137], v[164:165], v[136:137], v[142:143]
	v_pk_mul_f32 v[142:143], v[144:145], v[162:163] op_sel_hi:[1,0]
	v_pk_mul_f32 v[144:145], v[152:153], v[162:163] op_sel_hi:[1,0]
	v_pk_fma_f32 v[142:143], v[20:21], v[142:143], v[24:25]
	v_pk_fma_f32 v[144:145], v[12:13], v[144:145], v[16:17]
	v_pk_fma_f32 v[140:141], v[164:165], v[140:141], v[142:143]
	v_pk_mul_f32 v[142:143], v[150:151], v[162:163] op_sel_hi:[1,0]
	v_and_b32_e32 v158, 0xffff0000, v46
	v_and_b32_e32 v161, 0xffff0000, v49
	v_and_b32_e32 v160, 0xffff0000, v48
	v_pk_fma_f32 v[142:143], v[10:11], v[142:143], v[14:15]
	v_pk_fma_f32 v[144:145], v[164:165], v[148:149], v[144:145]
	v_lshlrev_b32_e32 v157, 16, v47
	v_lshlrev_b32_e32 v156, 16, v46
	v_lshlrev_b32_e32 v154, 16, v48
	v_pk_mul_f32 v[140:141], v[140:141], v[158:159]
	v_pk_fma_f32 v[142:143], v[164:165], v[146:147], v[142:143]
	v_pk_mul_f32 v[144:145], v[144:145], v[160:161]
	v_pk_mul_f32 v[136:137], v[136:137], v[156:157]
	v_pk_mul_f32 v[142:143], v[142:143], v[154:155]
	v_cvt_pk_bf16_f32 v143, v143, v145
	v_cvt_pk_bf16_f32 v142, v142, v144
	v_cvt_pk_bf16_f32 v141, v137, v141
	v_cvt_pk_bf16_f32 v140, v136, v140
	v_lshl_add_u64 v[136:137], v[130:131], 0, v[124:125]
	global_store_dwordx4 v[136:137], v[140:143], off
	v_add_u32_e32 v136, s0, v132
	v_cmp_lt_i32_e32 vcc, s9, v136
	s_and_saveexec_b64 s[4:5], vcc
	s_xor_b64 s[4:5], exec, s[4:5]
	v_add_u32_e32 v140, s8, v132
	s_andn2_saveexec_b64 s[22:23], s[4:5]
	s_cbranch_execz .LBB0_584
	v_add_u32_e32 v140, s8, v132
	v_min_i32_e32 v112, 0x4fff, v140
	v_cmp_gt_i32_e32 vcc, s26, v140
	v_cmp_lt_i32_e64 s[4:5], s1, v140
	s_and_saveexec_b64 s[6:7], s[4:5]
	s_xor_b64 s[4:5], exec, s[6:7]
	v_add_u32_e32 v26, 0xfffff000, v112
	v_mov_b32_e32 v27, v111
	v_lshlrev_b64 v[26:27], 11, v[26:27]
	v_lshl_add_u64 v[26:27], s[18:19], 0, v[26:27]
	v_mov_b32_e32 v113, v111
	s_or_saveexec_b64 s[4:5], s[4:5]
	v_mov_b32_e32 v38, 0xfff
	s_xor_b64 exec, exec, s[4:5]
	v_ashrrev_i32_e32 v113, 31, v112
	v_lshlrev_b64 v[26:27], 11, v[112:113]
	v_lshl_add_u64 v[26:27], s[16:17], 0, v[26:27]
	v_mov_b32_e32 v38, 0xff
	s_or_b64 exec, exec, s[4:5]
	v_cndmask_b32_e32 v28, v1, v138, vcc
	v_and_b32_e32 v39, v28, v112
	v_cmp_ne_u32_e32 vcc, 0, v39
	v_max_i32_e32 v48, 0x1000, v112
	v_add_u32_e32 v48, 0xfffff000, v48
	v_subbrev_co_u32_e32 v40, vcc, 0, v112, vcc
	v_cmp_lt_u32_e32 vcc, v39, v38
	v_ashrrev_i32_e32 v41, 31, v40
	v_mov_b32_e32 v49, v111
	v_addc_co_u32_e32 v38, vcc, 0, v112, vcc
	v_ashrrev_i32_e32 v39, 31, v38
	v_lshlrev_b64 v[30:31], 11, v[112:113]
	v_lshlrev_b64 v[40:41], 11, v[40:41]
	v_lshlrev_b64 v[38:39], 11, v[38:39]
	v_lshlrev_b64 v[46:47], 12, v[112:113]
	v_lshlrev_b64 v[48:49], 11, v[48:49]
	v_lshlrev_b64 v[112:113], 7, v[112:113]
	v_lshl_add_u64 v[26:27], v[26:27], 0, v[110:111]
	v_lshl_add_u64 v[32:33], v[114:115], 0, v[30:31]
	v_lshl_add_u64 v[34:35], v[116:117], 0, v[30:31]
	v_lshl_add_u64 v[40:41], v[116:117], 0, v[40:41]
	v_lshl_add_u64 v[42:43], v[116:117], 0, v[38:39]
	v_lshl_add_u64 v[46:47], v[118:119], 0, v[46:47]
	v_lshl_add_u64 v[50:51], v[120:121], 0, v[48:49]
	v_lshl_add_u64 v[112:113], v[122:123], 0, v[112:113]
	global_load_dwordx4 v[26:29], v[26:27], off
	s_nop 0
	global_load_dwordx4 v[30:33], v[32:33], off
	s_nop 0
	global_load_dwordx4 v[34:37], v[34:35], off
	s_nop 0
	global_load_dwordx4 v[38:41], v[40:41], off
	s_nop 0
	global_load_dwordx4 v[42:45], v[42:43], off
	s_nop 0
	global_load_dwordx4 v[46:49], v[46:47], off
	s_nop 0
	global_load_dwordx4 v[50:53], v[50:51], off
	v_cmp_lt_i32_e64 s[6:7], s1, v136
	global_load_dwordx2 v[112:113], v[112:113], off
	s_waitcnt vmcnt(20)
	v_lshlrev_b32_e32 v142, 16, v78
	v_cndmask_b32_e64 v137, v138, v1, s[6:7]
	v_and_b32_e32 v141, v137, v136
	v_cmp_eq_u32_e32 vcc, 0, v141
	v_lshlrev_b32_e32 v143, 16, v74
	v_cmp_eq_u32_e64 s[4:5], v141, v137
	v_cndmask_b32_e64 v142, v142, 0, vcc
	v_and_b32_e32 v141, 0xffff0000, v78
	v_cndmask_b32_e64 v137, v143, 0, s[4:5]
	v_add_f32_e32 v137, v142, v137
	v_and_b32_e32 v142, 0xffff0000, v74
	v_cndmask_b32_e64 v141, v141, 0, vcc
	v_cndmask_b32_e64 v142, v142, 0, s[4:5]
	v_add_f32_e32 v141, v141, v142
	v_mul_f32_e32 v142, 0.5, v137
	v_mul_f32_e32 v144, 0.5, v141
	s_waitcnt vmcnt(17)
	v_lshlrev_b32_e32 v147, 16, v63
	v_lshlrev_b32_e32 v146, 16, v62
	v_lshlrev_b32_e32 v149, 16, v71
	v_lshlrev_b32_e32 v148, 16, v70
	v_lshlrev_b32_e32 v137, 16, v54
	v_lshlrev_b32_e32 v141, 16, v55
	v_pk_add_f32 v[146:147], v[148:149], v[146:147]
	v_cndmask_b32_e64 v149, 0, v141, s[6:7]
	v_cndmask_b32_e64 v148, 0, v137, s[6:7]
	v_pk_add_f32 v[146:147], v[146:147], v[148:149]
	v_and_b32_e32 v149, 0xffff0000, v63
	v_and_b32_e32 v148, 0xffff0000, v62
	v_and_b32_e32 v151, 0xffff0000, v71
	v_and_b32_e32 v150, 0xffff0000, v70
	v_and_b32_e32 v141, 0xffff0000, v54
	v_pk_add_f32 v[148:149], v[150:151], v[148:149]
	v_and_b32_e32 v137, 0xffff0000, v55
	v_cndmask_b32_e64 v150, 0, v141, s[6:7]
	v_lshlrev_b32_e32 v141, 16, v79
	v_lshlrev_b32_e32 v143, 16, v75
	v_cndmask_b32_e64 v151, 0, v137, s[6:7]
	v_cndmask_b32_e64 v141, v141, 0, vcc
	v_cndmask_b32_e64 v143, v143, 0, s[4:5]
	v_pk_add_f32 v[148:149], v[148:149], v[150:151]
	v_add_f32_e32 v141, v141, v143
	v_and_b32_e32 v143, 0xffff0000, v79
	v_and_b32_e32 v145, 0xffff0000, v75
	v_pk_add_f32 v[150:151], v[146:147], v[148:149]
	v_cndmask_b32_e64 v143, v143, 0, vcc
	v_cndmask_b32_e64 v145, v145, 0, s[4:5]
	v_add_f32_e32 v137, 0, v150
	v_add_f32_e32 v145, v143, v145
	v_mul_f32_e32 v143, 0.5, v141
	v_lshlrev_b32_e32 v141, 16, v80
	v_lshlrev_b32_e32 v150, 16, v76
	v_cndmask_b32_e64 v141, v141, 0, vcc
	v_cndmask_b32_e64 v150, v150, 0, s[4:5]
	v_add_f32_e32 v137, v151, v137
	v_add_f32_e32 v141, v141, v150
	v_and_b32_e32 v150, 0xffff0000, v80
	v_and_b32_e32 v151, 0xffff0000, v76
	v_cndmask_b32_e64 v150, v150, 0, vcc
	v_cndmask_b32_e64 v151, v151, 0, s[4:5]
	v_add_f32_e32 v151, v150, v151
	v_mul_f32_e32 v150, 0.5, v141
	v_mul_f32_e32 v152, 0.5, v151
	v_lshlrev_b32_e32 v155, 16, v65
	v_lshlrev_b32_e32 v154, 16, v64
	v_lshlrev_b32_e32 v157, 16, v73
	v_lshlrev_b32_e32 v156, 16, v72
	v_lshlrev_b32_e32 v141, 16, v56
	v_lshlrev_b32_e32 v151, 16, v57
	v_pk_add_f32 v[154:155], v[156:157], v[154:155]
	v_cndmask_b32_e64 v157, 0, v151, s[6:7]
	v_cndmask_b32_e64 v156, 0, v141, s[6:7]
	v_pk_add_f32 v[154:155], v[154:155], v[156:157]
	v_and_b32_e32 v157, 0xffff0000, v65
	v_and_b32_e32 v156, 0xffff0000, v64
	v_and_b32_e32 v159, 0xffff0000, v73
	v_and_b32_e32 v158, 0xffff0000, v72
	v_and_b32_e32 v141, 0xffff0000, v57
	v_and_b32_e32 v151, 0xffff0000, v56
	v_pk_add_f32 v[156:157], v[158:159], v[156:157]
	v_cndmask_b32_e64 v159, 0, v141, s[6:7]
	v_cndmask_b32_e64 v158, 0, v151, s[6:7]
	v_pk_add_f32 v[156:157], v[156:157], v[158:159]
	v_lshlrev_b32_e32 v141, 16, v81
	v_pk_add_f32 v[158:159], v[154:155], v[156:157]
	v_lshlrev_b32_e32 v151, 16, v77
	v_add_f32_e32 v137, v158, v137
	v_add_f32_e32 v137, v159, v137
	v_cndmask_b32_e64 v141, v141, 0, vcc
	v_cndmask_b32_e64 v151, v151, 0, s[4:5]
	v_add_f32_dpp v137, v137, v137 quad_perm:[1,0,3,2] row_mask:0xf bank_mask:0xf bound_ctrl:1
	v_add_f32_e32 v141, v141, v151
	v_and_b32_e32 v151, 0xffff0000, v81
	v_add_f32_dpp v137, v137, v137 quad_perm:[2,3,0,1] row_mask:0xf bank_mask:0xf bound_ctrl:1
	v_and_b32_e32 v153, 0xffff0000, v77
	v_cndmask_b32_e64 v151, v151, 0, vcc
	v_add_f32_dpp v137, v137, v137 row_half_mirror row_mask:0xf bank_mask:0xf bound_ctrl:1
	v_mul_f32_e32 v158, 0x3c800000, v137
	v_pk_add_f32 v[146:147], v[146:147], v[158:159] op_sel_hi:[1,0] neg_lo:[0,1] neg_hi:[0,1]
	v_pk_add_f32 v[148:149], v[148:149], v[158:159] op_sel_hi:[1,0] neg_lo:[0,1] neg_hi:[0,1]
	v_cndmask_b32_e64 v153, v153, 0, s[4:5]
	v_mov_b32_e32 v164, v146
	v_mov_b32_e32 v165, v148
	v_add_f32_e32 v153, v151, v153
	v_mul_f32_e32 v151, 0.5, v141
	v_pk_mul_f32 v[164:165], v[164:165], v[164:165]
	v_mov_b32_e32 v168, v149
	v_mov_b32_e32 v169, v147
	v_lshlrev_b32_e32 v173, 16, v69
	v_lshlrev_b32_e32 v172, 16, v68
	v_lshlrev_b32_e32 v159, 16, v61
	v_pk_mul_f32 v[168:169], v[168:169], v[168:169]
	v_pk_add_f32 v[150:151], v[150:151], v[172:173] neg_lo:[0,1] neg_hi:[0,1]
	v_pk_add_f32 v[154:155], v[154:155], v[158:159] op_sel_hi:[1,0] neg_lo:[0,1] neg_hi:[0,1]
	v_pk_add_f32 v[156:157], v[156:157], v[158:159] op_sel_hi:[1,0] neg_lo:[0,1] neg_hi:[0,1]
	v_add_f32_e32 v137, v164, v165
	v_mul_f32_e32 v153, 0.5, v153
	v_and_b32_e32 v175, 0xffff0000, v69
	v_and_b32_e32 v174, 0xffff0000, v68
	v_pk_fma_f32 v[150:151], v[6:7], v[150:151], v[172:173]
	v_mov_b32_e32 v172, v156
	v_mov_b32_e32 v173, v154
	v_add_f32_e32 v137, v169, v137
	v_pk_add_f32 v[152:153], v[152:153], v[174:175] neg_lo:[0,1] neg_hi:[0,1]
	v_pk_mul_f32 v[172:173], v[172:173], v[172:173]
	v_add_f32_e32 v137, v168, v137
	v_pk_fma_f32 v[152:153], v[8:9], v[152:153], v[174:175]
	v_mov_b32_e32 v174, v157
	v_mov_b32_e32 v175, v155
	v_add_f32_e32 v137, v173, v137
	v_pk_mul_f32 v[174:175], v[174:175], v[174:175]
	v_add_f32_e32 v137, v172, v137
	v_add_f32_e32 v137, v175, v137
	v_add_f32_e32 v137, v174, v137
	v_lshlrev_b32_e32 v161, 16, v67
	v_lshlrev_b32_e32 v160, 16, v66
	v_add_f32_dpp v137, v137, v137 quad_perm:[1,0,3,2] row_mask:0xf bank_mask:0xf bound_ctrl:1
	v_pk_add_f32 v[142:143], v[142:143], v[160:161] neg_lo:[0,1] neg_hi:[0,1]
	v_mul_f32_e32 v145, 0.5, v145
	v_add_f32_dpp v137, v137, v137 quad_perm:[2,3,0,1] row_mask:0xf bank_mask:0xf bound_ctrl:1
	v_and_b32_e32 v163, 0xffff0000, v67
	v_and_b32_e32 v162, 0xffff0000, v66
	v_add_f32_dpp v137, v137, v137 row_half_mirror row_mask:0xf bank_mask:0xf bound_ctrl:1
	v_fmamk_f32 v137, v137, 0x3c800000, v133
	v_mul_f32_e32 v141, 0x4b800000, v137
	v_cmp_gt_f32_e32 vcc, s28, v137
	v_pk_fma_f32 v[142:143], v[2:3], v[142:143], v[160:161]
	v_pk_add_f32 v[170:171], v[128:129], v[128:129] op_sel:[0,1] op_sel_hi:[0,1]
	v_cndmask_b32_e32 v137, v137, v141, vcc
	v_rsq_f32_e32 v137, v137
	v_pk_add_f32 v[144:145], v[144:145], v[162:163] neg_lo:[0,1] neg_hi:[0,1]
	v_and_b32_e32 v165, 0xffff0000, v61
	v_pk_fma_f32 v[144:145], v[4:5], v[144:145], v[162:163]
	v_mul_f32_e32 v141, 0x45800000, v137
	v_cndmask_b32_e32 v168, v137, v141, vcc
	v_pk_mul_f32 v[146:147], v[146:147], v[168:169] op_sel_hi:[1,0]
	v_and_b32_e32 v164, 0xffff0000, v60
	v_pk_fma_f32 v[146:147], v[18:19], v[146:147], v[22:23]
	v_and_b32_e32 v163, 0xffff0000, v59
	v_pk_fma_f32 v[142:143], v[170:171], v[142:143], v[146:147]
	v_pk_mul_f32 v[146:147], v[148:149], v[168:169] op_sel_hi:[1,0]
	v_pk_mul_f32 v[148:149], v[156:157], v[168:169] op_sel_hi:[1,0]
	v_pk_fma_f32 v[146:147], v[20:21], v[146:147], v[24:25]
	v_pk_fma_f32 v[148:149], v[12:13], v[148:149], v[16:17]
	v_pk_fma_f32 v[144:145], v[170:171], v[144:145], v[146:147]
	v_pk_mul_f32 v[146:147], v[154:155], v[168:169] op_sel_hi:[1,0]
	v_pk_fma_f32 v[148:149], v[170:171], v[152:153], v[148:149]
	v_pk_fma_f32 v[146:147], v[10:11], v[146:147], v[14:15]
	v_and_b32_e32 v162, 0xffff0000, v58
	v_lshlrev_b32_e32 v158, 16, v60
	v_pk_fma_f32 v[146:147], v[170:171], v[150:151], v[146:147]
	v_pk_mul_f32 v[148:149], v[148:149], v[164:165]
	v_lshlrev_b32_e32 v161, 16, v59
	v_lshlrev_b32_e32 v160, 16, v58
	v_pk_mul_f32 v[144:145], v[144:145], v[162:163]
	v_pk_mul_f32 v[146:147], v[146:147], v[158:159]
	v_pk_mul_f32 v[142:143], v[142:143], v[160:161]
	v_bfe_u32 v150, v145, 16, 1
	v_bfe_u32 v151, v144, 16, 1
	v_add3_u32 v150, v145, v150, s29
	v_bfe_u32 v145, v143, 16, 1
	v_add3_u32 v151, v144, v151, s29
	v_bfe_u32 v144, v142, 16, 1
	v_add3_u32 v143, v143, v145, s29
	v_add3_u32 v142, v142, v144, s29
	v_cvt_pk_bf16_f32 v145, v147, v149
	v_ashrrev_i32_e32 v137, 31, v136
	v_lshrrev_b32_e32 v142, 16, v142
	v_lshrrev_b32_e32 v143, 16, v143
	v_lshlrev_b64 v[136:137], 12, v[136:137]
	v_cvt_pk_bf16_f32 v144, v146, v148
	v_and_or_b32 v143, v150, s27, v143
	v_and_or_b32 v142, v151, s27, v142
	v_lshl_add_u64 v[136:137], v[118:119], 0, v[136:137]
	v_cmp_gt_i32_e32 vcc, s30, v139
	global_store_dwordx4 v[136:137], v[142:145], off
	s_and_saveexec_b64 s[24:25], vcc
	s_cbranch_execz .LBB0_583
	v_add_u32_e32 v54, s3, v132
	v_min_i32_e32 v128, 0x4fff, v54
	v_cmp_gt_i32_e32 vcc, s26, v54
	v_cmp_lt_i32_e64 s[4:5], s1, v54
	s_and_saveexec_b64 s[6:7], s[4:5]
	s_xor_b64 s[4:5], exec, s[6:7]
	v_add_u32_e32 v54, 0xfffff000, v128
	v_mov_b32_e32 v55, v111
	v_lshlrev_b64 v[54:55], 11, v[54:55]
	v_lshl_add_u64 v[54:55], s[18:19], 0, v[54:55]
	v_mov_b32_e32 v129, v111
	s_or_saveexec_b64 s[4:5], s[4:5]
	v_mov_b32_e32 v56, 0xfff
	s_xor_b64 exec, exec, s[4:5]
	s_cbranch_execz .LBB0_582
	v_ashrrev_i32_e32 v129, 31, v128
	v_lshlrev_b64 v[54:55], 11, v[128:129]
	v_lshl_add_u64 v[54:55], s[16:17], 0, v[54:55]
	v_mov_b32_e32 v56, 0xff
	s_branch .LBB0_582

.LBB0_692:
	v_cvt_pk_bf16_f32 v134, v134, v135
	v_cvt_pk_bf16_f32 v135, v136, v137
	v_cvt_pk_bf16_f32 v136, v130, v131
	v_lshl_add_u64 v[172:173], v[170:171], 1, v[172:173]
	v_cvt_pk_bf16_f32 v137, v132, v133
	s_and_b64 vcc, exec, s[6:7]
	global_store_dwordx4 v[172:173], v[134:137], off
	s_cbranch_vccnz .LBB0_694
	global_store_dwordx4 v[174:175], v[118:121], off offset:512
	global_store_dwordx4 v[174:175], v[114:117], off offset:528

.LBB0_696:
	v_cvt_pk_bf16_f32 v134, v134, v135
	v_cvt_pk_bf16_f32 v135, v136, v137
	v_cvt_pk_bf16_f32 v136, v130, v131
	v_cvt_pk_bf16_f32 v137, v132, v133
	v_add_u32_e32 v130, 16, v168
	s_and_b64 vcc, exec, s[8:9]
	s_mov_b64 s[46:47], -1
	global_store_dwordx4 v[172:173], v[134:137], off offset:256
	s_cbranch_vccnz .LBB0_785
	v_ashrrev_i32_e32 v131, 31, v130
	v_lshlrev_b64 v[132:133], 12, v[130:131]
	v_lshl_add_u64 v[134:135], v[154:155], 0, v[132:133]
	v_lshl_add_u64 v[172:173], v[134:135], 0, s[40:41]
	s_cbranch_execz .LBB0_786

.LBB0_702:
	v_cvt_pk_bf16_f32 v134, v134, v135
	v_cvt_pk_bf16_f32 v135, v136, v137
	v_cvt_pk_bf16_f32 v136, v130, v131
	v_lshl_add_u64 v[172:173], v[170:171], 1, v[172:173]
	v_cvt_pk_bf16_f32 v137, v132, v133
	s_and_b64 vcc, exec, s[6:7]
	global_store_dwordx4 v[172:173], v[134:137], off
	s_cbranch_vccnz .LBB0_704
	global_store_dwordx4 v[174:175], v[102:105], off offset:512
	global_store_dwordx4 v[174:175], v[98:101], off offset:528

.LBB0_706:
	v_cvt_pk_bf16_f32 v134, v134, v135
	v_cvt_pk_bf16_f32 v135, v136, v137
	v_cvt_pk_bf16_f32 v136, v130, v131
	v_cvt_pk_bf16_f32 v137, v132, v133
	v_add_u32_e32 v130, 32, v168
	s_and_b64 vcc, exec, s[8:9]
	s_mov_b64 s[46:47], -1
	global_store_dwordx4 v[172:173], v[134:137], off offset:256
	s_cbranch_vccnz .LBB0_791
	v_ashrrev_i32_e32 v131, 31, v130
	v_lshlrev_b64 v[132:133], 12, v[130:131]
	v_lshl_add_u64 v[134:135], v[154:155], 0, v[132:133]
	v_lshl_add_u64 v[172:173], v[134:135], 0, s[40:41]
	s_cbranch_execz .LBB0_792

.LBB0_712:
	v_cvt_pk_bf16_f32 v134, v134, v135
	v_cvt_pk_bf16_f32 v135, v136, v137
	v_cvt_pk_bf16_f32 v136, v130, v131
	v_lshl_add_u64 v[172:173], v[170:171], 1, v[172:173]
	v_cvt_pk_bf16_f32 v137, v132, v133
	s_and_b64 vcc, exec, s[6:7]
	global_store_dwordx4 v[172:173], v[134:137], off
	s_cbranch_vccnz .LBB0_714
	global_store_dwordx4 v[174:175], v[86:89], off offset:512
	global_store_dwordx4 v[174:175], v[82:85], off offset:528

.LBB0_716:
	v_cvt_pk_bf16_f32 v134, v134, v135
	v_cvt_pk_bf16_f32 v135, v136, v137
	v_cvt_pk_bf16_f32 v136, v130, v131
	v_cvt_pk_bf16_f32 v137, v132, v133
	v_add_u32_e32 v130, 48, v168
	s_and_b64 vcc, exec, s[8:9]
	s_mov_b64 s[46:47], -1
	global_store_dwordx4 v[172:173], v[134:137], off offset:256
	s_cbranch_vccnz .LBB0_797
	v_ashrrev_i32_e32 v131, 31, v130
	v_lshlrev_b64 v[132:133], 12, v[130:131]
	v_lshl_add_u64 v[134:135], v[154:155], 0, v[132:133]
	v_lshl_add_u64 v[172:173], v[134:135], 0, s[40:41]
	s_cbranch_execz .LBB0_798

.LBB0_722:
	v_cvt_pk_bf16_f32 v134, v134, v135
	v_cvt_pk_bf16_f32 v135, v136, v137
	v_cvt_pk_bf16_f32 v136, v130, v131
	v_lshl_add_u64 v[172:173], v[170:171], 1, v[172:173]
	v_cvt_pk_bf16_f32 v137, v132, v133
	s_and_b64 vcc, exec, s[6:7]
	global_store_dwordx4 v[172:173], v[134:137], off
	s_cbranch_vccnz .LBB0_724
	global_store_dwordx4 v[174:175], v[70:73], off offset:512
	global_store_dwordx4 v[174:175], v[66:69], off offset:528

.LBB0_726:
	v_cvt_pk_bf16_f32 v134, v134, v135
	v_cvt_pk_bf16_f32 v135, v136, v137
	v_cvt_pk_bf16_f32 v136, v130, v131
	v_cvt_pk_bf16_f32 v137, v132, v133
	v_add_u32_e32 v130, 0x80, v168
	s_and_b64 vcc, exec, s[8:9]
	s_mov_b64 s[46:47], -1
	global_store_dwordx4 v[172:173], v[134:137], off offset:256
	s_cbranch_vccnz .LBB0_803
	v_ashrrev_i32_e32 v131, 31, v130
	v_lshlrev_b64 v[132:133], 12, v[130:131]
	v_lshl_add_u64 v[134:135], v[154:155], 0, v[132:133]
	v_lshl_add_u64 v[172:173], v[134:135], 0, s[40:41]
	s_cbranch_execz .LBB0_804

.LBB0_732:
	v_cvt_pk_bf16_f32 v134, v134, v135
	v_cvt_pk_bf16_f32 v135, v136, v137
	v_cvt_pk_bf16_f32 v136, v130, v131
	v_lshl_add_u64 v[172:173], v[170:171], 1, v[172:173]
	v_cvt_pk_bf16_f32 v137, v132, v133
	s_and_b64 vcc, exec, s[6:7]
	global_store_dwordx4 v[172:173], v[134:137], off
	s_cbranch_vccnz .LBB0_734
	global_store_dwordx4 v[174:175], v[54:57], off offset:512
	global_store_dwordx4 v[174:175], v[50:53], off offset:528

.LBB0_736:
	v_cvt_pk_bf16_f32 v134, v134, v135
	v_cvt_pk_bf16_f32 v135, v136, v137
	v_cvt_pk_bf16_f32 v136, v130, v131
	v_cvt_pk_bf16_f32 v137, v132, v133
	v_add_u32_e32 v130, 0x90, v168
	s_and_b64 vcc, exec, s[8:9]
	s_mov_b64 s[46:47], -1
	global_store_dwordx4 v[172:173], v[134:137], off offset:256
	s_cbranch_vccnz .LBB0_809
	v_ashrrev_i32_e32 v131, 31, v130
	v_lshlrev_b64 v[132:133], 12, v[130:131]
	v_lshl_add_u64 v[134:135], v[154:155], 0, v[132:133]
	v_lshl_add_u64 v[172:173], v[134:135], 0, s[40:41]
	s_cbranch_execz .LBB0_810

.LBB0_742:
	v_cvt_pk_bf16_f32 v134, v134, v135
	v_cvt_pk_bf16_f32 v135, v136, v137
	v_cvt_pk_bf16_f32 v136, v130, v131
	v_lshl_add_u64 v[172:173], v[170:171], 1, v[172:173]
	v_cvt_pk_bf16_f32 v137, v132, v133
	s_and_b64 vcc, exec, s[6:7]
	global_store_dwordx4 v[172:173], v[134:137], off
	s_cbranch_vccnz .LBB0_744
	global_store_dwordx4 v[174:175], v[38:41], off offset:512
	global_store_dwordx4 v[174:175], v[34:37], off offset:528

.LBB0_746:
	v_cvt_pk_bf16_f32 v134, v134, v135
	v_cvt_pk_bf16_f32 v135, v136, v137
	v_cvt_pk_bf16_f32 v136, v130, v131
	v_cvt_pk_bf16_f32 v137, v132, v133
	v_add_u32_e32 v130, 0xa0, v168
	s_and_b64 vcc, exec, s[8:9]
	s_mov_b64 s[46:47], -1
	global_store_dwordx4 v[172:173], v[134:137], off offset:256
	s_cbranch_vccnz .LBB0_815
	v_ashrrev_i32_e32 v131, 31, v130
	v_lshlrev_b64 v[132:133], 12, v[130:131]
	v_lshl_add_u64 v[134:135], v[154:155], 0, v[132:133]
	v_lshl_add_u64 v[172:173], v[134:135], 0, s[40:41]
	s_cbranch_execz .LBB0_816

.LBB0_752:
	v_cvt_pk_bf16_f32 v134, v134, v135
	v_cvt_pk_bf16_f32 v135, v136, v137
	v_cvt_pk_bf16_f32 v136, v130, v131
	v_lshl_add_u64 v[172:173], v[170:171], 1, v[172:173]
	v_cvt_pk_bf16_f32 v137, v132, v133
	s_and_b64 vcc, exec, s[6:7]
	global_store_dwordx4 v[172:173], v[134:137], off
	s_cbranch_vccnz .LBB0_754
	global_store_dwordx4 v[174:175], v[22:25], off offset:512
	global_store_dwordx4 v[174:175], v[18:21], off offset:528

.LBB0_756:
	v_cvt_pk_bf16_f32 v134, v134, v135
	v_cvt_pk_bf16_f32 v135, v136, v137
	v_cvt_pk_bf16_f32 v136, v130, v131
	v_cvt_pk_bf16_f32 v137, v132, v133
	v_add_u32_e32 v130, 0xb0, v168
	s_and_b64 vcc, exec, s[8:9]
	s_mov_b64 s[46:47], -1
	global_store_dwordx4 v[172:173], v[134:137], off offset:256
	s_cbranch_vccnz .LBB0_821
	v_ashrrev_i32_e32 v131, 31, v130
	v_lshlrev_b64 v[132:133], 12, v[130:131]
	v_lshl_add_u64 v[134:135], v[154:155], 0, v[132:133]
	v_lshl_add_u64 v[174:175], v[134:135], 0, s[40:41]
	s_cbranch_execz .LBB0_822

.LBB0_762:
	v_cvt_pk_bf16_f32 v134, v134, v135
	v_cvt_pk_bf16_f32 v135, v136, v137
	v_cvt_pk_bf16_f32 v136, v130, v131
	v_lshl_add_u64 v[170:171], v[170:171], 1, v[174:175]
	v_cvt_pk_bf16_f32 v137, v132, v133
	s_and_b64 vcc, exec, s[6:7]
	global_store_dwordx4 v[170:171], v[134:137], off
	s_cbranch_vccnz .LBB0_764
	global_store_dwordx4 v[172:173], v[6:9], off offset:512
	global_store_dwordx4 v[172:173], v[2:5], off offset:528

.LBB0_766:
	v_cvt_pk_bf16_f32 v134, v134, v135
	v_cvt_pk_bf16_f32 v135, v136, v137
	v_cvt_pk_bf16_f32 v136, v130, v131
	v_cvt_pk_bf16_f32 v137, v132, v133
	global_store_dwordx4 v[170:171], v[134:137], off offset:256

.LBB0_781:
	v_and_b32_e32 v1, 1, v1
	v_add_u32_e32 v134, 12, v132
	v_cmp_eq_u32_e32 vcc, 0, v1
	v_pk_mul_f32 v[126:127], v[126:127], s[12:13] op_sel_hi:[1,0]
	v_lshlrev_b64 v[136:137], 11, v[136:137]
	v_cndmask_b32_e32 v1, v134, v132, vcc
	v_add_u32_e32 v134, v1, v130
	v_lshl_add_u64 v[136:137], v[170:171], 0, v[136:137]
	v_pk_mul_f32 v[170:171], v[124:125], s[12:13] op_sel_hi:[1,0]
	v_pk_mul_f32 v[124:125], v[122:123], s[12:13] op_sel_hi:[1,0]
	v_cvt_pk_bf16_f32 v122, v126, v127
	v_pk_mul_f32 v[128:129], v[128:129], s[12:13] op_sel_hi:[1,0]
	v_cvt_pk_bf16_f32 v124, v124, v125
	v_cvt_pk_bf16_f32 v123, v128, v129
	v_ashrrev_i32_e32 v135, 31, v134
	v_cvt_pk_bf16_f32 v125, v170, v171
	v_lshl_add_u64 v[136:137], v[134:135], 1, v[136:137]
	v_permlane16_swap_b32_e32 v122, v124
	v_permlane16_swap_b32_e32 v123, v125
	v_pk_mul_f32 v[118:119], v[118:119], s[12:13] op_sel_hi:[1,0]
	global_store_dwordx4 v[136:137], v[122:125], off
	v_bfe_u32 v1, v118, 16, 1
	v_add3_u32 v1, v118, v1, s61
	v_pk_mul_f32 v[122:123], v[116:117], s[12:13] op_sel_hi:[1,0]
	v_pk_mul_f32 v[116:117], v[114:115], s[12:13] op_sel_hi:[1,0]
	v_bfe_u32 v114, v119, 16, 1
	v_mov_b32_e32 v124, v107
	v_mov_b32_e32 v125, v111
	v_add3_u32 v114, v119, v114, s61
	v_mov_b32_e32 v118, v106
	v_mov_b32_e32 v119, v110
	v_pk_mul_f32 v[124:125], v[124:125], v[124:125]
	v_mov_b32_e32 v126, v99
	v_pk_fma_f32 v[118:119], v[118:119], v[118:119], v[124:125]
	v_mov_b32_e32 v124, v108
	v_mov_b32_e32 v125, v112
	v_pk_fma_f32 v[118:119], v[124:125], v[124:125], v[118:119]
	v_mov_b32_e32 v124, v109
	v_mov_b32_e32 v125, v113
	v_mov_b32_e32 v127, v103
	v_pk_fma_f32 v[118:119], v[124:125], v[124:125], v[118:119]
	v_mov_b32_e32 v124, v98
	v_mov_b32_e32 v125, v102
	v_pk_mul_f32 v[126:127], v[126:127], v[126:127]
	v_bfe_u32 v115, v117, 16, 1
	v_pk_fma_f32 v[124:125], v[124:125], v[124:125], v[126:127]
	v_mov_b32_e32 v126, v100
	v_mov_b32_e32 v127, v104
	v_pk_fma_f32 v[124:125], v[126:127], v[126:127], v[124:125]
	v_mov_b32_e32 v126, v101
	v_mov_b32_e32 v127, v105
	v_add3_u32 v115, v117, v115, s61
	v_pk_fma_f32 v[124:125], v[126:127], v[126:127], v[124:125]
	v_add_f32_e32 v117, v118, v119
	v_add_f32_e32 v117, v125, v117
	v_add_f32_e32 v117, v124, v117
	ds_bpermute_b32 v118, v173, v117
	v_lshrrev_b32_e32 v1, 16, v1
	v_and_or_b32 v114, v114, s62, v1
	v_bfe_u32 v1, v116, 16, 1
	v_add3_u32 v1, v116, v1, s61
	v_pk_mul_f32 v[120:121], v[120:121], s[12:13] op_sel_hi:[1,0]
	v_lshrrev_b32_e32 v1, 16, v1
	v_and_or_b32 v116, v115, s62, v1
	s_waitcnt lgkmcnt(0)
	v_add_f32_e32 v118, v117, v118
	ds_bpermute_b32 v119, v175, v118
	v_cvt_pk_bf16_f32 v115, v120, v121
	v_cvt_pk_bf16_f32 v117, v122, v123
	s_waitcnt lgkmcnt(0)
	v_add_f32_e32 v1, v118, v119
	v_fmamk_f32 v1, v1, 0x3c800000, v179
	v_mul_f32_e32 v118, 0x4b800000, v1
	v_cmp_gt_f32_e32 vcc, s71, v1
	v_permlane16_swap_b32_e32 v114, v116
	s_nop 0
	v_cndmask_b32_e32 v1, v1, v118, vcc
	v_rsq_f32_e32 v1, v1
	v_permlane16_swap_b32_e32 v115, v117
	global_store_dwordx4 v[136:137], v[114:117], off offset:64
	v_mul_f32_e32 v118, 0x45800000, v1
	ds_read_b128 v[114:117], v174
	v_cndmask_b32_e32 v122, v1, v118, vcc
	ds_read_b128 v[118:121], v174 offset:64
	v_pk_mul_f32 v[110:111], v[110:111], v[122:123] op_sel_hi:[1,0]
	v_pk_mul_f32 v[112:113], v[112:113], v[122:123] op_sel_hi:[1,0]
	v_pk_mul_f32 v[106:107], v[106:107], v[122:123] op_sel_hi:[1,0]
	v_pk_mul_f32 v[108:109], v[108:109], v[122:123] op_sel_hi:[1,0]
	s_waitcnt lgkmcnt(0)
	v_pk_mul_f32 v[112:113], v[116:117], v[112:113]
	v_pk_mul_f32 v[110:111], v[114:115], v[110:111]
	v_pk_mul_f32 v[108:109], v[120:121], v[108:109]
	ds_read_b128 v[114:117], v174 offset:128
	v_pk_mul_f32 v[106:107], v[118:119], v[106:107]
	ds_read_b128 v[118:121], v174 offset:192
	v_pk_mul_f32 v[102:103], v[102:103], v[122:123] op_sel_hi:[1,0]
	v_pk_mul_f32 v[104:105], v[104:105], v[122:123] op_sel_hi:[1,0]
	v_pk_mul_f32 v[98:99], v[98:99], v[122:123] op_sel_hi:[1,0]
	v_pk_mul_f32 v[100:101], v[100:101], v[122:123] op_sel_hi:[1,0]
	s_waitcnt lgkmcnt(0)
	v_pk_mul_f32 v[104:105], v[116:117], v[104:105]
	v_pk_mul_f32 v[102:103], v[114:115], v[102:103]
	v_pk_mul_f32 v[100:101], v[120:121], v[100:101]
	v_pk_mul_f32 v[98:99], v[118:119], v[98:99]
	s_and_b64 vcc, exec, s[6:7]
	v_add_u32_e32 v114, 16, v168
	s_cbranch_vccnz .LBB0_827
	v_ashrrev_i32_e32 v115, 31, v114
	v_lshlrev_b64 v[116:117], 12, v[114:115]
	v_lshl_add_u64 v[116:117], s[20:21], 0, v[116:117]
	v_lshl_add_u64 v[116:117], v[130:131], 2, v[116:117]
	v_lshl_add_u64 v[116:117], v[132:133], 2, v[116:117]
	global_store_dwordx4 v[116:117], v[110:113], off
	global_store_dwordx4 v[116:117], v[106:109], off offset:64
	global_store_dwordx4 v[116:117], v[102:105], off offset:128
	global_store_dwordx4 v[116:117], v[98:101], off offset:192
	s_and_b64 vcc, exec, s[8:9]
	s_cbranch_vccz .LBB0_828

.LBB0_835:
	v_pk_mul_f32 v[110:111], v[110:111], s[12:13] op_sel_hi:[1,0]
	v_lshlrev_b64 v[114:115], 11, v[114:115]
	v_lshl_add_u64 v[114:115], v[116:117], 0, v[114:115]
	v_pk_mul_f32 v[116:117], v[108:109], s[12:13] op_sel_hi:[1,0]
	v_pk_mul_f32 v[108:109], v[106:107], s[12:13] op_sel_hi:[1,0]
	v_cvt_pk_bf16_f32 v106, v110, v111
	v_pk_mul_f32 v[112:113], v[112:113], s[12:13] op_sel_hi:[1,0]
	v_cvt_pk_bf16_f32 v108, v108, v109
	v_cvt_pk_bf16_f32 v107, v112, v113
	v_cvt_pk_bf16_f32 v109, v116, v117
	v_lshl_add_u64 v[114:115], v[134:135], 1, v[114:115]
	v_permlane16_swap_b32_e32 v106, v108
	v_permlane16_swap_b32_e32 v107, v109
	v_pk_mul_f32 v[102:103], v[102:103], s[12:13] op_sel_hi:[1,0]
	global_store_dwordx4 v[114:115], v[106:109], off
	v_bfe_u32 v1, v102, 16, 1
	v_add3_u32 v1, v102, v1, s61
	v_pk_mul_f32 v[106:107], v[100:101], s[12:13] op_sel_hi:[1,0]
	v_pk_mul_f32 v[100:101], v[98:99], s[12:13] op_sel_hi:[1,0]
	v_bfe_u32 v98, v103, 16, 1
	v_mov_b32_e32 v108, v91
	v_mov_b32_e32 v109, v95
	v_add3_u32 v98, v103, v98, s61
	v_mov_b32_e32 v102, v90
	v_mov_b32_e32 v103, v94
	v_pk_mul_f32 v[108:109], v[108:109], v[108:109]
	v_mov_b32_e32 v110, v83
	v_pk_fma_f32 v[102:103], v[102:103], v[102:103], v[108:109]
	v_mov_b32_e32 v108, v92
	v_mov_b32_e32 v109, v96
	v_pk_fma_f32 v[102:103], v[108:109], v[108:109], v[102:103]
	v_mov_b32_e32 v108, v93
	v_mov_b32_e32 v109, v97
	v_mov_b32_e32 v111, v87
	v_pk_fma_f32 v[102:103], v[108:109], v[108:109], v[102:103]
	v_mov_b32_e32 v108, v82
	v_mov_b32_e32 v109, v86
	v_pk_mul_f32 v[110:111], v[110:111], v[110:111]
	v_bfe_u32 v99, v101, 16, 1
	v_pk_fma_f32 v[108:109], v[108:109], v[108:109], v[110:111]
	v_mov_b32_e32 v110, v84
	v_mov_b32_e32 v111, v88
	v_pk_fma_f32 v[108:109], v[110:111], v[110:111], v[108:109]
	v_mov_b32_e32 v110, v85
	v_mov_b32_e32 v111, v89
	v_add3_u32 v99, v101, v99, s61
	v_pk_fma_f32 v[108:109], v[110:111], v[110:111], v[108:109]
	v_add_f32_e32 v101, v102, v103
	v_add_f32_e32 v101, v109, v101
	v_add_f32_e32 v101, v108, v101
	ds_bpermute_b32 v102, v173, v101
	v_lshrrev_b32_e32 v1, 16, v1
	v_and_or_b32 v98, v98, s62, v1
	v_bfe_u32 v1, v100, 16, 1
	v_add3_u32 v1, v100, v1, s61
	v_pk_mul_f32 v[104:105], v[104:105], s[12:13] op_sel_hi:[1,0]
	v_lshrrev_b32_e32 v1, 16, v1
	v_and_or_b32 v100, v99, s62, v1
	s_waitcnt lgkmcnt(0)
	v_add_f32_e32 v102, v101, v102
	ds_bpermute_b32 v103, v175, v102
	v_cvt_pk_bf16_f32 v99, v104, v105
	v_cvt_pk_bf16_f32 v101, v106, v107
	s_waitcnt lgkmcnt(0)
	v_add_f32_e32 v1, v102, v103
	v_fmamk_f32 v1, v1, 0x3c800000, v179
	v_mul_f32_e32 v102, 0x4b800000, v1
	v_cmp_gt_f32_e32 vcc, s71, v1
	v_permlane16_swap_b32_e32 v98, v100
	s_nop 0
	v_cndmask_b32_e32 v1, v1, v102, vcc
	v_rsq_f32_e32 v1, v1
	v_permlane16_swap_b32_e32 v99, v101
	global_store_dwordx4 v[114:115], v[98:101], off offset:64
	v_mul_f32_e32 v102, 0x45800000, v1
	ds_read_b128 v[98:101], v174
	v_cndmask_b32_e32 v106, v1, v102, vcc
	ds_read_b128 v[102:105], v174 offset:64
	v_pk_mul_f32 v[94:95], v[94:95], v[106:107] op_sel_hi:[1,0]
	v_pk_mul_f32 v[96:97], v[96:97], v[106:107] op_sel_hi:[1,0]
	v_pk_mul_f32 v[90:91], v[90:91], v[106:107] op_sel_hi:[1,0]
	v_pk_mul_f32 v[92:93], v[92:93], v[106:107] op_sel_hi:[1,0]
	s_waitcnt lgkmcnt(0)
	v_pk_mul_f32 v[96:97], v[100:101], v[96:97]
	v_pk_mul_f32 v[94:95], v[98:99], v[94:95]
	v_pk_mul_f32 v[92:93], v[104:105], v[92:93]
	ds_read_b128 v[98:101], v174 offset:128
	v_pk_mul_f32 v[90:91], v[102:103], v[90:91]
	ds_read_b128 v[102:105], v174 offset:192
	v_pk_mul_f32 v[86:87], v[86:87], v[106:107] op_sel_hi:[1,0]
	v_pk_mul_f32 v[88:89], v[88:89], v[106:107] op_sel_hi:[1,0]
	v_pk_mul_f32 v[82:83], v[82:83], v[106:107] op_sel_hi:[1,0]
	v_pk_mul_f32 v[84:85], v[84:85], v[106:107] op_sel_hi:[1,0]
	s_waitcnt lgkmcnt(0)
	v_pk_mul_f32 v[88:89], v[100:101], v[88:89]
	v_pk_mul_f32 v[86:87], v[98:99], v[86:87]
	v_pk_mul_f32 v[84:85], v[104:105], v[84:85]
	v_pk_mul_f32 v[82:83], v[102:103], v[82:83]
	s_and_b64 vcc, exec, s[6:7]
	v_add_u32_e32 v98, 32, v168
	s_cbranch_vccnz .LBB0_839
	v_ashrrev_i32_e32 v99, 31, v98
	v_lshlrev_b64 v[100:101], 12, v[98:99]
	v_lshl_add_u64 v[100:101], s[20:21], 0, v[100:101]
	v_lshl_add_u64 v[100:101], v[130:131], 2, v[100:101]
	v_lshl_add_u64 v[100:101], v[132:133], 2, v[100:101]
	global_store_dwordx4 v[100:101], v[94:97], off
	global_store_dwordx4 v[100:101], v[90:93], off offset:64
	global_store_dwordx4 v[100:101], v[86:89], off offset:128
	global_store_dwordx4 v[100:101], v[82:85], off offset:192
	s_and_b64 vcc, exec, s[8:9]
	s_cbranch_vccz .LBB0_840

.LBB0_847:
	v_pk_mul_f32 v[94:95], v[94:95], s[12:13] op_sel_hi:[1,0]
	v_lshlrev_b64 v[98:99], 11, v[98:99]
	v_lshl_add_u64 v[98:99], v[100:101], 0, v[98:99]
	v_pk_mul_f32 v[100:101], v[92:93], s[12:13] op_sel_hi:[1,0]
	v_pk_mul_f32 v[92:93], v[90:91], s[12:13] op_sel_hi:[1,0]
	v_cvt_pk_bf16_f32 v90, v94, v95
	v_pk_mul_f32 v[96:97], v[96:97], s[12:13] op_sel_hi:[1,0]
	v_cvt_pk_bf16_f32 v92, v92, v93
	v_cvt_pk_bf16_f32 v91, v96, v97
	v_cvt_pk_bf16_f32 v93, v100, v101
	v_lshl_add_u64 v[98:99], v[134:135], 1, v[98:99]
	v_permlane16_swap_b32_e32 v90, v92
	v_permlane16_swap_b32_e32 v91, v93
	v_pk_mul_f32 v[86:87], v[86:87], s[12:13] op_sel_hi:[1,0]
	global_store_dwordx4 v[98:99], v[90:93], off
	v_bfe_u32 v1, v86, 16, 1
	v_add3_u32 v1, v86, v1, s61
	v_pk_mul_f32 v[90:91], v[84:85], s[12:13] op_sel_hi:[1,0]
	v_pk_mul_f32 v[84:85], v[82:83], s[12:13] op_sel_hi:[1,0]
	v_bfe_u32 v82, v87, 16, 1
	v_mov_b32_e32 v92, v75
	v_mov_b32_e32 v93, v79
	v_add3_u32 v82, v87, v82, s61
	v_mov_b32_e32 v86, v74
	v_mov_b32_e32 v87, v78
	v_pk_mul_f32 v[92:93], v[92:93], v[92:93]
	v_mov_b32_e32 v94, v67
	v_pk_fma_f32 v[86:87], v[86:87], v[86:87], v[92:93]
	v_mov_b32_e32 v92, v76
	v_mov_b32_e32 v93, v80
	v_pk_fma_f32 v[86:87], v[92:93], v[92:93], v[86:87]
	v_mov_b32_e32 v92, v77
	v_mov_b32_e32 v93, v81
	v_mov_b32_e32 v95, v71
	v_pk_fma_f32 v[86:87], v[92:93], v[92:93], v[86:87]
	v_mov_b32_e32 v92, v66
	v_mov_b32_e32 v93, v70
	v_pk_mul_f32 v[94:95], v[94:95], v[94:95]
	v_bfe_u32 v83, v85, 16, 1
	v_pk_fma_f32 v[92:93], v[92:93], v[92:93], v[94:95]
	v_mov_b32_e32 v94, v68
	v_mov_b32_e32 v95, v72
	v_pk_fma_f32 v[92:93], v[94:95], v[94:95], v[92:93]
	v_mov_b32_e32 v94, v69
	v_mov_b32_e32 v95, v73
	v_add3_u32 v83, v85, v83, s61
	v_pk_fma_f32 v[92:93], v[94:95], v[94:95], v[92:93]
	v_add_f32_e32 v85, v86, v87
	v_add_f32_e32 v85, v93, v85
	v_add_f32_e32 v85, v92, v85
	ds_bpermute_b32 v86, v173, v85
	v_lshrrev_b32_e32 v1, 16, v1
	v_and_or_b32 v82, v82, s62, v1
	v_bfe_u32 v1, v84, 16, 1
	v_add3_u32 v1, v84, v1, s61
	v_pk_mul_f32 v[88:89], v[88:89], s[12:13] op_sel_hi:[1,0]
	v_lshrrev_b32_e32 v1, 16, v1
	v_and_or_b32 v84, v83, s62, v1
	s_waitcnt lgkmcnt(0)
	v_add_f32_e32 v86, v85, v86
	ds_bpermute_b32 v87, v175, v86
	v_cvt_pk_bf16_f32 v83, v88, v89
	v_cvt_pk_bf16_f32 v85, v90, v91
	s_waitcnt lgkmcnt(0)
	v_add_f32_e32 v1, v86, v87
	v_fmamk_f32 v1, v1, 0x3c800000, v179
	v_mul_f32_e32 v86, 0x4b800000, v1
	v_cmp_gt_f32_e32 vcc, s71, v1
	v_permlane16_swap_b32_e32 v82, v84
	s_nop 0
	v_cndmask_b32_e32 v1, v1, v86, vcc
	v_rsq_f32_e32 v1, v1
	v_permlane16_swap_b32_e32 v83, v85
	global_store_dwordx4 v[98:99], v[82:85], off offset:64
	v_mul_f32_e32 v86, 0x45800000, v1
	ds_read_b128 v[82:85], v174
	v_cndmask_b32_e32 v90, v1, v86, vcc
	ds_read_b128 v[86:89], v174 offset:64
	v_pk_mul_f32 v[78:79], v[78:79], v[90:91] op_sel_hi:[1,0]
	v_pk_mul_f32 v[80:81], v[80:81], v[90:91] op_sel_hi:[1,0]
	v_pk_mul_f32 v[74:75], v[74:75], v[90:91] op_sel_hi:[1,0]
	v_pk_mul_f32 v[76:77], v[76:77], v[90:91] op_sel_hi:[1,0]
	s_waitcnt lgkmcnt(0)
	v_pk_mul_f32 v[80:81], v[84:85], v[80:81]
	v_pk_mul_f32 v[78:79], v[82:83], v[78:79]
	v_pk_mul_f32 v[76:77], v[88:89], v[76:77]
	ds_read_b128 v[82:85], v174 offset:128
	v_pk_mul_f32 v[74:75], v[86:87], v[74:75]
	ds_read_b128 v[86:89], v174 offset:192
	v_pk_mul_f32 v[70:71], v[70:71], v[90:91] op_sel_hi:[1,0]
	v_pk_mul_f32 v[72:73], v[72:73], v[90:91] op_sel_hi:[1,0]
	v_pk_mul_f32 v[66:67], v[66:67], v[90:91] op_sel_hi:[1,0]
	v_pk_mul_f32 v[68:69], v[68:69], v[90:91] op_sel_hi:[1,0]
	s_waitcnt lgkmcnt(0)
	v_pk_mul_f32 v[72:73], v[84:85], v[72:73]
	v_pk_mul_f32 v[70:71], v[82:83], v[70:71]
	v_pk_mul_f32 v[68:69], v[88:89], v[68:69]
	v_pk_mul_f32 v[66:67], v[86:87], v[66:67]
	s_and_b64 vcc, exec, s[6:7]
	v_add_u32_e32 v82, 48, v168
	s_cbranch_vccnz .LBB0_851
	v_ashrrev_i32_e32 v83, 31, v82
	v_lshlrev_b64 v[84:85], 12, v[82:83]
	v_lshl_add_u64 v[84:85], s[20:21], 0, v[84:85]
	v_lshl_add_u64 v[84:85], v[130:131], 2, v[84:85]
	v_lshl_add_u64 v[84:85], v[132:133], 2, v[84:85]
	global_store_dwordx4 v[84:85], v[78:81], off
	global_store_dwordx4 v[84:85], v[74:77], off offset:64
	global_store_dwordx4 v[84:85], v[70:73], off offset:128
	global_store_dwordx4 v[84:85], v[66:69], off offset:192
	s_and_b64 vcc, exec, s[8:9]
	s_cbranch_vccz .LBB0_852

.LBB0_859:
	v_pk_mul_f32 v[78:79], v[78:79], s[12:13] op_sel_hi:[1,0]
	v_lshlrev_b64 v[82:83], 11, v[82:83]
	v_lshl_add_u64 v[82:83], v[84:85], 0, v[82:83]
	v_pk_mul_f32 v[84:85], v[76:77], s[12:13] op_sel_hi:[1,0]
	v_pk_mul_f32 v[76:77], v[74:75], s[12:13] op_sel_hi:[1,0]
	v_cvt_pk_bf16_f32 v74, v78, v79
	v_pk_mul_f32 v[80:81], v[80:81], s[12:13] op_sel_hi:[1,0]
	v_cvt_pk_bf16_f32 v76, v76, v77
	v_cvt_pk_bf16_f32 v75, v80, v81
	v_cvt_pk_bf16_f32 v77, v84, v85
	v_lshl_add_u64 v[82:83], v[134:135], 1, v[82:83]
	v_permlane16_swap_b32_e32 v74, v76
	v_permlane16_swap_b32_e32 v75, v77
	v_pk_mul_f32 v[70:71], v[70:71], s[12:13] op_sel_hi:[1,0]
	global_store_dwordx4 v[82:83], v[74:77], off
	v_bfe_u32 v1, v70, 16, 1
	v_add3_u32 v1, v70, v1, s61
	v_pk_mul_f32 v[74:75], v[68:69], s[12:13] op_sel_hi:[1,0]
	v_pk_mul_f32 v[68:69], v[66:67], s[12:13] op_sel_hi:[1,0]
	v_bfe_u32 v66, v71, 16, 1
	v_mov_b32_e32 v76, v59
	v_mov_b32_e32 v77, v63
	v_add3_u32 v66, v71, v66, s61
	v_mov_b32_e32 v70, v58
	v_mov_b32_e32 v71, v62
	v_pk_mul_f32 v[76:77], v[76:77], v[76:77]
	v_mov_b32_e32 v78, v51
	v_pk_fma_f32 v[70:71], v[70:71], v[70:71], v[76:77]
	v_mov_b32_e32 v76, v60
	v_mov_b32_e32 v77, v64
	v_pk_fma_f32 v[70:71], v[76:77], v[76:77], v[70:71]
	v_mov_b32_e32 v76, v61
	v_mov_b32_e32 v77, v65
	v_mov_b32_e32 v79, v55
	v_pk_fma_f32 v[70:71], v[76:77], v[76:77], v[70:71]
	v_mov_b32_e32 v76, v50
	v_mov_b32_e32 v77, v54
	v_pk_mul_f32 v[78:79], v[78:79], v[78:79]
	v_bfe_u32 v67, v69, 16, 1
	v_pk_fma_f32 v[76:77], v[76:77], v[76:77], v[78:79]
	v_mov_b32_e32 v78, v52
	v_mov_b32_e32 v79, v56
	v_pk_fma_f32 v[76:77], v[78:79], v[78:79], v[76:77]
	v_mov_b32_e32 v78, v53
	v_mov_b32_e32 v79, v57
	v_add3_u32 v67, v69, v67, s61
	v_pk_fma_f32 v[76:77], v[78:79], v[78:79], v[76:77]
	v_add_f32_e32 v69, v70, v71
	v_add_f32_e32 v69, v77, v69
	v_add_f32_e32 v69, v76, v69
	ds_bpermute_b32 v70, v173, v69
	v_lshrrev_b32_e32 v1, 16, v1
	v_and_or_b32 v66, v66, s62, v1
	v_bfe_u32 v1, v68, 16, 1
	v_add3_u32 v1, v68, v1, s61
	v_pk_mul_f32 v[72:73], v[72:73], s[12:13] op_sel_hi:[1,0]
	v_lshrrev_b32_e32 v1, 16, v1
	v_and_or_b32 v68, v67, s62, v1
	s_waitcnt lgkmcnt(0)
	v_add_f32_e32 v70, v69, v70
	ds_bpermute_b32 v71, v175, v70
	v_cvt_pk_bf16_f32 v67, v72, v73
	v_cvt_pk_bf16_f32 v69, v74, v75
	s_waitcnt lgkmcnt(0)
	v_add_f32_e32 v1, v70, v71
	v_fmamk_f32 v1, v1, 0x3c800000, v179
	v_mul_f32_e32 v70, 0x4b800000, v1
	v_cmp_gt_f32_e32 vcc, s71, v1
	v_permlane16_swap_b32_e32 v66, v68
	s_nop 0
	v_cndmask_b32_e32 v1, v1, v70, vcc
	v_rsq_f32_e32 v1, v1
	v_permlane16_swap_b32_e32 v67, v69
	global_store_dwordx4 v[82:83], v[66:69], off offset:64
	ds_read_b128 v[68:71], v174
	ds_read_b128 v[72:75], v174 offset:64
	v_mul_f32_e32 v67, 0x45800000, v1
	v_cndmask_b32_e32 v76, v1, v67, vcc
	v_pk_mul_f32 v[62:63], v[62:63], v[76:77] op_sel_hi:[1,0]
	v_pk_mul_f32 v[64:65], v[64:65], v[76:77] op_sel_hi:[1,0]
	v_pk_mul_f32 v[58:59], v[58:59], v[76:77] op_sel_hi:[1,0]
	v_pk_mul_f32 v[60:61], v[60:61], v[76:77] op_sel_hi:[1,0]
	s_waitcnt lgkmcnt(0)
	v_pk_mul_f32 v[64:65], v[70:71], v[64:65]
	v_pk_mul_f32 v[62:63], v[68:69], v[62:63]
	v_pk_mul_f32 v[60:61], v[74:75], v[60:61]
	ds_read_b128 v[68:71], v174 offset:128
	v_pk_mul_f32 v[58:59], v[72:73], v[58:59]
	ds_read_b128 v[72:75], v174 offset:192
	v_pk_mul_f32 v[54:55], v[54:55], v[76:77] op_sel_hi:[1,0]
	v_pk_mul_f32 v[56:57], v[56:57], v[76:77] op_sel_hi:[1,0]
	v_pk_mul_f32 v[50:51], v[50:51], v[76:77] op_sel_hi:[1,0]
	v_pk_mul_f32 v[52:53], v[52:53], v[76:77] op_sel_hi:[1,0]
	v_add_u32_e32 v66, 0x80, v168
	s_waitcnt lgkmcnt(0)
	v_pk_mul_f32 v[56:57], v[70:71], v[56:57]
	v_pk_mul_f32 v[54:55], v[68:69], v[54:55]
	v_pk_mul_f32 v[52:53], v[74:75], v[52:53]
	s_and_b64 vcc, exec, s[6:7]
	v_pk_mul_f32 v[50:51], v[72:73], v[50:51]
	s_cbranch_vccnz .LBB0_863
	v_ashrrev_i32_e32 v67, 31, v66
	v_lshlrev_b64 v[68:69], 12, v[66:67]
	v_lshl_add_u64 v[68:69], s[20:21], 0, v[68:69]
	v_lshl_add_u64 v[68:69], v[130:131], 2, v[68:69]
	v_lshl_add_u64 v[68:69], v[132:133], 2, v[68:69]
	global_store_dwordx4 v[68:69], v[62:65], off
	global_store_dwordx4 v[68:69], v[58:61], off offset:64
	global_store_dwordx4 v[68:69], v[54:57], off offset:128
	global_store_dwordx4 v[68:69], v[50:53], off offset:192
	s_and_b64 vcc, exec, s[8:9]
	s_cbranch_vccz .LBB0_864

.LBB0_871:
	v_pk_mul_f32 v[62:63], v[62:63], s[12:13] op_sel_hi:[1,0]
	v_lshlrev_b64 v[66:67], 11, v[66:67]
	v_lshl_add_u64 v[66:67], v[68:69], 0, v[66:67]
	v_pk_mul_f32 v[68:69], v[60:61], s[12:13] op_sel_hi:[1,0]
	v_pk_mul_f32 v[60:61], v[58:59], s[12:13] op_sel_hi:[1,0]
	v_cvt_pk_bf16_f32 v58, v62, v63
	v_pk_mul_f32 v[64:65], v[64:65], s[12:13] op_sel_hi:[1,0]
	v_cvt_pk_bf16_f32 v60, v60, v61
	v_cvt_pk_bf16_f32 v59, v64, v65
	v_cvt_pk_bf16_f32 v61, v68, v69
	v_lshl_add_u64 v[66:67], v[134:135], 1, v[66:67]
	v_permlane16_swap_b32_e32 v58, v60
	v_permlane16_swap_b32_e32 v59, v61
	v_pk_mul_f32 v[54:55], v[54:55], s[12:13] op_sel_hi:[1,0]
	global_store_dwordx4 v[66:67], v[58:61], off
	v_bfe_u32 v1, v54, 16, 1
	v_add3_u32 v1, v54, v1, s61
	v_pk_mul_f32 v[58:59], v[52:53], s[12:13] op_sel_hi:[1,0]
	v_pk_mul_f32 v[52:53], v[50:51], s[12:13] op_sel_hi:[1,0]
	v_bfe_u32 v50, v55, 16, 1
	v_mov_b32_e32 v60, v43
	v_mov_b32_e32 v61, v47
	v_add3_u32 v50, v55, v50, s61
	v_mov_b32_e32 v54, v42
	v_mov_b32_e32 v55, v46
	v_pk_mul_f32 v[60:61], v[60:61], v[60:61]
	v_mov_b32_e32 v62, v35
	v_pk_fma_f32 v[54:55], v[54:55], v[54:55], v[60:61]
	v_mov_b32_e32 v60, v44
	v_mov_b32_e32 v61, v48
	v_pk_fma_f32 v[54:55], v[60:61], v[60:61], v[54:55]
	v_mov_b32_e32 v60, v45
	v_mov_b32_e32 v61, v49
	v_mov_b32_e32 v63, v39
	v_pk_fma_f32 v[54:55], v[60:61], v[60:61], v[54:55]
	v_mov_b32_e32 v60, v34
	v_mov_b32_e32 v61, v38
	v_pk_mul_f32 v[62:63], v[62:63], v[62:63]
	v_bfe_u32 v51, v53, 16, 1
	v_pk_fma_f32 v[60:61], v[60:61], v[60:61], v[62:63]
	v_mov_b32_e32 v62, v36
	v_mov_b32_e32 v63, v40
	v_pk_fma_f32 v[60:61], v[62:63], v[62:63], v[60:61]
	v_mov_b32_e32 v62, v37
	v_mov_b32_e32 v63, v41
	v_add3_u32 v51, v53, v51, s61
	v_pk_fma_f32 v[60:61], v[62:63], v[62:63], v[60:61]
	v_add_f32_e32 v53, v54, v55
	v_add_f32_e32 v53, v61, v53
	v_add_f32_e32 v53, v60, v53
	ds_bpermute_b32 v54, v173, v53
	v_lshrrev_b32_e32 v1, 16, v1
	v_and_or_b32 v50, v50, s62, v1
	v_bfe_u32 v1, v52, 16, 1
	v_add3_u32 v1, v52, v1, s61
	v_pk_mul_f32 v[56:57], v[56:57], s[12:13] op_sel_hi:[1,0]
	v_lshrrev_b32_e32 v1, 16, v1
	v_and_or_b32 v52, v51, s62, v1
	s_waitcnt lgkmcnt(0)
	v_add_f32_e32 v54, v53, v54
	ds_bpermute_b32 v55, v175, v54
	v_cvt_pk_bf16_f32 v51, v56, v57
	v_cvt_pk_bf16_f32 v53, v58, v59
	s_waitcnt lgkmcnt(0)
	v_add_f32_e32 v1, v54, v55
	v_fmamk_f32 v1, v1, 0x3c800000, v179
	v_mul_f32_e32 v54, 0x4b800000, v1
	v_cmp_gt_f32_e32 vcc, s71, v1
	v_permlane16_swap_b32_e32 v50, v52
	s_nop 0
	v_cndmask_b32_e32 v1, v1, v54, vcc
	v_rsq_f32_e32 v1, v1
	v_permlane16_swap_b32_e32 v51, v53
	global_store_dwordx4 v[66:67], v[50:53], off offset:64
	v_mul_f32_e32 v54, 0x45800000, v1
	ds_read_b128 v[50:53], v174
	v_cndmask_b32_e32 v58, v1, v54, vcc
	ds_read_b128 v[54:57], v174 offset:64
	v_pk_mul_f32 v[46:47], v[46:47], v[58:59] op_sel_hi:[1,0]
	v_pk_mul_f32 v[48:49], v[48:49], v[58:59] op_sel_hi:[1,0]
	v_pk_mul_f32 v[42:43], v[42:43], v[58:59] op_sel_hi:[1,0]
	v_pk_mul_f32 v[44:45], v[44:45], v[58:59] op_sel_hi:[1,0]
	s_waitcnt lgkmcnt(0)
	v_pk_mul_f32 v[48:49], v[52:53], v[48:49]
	v_pk_mul_f32 v[46:47], v[50:51], v[46:47]
	v_pk_mul_f32 v[44:45], v[56:57], v[44:45]
	ds_read_b128 v[50:53], v174 offset:128
	v_pk_mul_f32 v[42:43], v[54:55], v[42:43]
	ds_read_b128 v[54:57], v174 offset:192
	v_pk_mul_f32 v[38:39], v[38:39], v[58:59] op_sel_hi:[1,0]
	v_pk_mul_f32 v[40:41], v[40:41], v[58:59] op_sel_hi:[1,0]
	v_pk_mul_f32 v[34:35], v[34:35], v[58:59] op_sel_hi:[1,0]
	v_pk_mul_f32 v[36:37], v[36:37], v[58:59] op_sel_hi:[1,0]
	s_waitcnt lgkmcnt(0)
	v_pk_mul_f32 v[40:41], v[52:53], v[40:41]
	v_pk_mul_f32 v[38:39], v[50:51], v[38:39]
	v_pk_mul_f32 v[36:37], v[56:57], v[36:37]
	v_pk_mul_f32 v[34:35], v[54:55], v[34:35]
	s_and_b64 vcc, exec, s[6:7]
	v_add_u32_e32 v50, 0x90, v168
	s_cbranch_vccnz .LBB0_875
	v_ashrrev_i32_e32 v51, 31, v50
	v_lshlrev_b64 v[52:53], 12, v[50:51]
	v_lshl_add_u64 v[52:53], s[20:21], 0, v[52:53]
	v_lshl_add_u64 v[52:53], v[130:131], 2, v[52:53]
	v_lshl_add_u64 v[52:53], v[132:133], 2, v[52:53]
	global_store_dwordx4 v[52:53], v[46:49], off
	global_store_dwordx4 v[52:53], v[42:45], off offset:64
	global_store_dwordx4 v[52:53], v[38:41], off offset:128
	global_store_dwordx4 v[52:53], v[34:37], off offset:192
	s_and_b64 vcc, exec, s[8:9]
	s_cbranch_vccz .LBB0_876

.LBB0_883:
	v_pk_mul_f32 v[46:47], v[46:47], s[12:13] op_sel_hi:[1,0]
	v_lshlrev_b64 v[50:51], 11, v[50:51]
	v_lshl_add_u64 v[50:51], v[52:53], 0, v[50:51]
	v_pk_mul_f32 v[52:53], v[44:45], s[12:13] op_sel_hi:[1,0]
	v_pk_mul_f32 v[44:45], v[42:43], s[12:13] op_sel_hi:[1,0]
	v_cvt_pk_bf16_f32 v42, v46, v47
	v_pk_mul_f32 v[48:49], v[48:49], s[12:13] op_sel_hi:[1,0]
	v_cvt_pk_bf16_f32 v44, v44, v45
	v_cvt_pk_bf16_f32 v43, v48, v49
	v_cvt_pk_bf16_f32 v45, v52, v53
	v_lshl_add_u64 v[50:51], v[134:135], 1, v[50:51]
	v_permlane16_swap_b32_e32 v42, v44
	v_permlane16_swap_b32_e32 v43, v45
	v_pk_mul_f32 v[38:39], v[38:39], s[12:13] op_sel_hi:[1,0]
	global_store_dwordx4 v[50:51], v[42:45], off
	v_bfe_u32 v1, v38, 16, 1
	v_add3_u32 v1, v38, v1, s61
	v_pk_mul_f32 v[42:43], v[36:37], s[12:13] op_sel_hi:[1,0]
	v_pk_mul_f32 v[36:37], v[34:35], s[12:13] op_sel_hi:[1,0]
	v_bfe_u32 v34, v39, 16, 1
	v_mov_b32_e32 v44, v27
	v_mov_b32_e32 v45, v31
	v_add3_u32 v34, v39, v34, s61
	v_mov_b32_e32 v38, v26
	v_mov_b32_e32 v39, v30
	v_pk_mul_f32 v[44:45], v[44:45], v[44:45]
	v_mov_b32_e32 v46, v19
	v_pk_fma_f32 v[38:39], v[38:39], v[38:39], v[44:45]
	v_mov_b32_e32 v44, v28
	v_mov_b32_e32 v45, v32
	v_pk_fma_f32 v[38:39], v[44:45], v[44:45], v[38:39]
	v_mov_b32_e32 v44, v29
	v_mov_b32_e32 v45, v33
	v_mov_b32_e32 v47, v23
	v_pk_fma_f32 v[38:39], v[44:45], v[44:45], v[38:39]
	v_mov_b32_e32 v44, v18
	v_mov_b32_e32 v45, v22
	v_pk_mul_f32 v[46:47], v[46:47], v[46:47]
	v_bfe_u32 v35, v37, 16, 1
	v_pk_fma_f32 v[44:45], v[44:45], v[44:45], v[46:47]
	v_mov_b32_e32 v46, v20
	v_mov_b32_e32 v47, v24
	v_pk_fma_f32 v[44:45], v[46:47], v[46:47], v[44:45]
	v_mov_b32_e32 v46, v21
	v_mov_b32_e32 v47, v25
	v_add3_u32 v35, v37, v35, s61
	v_pk_fma_f32 v[44:45], v[46:47], v[46:47], v[44:45]
	v_add_f32_e32 v37, v38, v39
	v_add_f32_e32 v37, v45, v37
	v_add_f32_e32 v37, v44, v37
	ds_bpermute_b32 v38, v173, v37
	v_lshrrev_b32_e32 v1, 16, v1
	v_and_or_b32 v34, v34, s62, v1
	v_bfe_u32 v1, v36, 16, 1
	v_add3_u32 v1, v36, v1, s61
	v_pk_mul_f32 v[40:41], v[40:41], s[12:13] op_sel_hi:[1,0]
	v_lshrrev_b32_e32 v1, 16, v1
	v_and_or_b32 v36, v35, s62, v1
	s_waitcnt lgkmcnt(0)
	v_add_f32_e32 v38, v37, v38
	ds_bpermute_b32 v39, v175, v38
	v_cvt_pk_bf16_f32 v35, v40, v41
	v_cvt_pk_bf16_f32 v37, v42, v43
	s_waitcnt lgkmcnt(0)
	v_add_f32_e32 v1, v38, v39
	v_fmamk_f32 v1, v1, 0x3c800000, v179
	v_mul_f32_e32 v38, 0x4b800000, v1
	v_cmp_gt_f32_e32 vcc, s71, v1
	v_permlane16_swap_b32_e32 v34, v36
	s_nop 0
	v_cndmask_b32_e32 v1, v1, v38, vcc
	v_rsq_f32_e32 v1, v1
	v_permlane16_swap_b32_e32 v35, v37
	global_store_dwordx4 v[50:51], v[34:37], off offset:64
	v_mul_f32_e32 v38, 0x45800000, v1
	ds_read_b128 v[34:37], v174
	v_cndmask_b32_e32 v42, v1, v38, vcc
	ds_read_b128 v[38:41], v174 offset:64
	v_pk_mul_f32 v[30:31], v[30:31], v[42:43] op_sel_hi:[1,0]
	v_pk_mul_f32 v[32:33], v[32:33], v[42:43] op_sel_hi:[1,0]
	v_pk_mul_f32 v[26:27], v[26:27], v[42:43] op_sel_hi:[1,0]
	v_pk_mul_f32 v[28:29], v[28:29], v[42:43] op_sel_hi:[1,0]
	s_waitcnt lgkmcnt(0)
	v_pk_mul_f32 v[32:33], v[36:37], v[32:33]
	v_pk_mul_f32 v[30:31], v[34:35], v[30:31]
	v_pk_mul_f32 v[28:29], v[40:41], v[28:29]
	ds_read_b128 v[34:37], v174 offset:128
	v_pk_mul_f32 v[26:27], v[38:39], v[26:27]
	ds_read_b128 v[38:41], v174 offset:192
	v_pk_mul_f32 v[22:23], v[22:23], v[42:43] op_sel_hi:[1,0]
	v_pk_mul_f32 v[24:25], v[24:25], v[42:43] op_sel_hi:[1,0]
	v_pk_mul_f32 v[18:19], v[18:19], v[42:43] op_sel_hi:[1,0]
	v_pk_mul_f32 v[20:21], v[20:21], v[42:43] op_sel_hi:[1,0]
	s_waitcnt lgkmcnt(0)
	v_pk_mul_f32 v[24:25], v[36:37], v[24:25]
	v_pk_mul_f32 v[22:23], v[34:35], v[22:23]
	v_pk_mul_f32 v[20:21], v[40:41], v[20:21]
	v_pk_mul_f32 v[18:19], v[38:39], v[18:19]
	s_and_b64 vcc, exec, s[6:7]
	v_add_u32_e32 v34, 0xa0, v168
	s_cbranch_vccnz .LBB0_887
	v_ashrrev_i32_e32 v35, 31, v34
	v_lshlrev_b64 v[36:37], 12, v[34:35]
	v_lshl_add_u64 v[36:37], s[20:21], 0, v[36:37]
	v_lshl_add_u64 v[36:37], v[130:131], 2, v[36:37]
	v_lshl_add_u64 v[36:37], v[132:133], 2, v[36:37]
	global_store_dwordx4 v[36:37], v[30:33], off
	global_store_dwordx4 v[36:37], v[26:29], off offset:64
	global_store_dwordx4 v[36:37], v[22:25], off offset:128
	global_store_dwordx4 v[36:37], v[18:21], off offset:192
	s_and_b64 vcc, exec, s[8:9]
	s_cbranch_vccz .LBB0_888

.LBB0_895:
	v_pk_mul_f32 v[30:31], v[30:31], s[12:13] op_sel_hi:[1,0]
	v_lshlrev_b64 v[34:35], 11, v[34:35]
	v_lshl_add_u64 v[34:35], v[36:37], 0, v[34:35]
	v_pk_mul_f32 v[36:37], v[28:29], s[12:13] op_sel_hi:[1,0]
	v_pk_mul_f32 v[28:29], v[26:27], s[12:13] op_sel_hi:[1,0]
	v_cvt_pk_bf16_f32 v26, v30, v31
	v_pk_mul_f32 v[32:33], v[32:33], s[12:13] op_sel_hi:[1,0]
	v_cvt_pk_bf16_f32 v28, v28, v29
	v_cvt_pk_bf16_f32 v27, v32, v33
	v_cvt_pk_bf16_f32 v29, v36, v37
	v_lshl_add_u64 v[34:35], v[134:135], 1, v[34:35]
	v_permlane16_swap_b32_e32 v26, v28
	v_permlane16_swap_b32_e32 v27, v29
	v_pk_mul_f32 v[22:23], v[22:23], s[12:13] op_sel_hi:[1,0]
	global_store_dwordx4 v[34:35], v[26:29], off
	v_bfe_u32 v1, v22, 16, 1
	v_add3_u32 v1, v22, v1, s61
	v_pk_mul_f32 v[26:27], v[20:21], s[12:13] op_sel_hi:[1,0]
	v_pk_mul_f32 v[20:21], v[18:19], s[12:13] op_sel_hi:[1,0]
	v_bfe_u32 v18, v23, 16, 1
	v_mov_b32_e32 v28, v11
	v_mov_b32_e32 v29, v15
	v_add3_u32 v18, v23, v18, s61
	v_mov_b32_e32 v22, v10
	v_mov_b32_e32 v23, v14
	v_pk_mul_f32 v[28:29], v[28:29], v[28:29]
	v_mov_b32_e32 v30, v3
	v_pk_fma_f32 v[22:23], v[22:23], v[22:23], v[28:29]
	v_mov_b32_e32 v28, v12
	v_mov_b32_e32 v29, v16
	v_pk_fma_f32 v[22:23], v[28:29], v[28:29], v[22:23]
	v_mov_b32_e32 v28, v13
	v_mov_b32_e32 v29, v17
	v_mov_b32_e32 v31, v7
	v_pk_fma_f32 v[22:23], v[28:29], v[28:29], v[22:23]
	v_mov_b32_e32 v28, v2
	v_mov_b32_e32 v29, v6
	v_pk_mul_f32 v[30:31], v[30:31], v[30:31]
	v_bfe_u32 v19, v21, 16, 1
	v_pk_fma_f32 v[28:29], v[28:29], v[28:29], v[30:31]
	v_mov_b32_e32 v30, v4
	v_mov_b32_e32 v31, v8
	v_pk_fma_f32 v[28:29], v[30:31], v[30:31], v[28:29]
	v_mov_b32_e32 v30, v5
	v_mov_b32_e32 v31, v9
	v_add3_u32 v19, v21, v19, s61
	v_pk_fma_f32 v[28:29], v[30:31], v[30:31], v[28:29]
	v_add_f32_e32 v21, v22, v23
	v_add_f32_e32 v21, v29, v21
	v_add_f32_e32 v21, v28, v21
	ds_bpermute_b32 v22, v173, v21
	v_lshrrev_b32_e32 v1, 16, v1
	v_and_or_b32 v18, v18, s62, v1
	v_bfe_u32 v1, v20, 16, 1
	v_add3_u32 v1, v20, v1, s61
	v_pk_mul_f32 v[24:25], v[24:25], s[12:13] op_sel_hi:[1,0]
	v_lshrrev_b32_e32 v1, 16, v1
	v_and_or_b32 v20, v19, s62, v1
	s_waitcnt lgkmcnt(0)
	v_add_f32_e32 v22, v21, v22
	ds_bpermute_b32 v23, v175, v22
	v_cvt_pk_bf16_f32 v19, v24, v25
	v_cvt_pk_bf16_f32 v21, v26, v27
	s_waitcnt lgkmcnt(0)
	v_add_f32_e32 v1, v22, v23
	v_fmamk_f32 v1, v1, 0x3c800000, v179
	v_mul_f32_e32 v22, 0x4b800000, v1
	v_cmp_gt_f32_e32 vcc, s71, v1
	v_permlane16_swap_b32_e32 v18, v20
	s_nop 0
	v_cndmask_b32_e32 v1, v1, v22, vcc
	v_rsq_f32_e32 v1, v1
	v_permlane16_swap_b32_e32 v19, v21
	global_store_dwordx4 v[34:35], v[18:21], off offset:64
	v_mul_f32_e32 v22, 0x45800000, v1
	ds_read_b128 v[18:21], v174
	v_cndmask_b32_e32 v26, v1, v22, vcc
	ds_read_b128 v[22:25], v174 offset:64
	v_pk_mul_f32 v[14:15], v[14:15], v[26:27] op_sel_hi:[1,0]
	v_pk_mul_f32 v[16:17], v[16:17], v[26:27] op_sel_hi:[1,0]
	v_pk_mul_f32 v[10:11], v[10:11], v[26:27] op_sel_hi:[1,0]
	v_pk_mul_f32 v[12:13], v[12:13], v[26:27] op_sel_hi:[1,0]
	s_waitcnt lgkmcnt(0)
	v_pk_mul_f32 v[16:17], v[20:21], v[16:17]
	v_pk_mul_f32 v[14:15], v[18:19], v[14:15]
	v_pk_mul_f32 v[12:13], v[24:25], v[12:13]
	ds_read_b128 v[18:21], v174 offset:128
	v_pk_mul_f32 v[10:11], v[22:23], v[10:11]
	ds_read_b128 v[22:25], v174 offset:192
	v_pk_mul_f32 v[6:7], v[6:7], v[26:27] op_sel_hi:[1,0]
	v_pk_mul_f32 v[8:9], v[8:9], v[26:27] op_sel_hi:[1,0]
	v_pk_mul_f32 v[2:3], v[2:3], v[26:27] op_sel_hi:[1,0]
	v_pk_mul_f32 v[4:5], v[4:5], v[26:27] op_sel_hi:[1,0]
	s_waitcnt lgkmcnt(0)
	v_pk_mul_f32 v[8:9], v[20:21], v[8:9]
	v_pk_mul_f32 v[6:7], v[18:19], v[6:7]
	v_pk_mul_f32 v[4:5], v[24:25], v[4:5]
	v_pk_mul_f32 v[2:3], v[22:23], v[2:3]
	s_and_b64 vcc, exec, s[6:7]
	v_add_u32_e32 v18, 0xb0, v168
	s_cbranch_vccnz .LBB0_899
	v_ashrrev_i32_e32 v19, 31, v18
	v_lshlrev_b64 v[20:21], 12, v[18:19]
	v_lshl_add_u64 v[20:21], s[20:21], 0, v[20:21]
	v_lshl_add_u64 v[20:21], v[130:131], 2, v[20:21]
	v_lshl_add_u64 v[20:21], v[132:133], 2, v[20:21]
	global_store_dwordx4 v[20:21], v[14:17], off
	global_store_dwordx4 v[20:21], v[10:13], off offset:64
	global_store_dwordx4 v[20:21], v[6:9], off offset:128
	global_store_dwordx4 v[20:21], v[2:5], off offset:192
	s_and_b64 vcc, exec, s[8:9]
	s_cbranch_vccz .LBB0_900

.LBB0_907:
	v_pk_mul_f32 v[14:15], v[14:15], s[6:7] op_sel_hi:[1,0]
	v_lshlrev_b64 v[18:19], 11, v[18:19]
	v_lshl_add_u64 v[18:19], v[20:21], 0, v[18:19]
	v_pk_mul_f32 v[20:21], v[12:13], s[6:7] op_sel_hi:[1,0]
	v_pk_mul_f32 v[12:13], v[10:11], s[6:7] op_sel_hi:[1,0]
	v_cvt_pk_bf16_f32 v10, v14, v15
	v_pk_mul_f32 v[16:17], v[16:17], s[6:7] op_sel_hi:[1,0]
	v_cvt_pk_bf16_f32 v12, v12, v13
	v_cvt_pk_bf16_f32 v11, v16, v17
	v_cvt_pk_bf16_f32 v13, v20, v21
	v_pk_mul_f32 v[6:7], v[6:7], s[6:7] op_sel_hi:[1,0]
	v_lshl_add_u64 v[18:19], v[134:135], 1, v[18:19]
	v_permlane16_swap_b32_e32 v10, v12
	v_permlane16_swap_b32_e32 v11, v13
	global_store_dwordx4 v[18:19], v[10:13], off
	s_nop 1
	v_pk_mul_f32 v[10:11], v[4:5], s[6:7] op_sel_hi:[1,0]
	v_pk_mul_f32 v[4:5], v[2:3], s[6:7] op_sel_hi:[1,0]
	v_cvt_pk_bf16_f32 v2, v6, v7
	v_pk_mul_f32 v[8:9], v[8:9], s[6:7] op_sel_hi:[1,0]
	v_cvt_pk_bf16_f32 v4, v4, v5
	v_cvt_pk_bf16_f32 v3, v8, v9
	v_cvt_pk_bf16_f32 v5, v10, v11
	v_permlane16_swap_b32_e32 v2, v4
	s_nop 0
	v_permlane16_swap_b32_e32 v3, v5
	global_store_dwordx4 v[18:19], v[2:5], off offset:64
	s_andn2_b64 vcc, exec, s[4:5]
	s_mov_b64 s[4:5], -1
	s_cbranch_vccnz .LBB0_672

.LBB0_913:
	v_cmp_gt_u32_e32 vcc, s2, v1
	v_bfe_u32 v11, v1, 16, 2
	v_and_b32_e32 v18, 0x3fc, v4
	v_cndmask_b32_e64 v2, 40, 32, vcc
	v_lshl_add_u64 v[12:13], s[60:61], 0, v[2:3]
	global_load_dwordx2 v[12:13], v[12:13], off
	v_lshlrev_b32_sdwa v2, v10, v1 dst_sel:DWORD dst_unused:UNUSED_PAD src0_sel:DWORD src1_sel:BYTE_1
	v_lshlrev_b32_e32 v14, 18, v11
	v_or3_b32 v2, v14, v2, v18
	v_lshlrev_b32_e32 v2, 2, v2
	v_cndmask_b32_e32 v17, v5, v6, vcc
	v_cndmask_b32_e32 v16, v7, v8, vcc
	v_add_u32_e32 v4, s1, v4
	s_waitcnt vmcnt(0)
	v_lshl_add_u64 v[12:13], v[12:13], 0, v[2:3]
	global_load_dwordx4 v[12:15], v[12:13], off
	v_mul_u32_u24_e32 v2, 0x1100, v11
	v_or_b32_sdwa v2, v2, v1 dst_sel:DWORD dst_unused:UNUSED_PAD src0_sel:DWORD src1_sel:BYTE_1
	v_lshl_add_u32 v2, v2, 11, v9
	v_lshl_add_u64 v[16:17], v[16:17], 0, v[2:3]
	v_lshlrev_b32_e32 v2, 1, v18
	v_lshl_add_u64 v[16:17], v[16:17], 0, v[2:3]
	v_add_u32_e32 v1, s0, v1
	v_cmp_lt_i32_e32 vcc, s9, v1
	s_or_b64 s[6:7], vcc, s[6:7]
	s_waitcnt vmcnt(0)
	v_bfe_u32 v2, v12, 16, 1
	v_bfe_u32 v11, v13, 16, 1
	v_add3_u32 v2, v12, v2, s3
	v_add3_u32 v11, v13, v11, s3
	v_lshrrev_b32_e32 v2, 16, v2
	v_and_or_b32 v12, v11, s8, v2
	v_cvt_pk_bf16_f32 v13, v14, v15
	global_store_dwordx2 v[16:17], v[12:13], off
	s_andn2_b64 exec, exec, s[6:7]
	s_cbranch_execnz .LBB0_913

.LBB0_1070:
	s_lshl_b32 s8, s8, 8
	v_lshl_add_u32 v208, v153, 5, s8
	v_lshlrev_b32_e32 v209, 2, v1
	s_lshl_b32 s9, s30, 8
	v_lshlrev_b32_e32 v130, 6, v152
	v_add_u32_e32 v196, v208, v209
	v_add3_u32 v192, v154, s9, v130
	v_lshl_add_u64 v[130:131], s[54:55], 2, v[166:167]
	v_ashrrev_i32_e32 v197, 31, v196
	v_lshl_add_u64 v[130:131], v[196:197], 2, v[130:131]
	v_lshl_add_u64 v[194:195], v[130:131], 0, s[42:43]
	s_cmp_lt_i32 s3, 0
	s_mov_b64 s[8:9], -1
	s_cbranch_scc0 .LBB0_1072
	v_ashrrev_i32_e32 v193, 31, v192
	v_lshl_add_u64 v[150:151], v[196:197], 2, s[12:13]
	v_lshlrev_b64 v[130:131], 12, v[192:193]
	v_lshl_add_u64 v[164:165], v[150:151], 0, v[130:131]
	global_load_dwordx4 v[156:159], v[164:165], off
	global_load_dwordx4 v[142:145], v[194:195], off
	global_load_dwordx4 v[138:141], v[194:195], off offset:64
	global_load_dwordx4 v[160:163], v[164:165], off offset:64
	global_load_dwordx4 v[134:137], v[194:195], off offset:512
	global_load_dwordx4 v[130:133], v[194:195], off offset:576
	v_and_b32_e32 v146, 1, v1
	v_add_u32_e32 v147, 12, v209
	v_cmp_eq_u32_e32 vcc, 0, v146
	v_lshlrev_b64 v[148:149], 11, v[192:193]
	v_lshl_add_u64 v[198:199], v[176:177], 0, v[148:149]
	v_cndmask_b32_e32 v146, v147, v209, vcc
	v_add_u32_e32 v146, v146, v208
	v_ashrrev_i32_e32 v147, 31, v146
	v_lshlrev_b64 v[148:149], 1, v[146:147]
	v_lshl_add_u64 v[198:199], v[198:199], 0, v[148:149]
	s_mov_b64 s[8:9], 0
	s_mov_b64 s[52:53], -1
	s_waitcnt vmcnt(0)
	v_pk_fma_f32 v[158:159], v[64:65], v[144:145], v[158:159]
	v_pk_fma_f32 v[156:157], v[62:63], v[142:143], v[156:157]
	v_pk_fma_f32 v[162:163], v[60:61], v[140:141], v[162:163]
	v_pk_fma_f32 v[160:161], v[58:59], v[138:139], v[160:161]
	v_bfe_u32 v155, v156, 16, 1
	v_bfe_u32 v193, v157, 16, 1
	v_bfe_u32 v210, v160, 16, 1
	v_bfe_u32 v211, v161, 16, 1
	v_bfe_u32 v212, v158, 16, 1
	v_bfe_u32 v214, v162, 16, 1
	v_bfe_u32 v213, v159, 16, 1
	v_bfe_u32 v215, v163, 16, 1
	v_add3_u32 v155, v156, v155, s66
	v_add3_u32 v156, v157, v193, s66
	v_add3_u32 v157, v160, v210, s66
	v_add3_u32 v160, v161, v211, s66
	v_add3_u32 v158, v158, v212, s66
	v_add3_u32 v161, v162, v214, s66
	v_add3_u32 v159, v159, v213, s66
	v_add3_u32 v162, v163, v215, s66
	v_lshrrev_b32_e32 v155, 16, v155
	v_lshrrev_b32_e32 v157, 16, v157
	v_lshrrev_b32_e32 v163, 16, v158
	v_lshrrev_b32_e32 v161, 16, v161
	v_and_or_b32 v156, v156, s67, v155
	v_and_or_b32 v158, v160, s67, v157
	v_and_or_b32 v157, v159, s67, v163
	v_and_or_b32 v159, v162, s67, v161
	v_permlane16_swap_b32_e32 v156, v158
	s_nop 0
	v_permlane16_swap_b32_e32 v157, v159
	global_store_dwordx4 v[198:199], v[156:159], off
	global_load_dwordx4 v[156:159], v[164:165], off offset:512
	s_nop 0
	global_load_dwordx4 v[160:163], v[164:165], off offset:576
	v_add_u32_e32 v164, 16, v192
	v_ashrrev_i32_e32 v165, 31, v164
	v_lshlrev_b64 v[210:211], 12, v[164:165]
	v_lshl_add_u64 v[210:211], v[150:151], 0, v[210:211]
	v_lshlrev_b64 v[164:165], 11, v[164:165]
	v_lshl_add_u64 v[164:165], v[176:177], 0, v[164:165]
	v_lshl_add_u64 v[164:165], v[164:165], 0, v[148:149]
	s_waitcnt vmcnt(1)
	v_pk_fma_f32 v[158:159], v[32:33], v[136:137], v[158:159]
	v_pk_fma_f32 v[156:157], v[30:31], v[134:135], v[156:157]
	s_waitcnt vmcnt(0)
	v_pk_fma_f32 v[162:163], v[28:29], v[132:133], v[162:163]
	v_pk_fma_f32 v[160:161], v[26:27], v[130:131], v[160:161]
	v_bfe_u32 v155, v156, 16, 1
	v_bfe_u32 v193, v157, 16, 1
	v_bfe_u32 v212, v160, 16, 1
	v_bfe_u32 v213, v161, 16, 1
	v_bfe_u32 v214, v158, 16, 1
	v_bfe_u32 v216, v162, 16, 1
	v_bfe_u32 v215, v159, 16, 1
	v_bfe_u32 v217, v163, 16, 1
	v_add3_u32 v155, v156, v155, s66
	v_add3_u32 v156, v157, v193, s66
	v_add3_u32 v157, v160, v212, s66
	v_add3_u32 v160, v161, v213, s66
	v_add3_u32 v158, v158, v214, s66
	v_add3_u32 v161, v162, v216, s66
	v_add3_u32 v159, v159, v215, s66
	v_add3_u32 v162, v163, v217, s66
	v_lshrrev_b32_e32 v155, 16, v155
	v_lshrrev_b32_e32 v157, 16, v157
	v_lshrrev_b32_e32 v163, 16, v158
	v_lshrrev_b32_e32 v161, 16, v161
	v_and_or_b32 v156, v156, s67, v155
	v_and_or_b32 v158, v160, s67, v157
	v_and_or_b32 v157, v159, s67, v163
	v_and_or_b32 v159, v162, s67, v161
	v_permlane16_swap_b32_e32 v156, v158
	s_nop 0
	v_permlane16_swap_b32_e32 v157, v159
	global_store_dwordx4 v[198:199], v[156:159], off offset:256
	global_load_dwordx4 v[156:159], v[210:211], off
	s_nop 0
	global_load_dwordx4 v[160:163], v[210:211], off offset:64
	s_waitcnt vmcnt(1)
	v_pk_fma_f32 v[158:159], v[56:57], v[144:145], v[158:159]
	v_pk_fma_f32 v[156:157], v[54:55], v[142:143], v[156:157]
	s_waitcnt vmcnt(0)
	v_pk_fma_f32 v[162:163], v[52:53], v[140:141], v[162:163]
	v_pk_fma_f32 v[160:161], v[50:51], v[138:139], v[160:161]
	v_bfe_u32 v155, v156, 16, 1
	v_bfe_u32 v193, v157, 16, 1
	v_bfe_u32 v198, v160, 16, 1
	v_bfe_u32 v199, v161, 16, 1
	v_bfe_u32 v212, v158, 16, 1
	v_bfe_u32 v214, v162, 16, 1
	v_bfe_u32 v213, v159, 16, 1
	v_bfe_u32 v215, v163, 16, 1
	v_add3_u32 v155, v156, v155, s66
	v_add3_u32 v156, v157, v193, s66
	v_add3_u32 v157, v160, v198, s66
	v_add3_u32 v160, v161, v199, s66
	v_add3_u32 v158, v158, v212, s66
	v_add3_u32 v161, v162, v214, s66
	v_add3_u32 v159, v159, v213, s66
	v_add3_u32 v162, v163, v215, s66
	v_lshrrev_b32_e32 v155, 16, v155
	v_lshrrev_b32_e32 v157, 16, v157
	v_lshrrev_b32_e32 v163, 16, v158
	v_lshrrev_b32_e32 v161, 16, v161
	v_and_or_b32 v156, v156, s67, v155
	v_and_or_b32 v158, v160, s67, v157
	v_and_or_b32 v157, v159, s67, v163
	v_and_or_b32 v159, v162, s67, v161
	v_permlane16_swap_b32_e32 v156, v158
	s_nop 0
	v_permlane16_swap_b32_e32 v157, v159
	global_store_dwordx4 v[164:165], v[156:159], off
	global_load_dwordx4 v[156:159], v[210:211], off offset:512
	s_nop 0
	global_load_dwordx4 v[160:163], v[210:211], off offset:576
	v_add_u32_e32 v198, 32, v192
	v_ashrrev_i32_e32 v199, 31, v198
	v_lshlrev_b64 v[210:211], 12, v[198:199]
	v_lshl_add_u64 v[210:211], v[150:151], 0, v[210:211]
	s_waitcnt vmcnt(1)
	v_pk_fma_f32 v[158:159], v[24:25], v[136:137], v[158:159]
	v_pk_fma_f32 v[156:157], v[22:23], v[134:135], v[156:157]
	s_waitcnt vmcnt(0)
	v_pk_fma_f32 v[162:163], v[20:21], v[132:133], v[162:163]
	v_pk_fma_f32 v[160:161], v[18:19], v[130:131], v[160:161]
	v_bfe_u32 v155, v156, 16, 1
	v_bfe_u32 v193, v157, 16, 1
	v_bfe_u32 v212, v160, 16, 1
	v_bfe_u32 v213, v161, 16, 1
	v_bfe_u32 v214, v158, 16, 1
	v_bfe_u32 v216, v162, 16, 1
	v_bfe_u32 v215, v159, 16, 1
	v_bfe_u32 v217, v163, 16, 1
	v_add3_u32 v155, v156, v155, s66
	v_add3_u32 v156, v157, v193, s66
	v_add3_u32 v157, v160, v212, s66
	v_add3_u32 v160, v161, v213, s66
	v_add3_u32 v158, v158, v214, s66
	v_add3_u32 v161, v162, v216, s66
	v_add3_u32 v159, v159, v215, s66
	v_add3_u32 v162, v163, v217, s66
	v_lshrrev_b32_e32 v155, 16, v155
	v_lshrrev_b32_e32 v157, 16, v157
	v_lshrrev_b32_e32 v163, 16, v158
	v_lshrrev_b32_e32 v161, 16, v161
	v_and_or_b32 v156, v156, s67, v155
	v_and_or_b32 v158, v160, s67, v157
	v_and_or_b32 v157, v159, s67, v163
	v_and_or_b32 v159, v162, s67, v161
	v_permlane16_swap_b32_e32 v156, v158
	s_nop 0
	v_permlane16_swap_b32_e32 v157, v159
	global_store_dwordx4 v[164:165], v[156:159], off offset:256
	global_load_dwordx4 v[156:159], v[210:211], off
	s_nop 0
	global_load_dwordx4 v[160:163], v[210:211], off offset:64
	v_lshlrev_b64 v[164:165], 11, v[198:199]
	v_lshl_add_u64 v[164:165], v[176:177], 0, v[164:165]
	v_lshl_add_u64 v[164:165], v[164:165], 0, v[148:149]
	s_waitcnt vmcnt(1)
	v_pk_fma_f32 v[158:159], v[48:49], v[144:145], v[158:159]
	v_pk_fma_f32 v[156:157], v[46:47], v[142:143], v[156:157]
	s_waitcnt vmcnt(0)
	v_pk_fma_f32 v[162:163], v[44:45], v[140:141], v[162:163]
	v_pk_fma_f32 v[160:161], v[42:43], v[138:139], v[160:161]
	v_bfe_u32 v155, v156, 16, 1
	v_bfe_u32 v193, v157, 16, 1
	v_bfe_u32 v198, v160, 16, 1
	v_bfe_u32 v199, v161, 16, 1
	v_bfe_u32 v212, v158, 16, 1
	v_bfe_u32 v214, v162, 16, 1
	v_bfe_u32 v213, v159, 16, 1
	v_bfe_u32 v215, v163, 16, 1
	v_add3_u32 v155, v156, v155, s66
	v_add3_u32 v156, v157, v193, s66
	v_add3_u32 v157, v160, v198, s66
	v_add3_u32 v160, v161, v199, s66
	v_add3_u32 v158, v158, v212, s66
	v_add3_u32 v161, v162, v214, s66
	v_add3_u32 v159, v159, v213, s66
	v_add3_u32 v162, v163, v215, s66
	v_lshrrev_b32_e32 v155, 16, v155
	v_lshrrev_b32_e32 v157, 16, v157
	v_lshrrev_b32_e32 v163, 16, v158
	v_lshrrev_b32_e32 v161, 16, v161
	v_and_or_b32 v156, v156, s67, v155
	v_and_or_b32 v158, v160, s67, v157
	v_and_or_b32 v157, v159, s67, v163
	v_and_or_b32 v159, v162, s67, v161
	v_permlane16_swap_b32_e32 v156, v158
	s_nop 0
	v_permlane16_swap_b32_e32 v157, v159
	global_store_dwordx4 v[164:165], v[156:159], off
	global_load_dwordx4 v[156:159], v[210:211], off offset:512
	s_nop 0
	global_load_dwordx4 v[160:163], v[210:211], off offset:576
	v_add_u32_e32 v198, 48, v192
	v_ashrrev_i32_e32 v199, 31, v198
	v_lshlrev_b64 v[210:211], 12, v[198:199]
	v_lshl_add_u64 v[210:211], v[150:151], 0, v[210:211]
	s_waitcnt vmcnt(1)
	v_pk_fma_f32 v[158:159], v[16:17], v[136:137], v[158:159]
	v_pk_fma_f32 v[156:157], v[14:15], v[134:135], v[156:157]
	s_waitcnt vmcnt(0)
	v_pk_fma_f32 v[162:163], v[12:13], v[132:133], v[162:163]
	v_pk_fma_f32 v[160:161], v[10:11], v[130:131], v[160:161]
	v_bfe_u32 v155, v156, 16, 1
	v_bfe_u32 v193, v157, 16, 1
	v_bfe_u32 v212, v160, 16, 1
	v_bfe_u32 v213, v161, 16, 1
	v_bfe_u32 v214, v158, 16, 1
	v_bfe_u32 v216, v162, 16, 1
	v_bfe_u32 v215, v159, 16, 1
	v_bfe_u32 v217, v163, 16, 1
	v_add3_u32 v155, v156, v155, s66
	v_add3_u32 v156, v157, v193, s66
	v_add3_u32 v157, v160, v212, s66
	v_add3_u32 v160, v161, v213, s66
	v_add3_u32 v158, v158, v214, s66
	v_add3_u32 v161, v162, v216, s66
	v_add3_u32 v159, v159, v215, s66
	v_add3_u32 v162, v163, v217, s66
	v_lshrrev_b32_e32 v155, 16, v155
	v_lshrrev_b32_e32 v157, 16, v157
	v_lshrrev_b32_e32 v163, 16, v158
	v_lshrrev_b32_e32 v161, 16, v161
	v_and_or_b32 v156, v156, s67, v155
	v_and_or_b32 v158, v160, s67, v157
	v_and_or_b32 v157, v159, s67, v163
	v_and_or_b32 v159, v162, s67, v161
	v_permlane16_swap_b32_e32 v156, v158
	s_nop 0
	v_permlane16_swap_b32_e32 v157, v159
	global_store_dwordx4 v[164:165], v[156:159], off offset:256
	global_load_dwordx4 v[156:159], v[210:211], off
	s_nop 0
	global_load_dwordx4 v[160:163], v[210:211], off offset:64
	v_lshlrev_b64 v[164:165], 11, v[198:199]
	v_lshl_add_u64 v[164:165], v[176:177], 0, v[164:165]
	v_lshl_add_u64 v[164:165], v[164:165], 0, v[148:149]
	v_add_u32_e32 v198, 0x80, v192
	v_ashrrev_i32_e32 v199, 31, v198
	s_waitcnt vmcnt(1)
	v_pk_fma_f32 v[144:145], v[40:41], v[144:145], v[158:159]
	v_pk_fma_f32 v[142:143], v[38:39], v[142:143], v[156:157]
	s_waitcnt vmcnt(0)
	v_pk_fma_f32 v[140:141], v[36:37], v[140:141], v[162:163]
	v_pk_fma_f32 v[138:139], v[34:35], v[138:139], v[160:161]
	v_bfe_u32 v157, v138, 16, 1
	v_bfe_u32 v161, v140, 16, 1
	v_bfe_u32 v158, v139, 16, 1
	v_bfe_u32 v162, v141, 16, 1
	v_add3_u32 v138, v138, v157, s66
	v_add3_u32 v140, v140, v161, s66
	v_add3_u32 v139, v139, v158, s66
	v_add3_u32 v141, v141, v162, s66
	v_lshrrev_b32_e32 v155, 16, v138
	v_lshrrev_b32_e32 v156, 16, v140
	v_cvt_pk_bf16_f32 v138, v142, v143
	v_and_or_b32 v140, v139, s67, v155
	v_cvt_pk_bf16_f32 v139, v144, v145
	v_and_or_b32 v141, v141, s67, v156
	v_permlane16_swap_b32_e32 v138, v140
	s_nop 0
	v_permlane16_swap_b32_e32 v139, v141
	global_store_dwordx4 v[164:165], v[138:141], off
	global_load_dwordx4 v[138:141], v[210:211], off offset:512
	s_nop 0
	global_load_dwordx4 v[142:145], v[210:211], off offset:576
	v_lshlrev_b64 v[156:157], 12, v[198:199]
	v_lshl_add_u64 v[210:211], v[150:151], 0, v[156:157]
	s_waitcnt vmcnt(1)
	v_pk_fma_f32 v[136:137], v[8:9], v[136:137], v[140:141]
	v_pk_fma_f32 v[134:135], v[6:7], v[134:135], v[138:139]
	s_waitcnt vmcnt(0)
	v_pk_fma_f32 v[132:133], v[4:5], v[132:133], v[144:145]
	v_pk_fma_f32 v[130:131], v[2:3], v[130:131], v[142:143]
	v_bfe_u32 v140, v130, 16, 1
	v_bfe_u32 v144, v132, 16, 1
	v_bfe_u32 v141, v131, 16, 1
	v_bfe_u32 v145, v133, 16, 1
	v_add3_u32 v130, v130, v140, s66
	v_add3_u32 v132, v132, v144, s66
	v_add3_u32 v131, v131, v141, s66
	v_add3_u32 v133, v133, v145, s66
	v_lshrrev_b32_e32 v138, 16, v130
	v_lshrrev_b32_e32 v139, 16, v132
	v_cvt_pk_bf16_f32 v130, v134, v135
	v_and_or_b32 v132, v131, s67, v138
	v_cvt_pk_bf16_f32 v131, v136, v137
	v_and_or_b32 v133, v133, s67, v139
	v_permlane16_swap_b32_e32 v130, v132
	s_nop 0
	v_permlane16_swap_b32_e32 v131, v133
	global_store_dwordx4 v[164:165], v[130:133], off offset:256
	global_load_dwordx4 v[156:159], v[210:211], off
	global_load_dwordx4 v[142:145], v[194:195], off
	global_load_dwordx4 v[138:141], v[194:195], off offset:64
	global_load_dwordx4 v[160:163], v[210:211], off offset:64
	v_lshlrev_b64 v[130:131], 11, v[198:199]
	v_lshl_add_u64 v[130:131], v[176:177], 0, v[130:131]
	v_lshl_add_u64 v[164:165], v[130:131], 0, v[148:149]
	global_load_dwordx4 v[134:137], v[194:195], off offset:512
	global_load_dwordx4 v[130:133], v[194:195], off offset:576
	s_waitcnt vmcnt(4)
	v_pk_fma_f32 v[158:159], v[128:129], v[144:145], v[158:159]
	v_pk_fma_f32 v[156:157], v[126:127], v[142:143], v[156:157]
	s_waitcnt vmcnt(2)
	v_pk_fma_f32 v[162:163], v[124:125], v[140:141], v[162:163]
	v_pk_fma_f32 v[160:161], v[122:123], v[138:139], v[160:161]
	v_bfe_u32 v155, v156, 16, 1
	v_bfe_u32 v193, v157, 16, 1
	v_bfe_u32 v198, v160, 16, 1
	v_bfe_u32 v199, v161, 16, 1
	v_bfe_u32 v212, v158, 16, 1
	v_bfe_u32 v214, v162, 16, 1
	v_bfe_u32 v213, v159, 16, 1
	v_bfe_u32 v215, v163, 16, 1
	v_add3_u32 v155, v156, v155, s66
	v_add3_u32 v156, v157, v193, s66
	v_add3_u32 v157, v160, v198, s66
	v_add3_u32 v160, v161, v199, s66
	v_add3_u32 v158, v158, v212, s66
	v_add3_u32 v161, v162, v214, s66
	v_add3_u32 v159, v159, v213, s66
	v_add3_u32 v162, v163, v215, s66
	v_lshrrev_b32_e32 v155, 16, v155
	v_lshrrev_b32_e32 v157, 16, v157
	v_lshrrev_b32_e32 v163, 16, v158
	v_lshrrev_b32_e32 v161, 16, v161
	v_and_or_b32 v156, v156, s67, v155
	v_and_or_b32 v158, v160, s67, v157
	v_and_or_b32 v157, v159, s67, v163
	v_and_or_b32 v159, v162, s67, v161
	v_permlane16_swap_b32_e32 v156, v158
	s_nop 0
	v_permlane16_swap_b32_e32 v157, v159
	global_store_dwordx4 v[164:165], v[156:159], off
	global_load_dwordx4 v[156:159], v[210:211], off offset:512
	s_nop 0
	global_load_dwordx4 v[160:163], v[210:211], off offset:576
	v_add_u32_e32 v198, 0x90, v192
	v_ashrrev_i32_e32 v199, 31, v198
	v_lshlrev_b64 v[210:211], 12, v[198:199]
	v_lshl_add_u64 v[210:211], v[150:151], 0, v[210:211]
	s_waitcnt vmcnt(1)
	v_pk_fma_f32 v[158:159], v[96:97], v[136:137], v[158:159]
	v_pk_fma_f32 v[156:157], v[94:95], v[134:135], v[156:157]
	s_waitcnt vmcnt(0)
	v_pk_fma_f32 v[162:163], v[92:93], v[132:133], v[162:163]
	v_pk_fma_f32 v[160:161], v[90:91], v[130:131], v[160:161]
	v_bfe_u32 v155, v156, 16, 1
	v_bfe_u32 v193, v157, 16, 1
	v_bfe_u32 v212, v160, 16, 1
	v_bfe_u32 v213, v161, 16, 1
	v_bfe_u32 v214, v158, 16, 1
	v_bfe_u32 v216, v162, 16, 1
	v_bfe_u32 v215, v159, 16, 1
	v_bfe_u32 v217, v163, 16, 1
	v_add3_u32 v155, v156, v155, s66
	v_add3_u32 v156, v157, v193, s66
	v_add3_u32 v157, v160, v212, s66
	v_add3_u32 v160, v161, v213, s66
	v_add3_u32 v158, v158, v214, s66
	v_add3_u32 v161, v162, v216, s66
	v_add3_u32 v159, v159, v215, s66
	v_add3_u32 v162, v163, v217, s66
	v_lshrrev_b32_e32 v155, 16, v155
	v_lshrrev_b32_e32 v157, 16, v157
	v_lshrrev_b32_e32 v163, 16, v158
	v_lshrrev_b32_e32 v161, 16, v161
	v_and_or_b32 v156, v156, s67, v155
	v_and_or_b32 v158, v160, s67, v157
	v_and_or_b32 v157, v159, s67, v163
	v_and_or_b32 v159, v162, s67, v161
	v_permlane16_swap_b32_e32 v156, v158
	s_nop 0
	v_permlane16_swap_b32_e32 v157, v159
	global_store_dwordx4 v[164:165], v[156:159], off offset:256
	global_load_dwordx4 v[156:159], v[210:211], off
	s_nop 0
	global_load_dwordx4 v[160:163], v[210:211], off offset:64
	v_lshlrev_b64 v[164:165], 11, v[198:199]
	v_lshl_add_u64 v[164:165], v[176:177], 0, v[164:165]
	v_lshl_add_u64 v[164:165], v[164:165], 0, v[148:149]
	s_waitcnt vmcnt(1)
	v_pk_fma_f32 v[158:159], v[120:121], v[144:145], v[158:159]
	v_pk_fma_f32 v[156:157], v[118:119], v[142:143], v[156:157]
	s_waitcnt vmcnt(0)
	v_pk_fma_f32 v[162:163], v[116:117], v[140:141], v[162:163]
	v_pk_fma_f32 v[160:161], v[114:115], v[138:139], v[160:161]
	v_bfe_u32 v155, v156, 16, 1
	v_bfe_u32 v193, v157, 16, 1
	v_bfe_u32 v198, v160, 16, 1
	v_bfe_u32 v199, v161, 16, 1
	v_bfe_u32 v212, v158, 16, 1
	v_bfe_u32 v214, v162, 16, 1
	v_bfe_u32 v213, v159, 16, 1
	v_bfe_u32 v215, v163, 16, 1
	v_add3_u32 v155, v156, v155, s66
	v_add3_u32 v156, v157, v193, s66
	v_add3_u32 v157, v160, v198, s66
	v_add3_u32 v160, v161, v199, s66
	v_add3_u32 v158, v158, v212, s66
	v_add3_u32 v161, v162, v214, s66
	v_add3_u32 v159, v159, v213, s66
	v_add3_u32 v162, v163, v215, s66
	v_lshrrev_b32_e32 v155, 16, v155
	v_lshrrev_b32_e32 v157, 16, v157
	v_lshrrev_b32_e32 v163, 16, v158
	v_lshrrev_b32_e32 v161, 16, v161
	v_and_or_b32 v156, v156, s67, v155
	v_and_or_b32 v158, v160, s67, v157
	v_and_or_b32 v157, v159, s67, v163
	v_and_or_b32 v159, v162, s67, v161
	v_permlane16_swap_b32_e32 v156, v158
	s_nop 0
	v_permlane16_swap_b32_e32 v157, v159
	global_store_dwordx4 v[164:165], v[156:159], off
	global_load_dwordx4 v[156:159], v[210:211], off offset:512
	s_nop 0
	global_load_dwordx4 v[160:163], v[210:211], off offset:576
	v_add_u32_e32 v198, 0xa0, v192
	v_ashrrev_i32_e32 v199, 31, v198
	v_lshlrev_b64 v[210:211], 12, v[198:199]
	v_lshl_add_u64 v[210:211], v[150:151], 0, v[210:211]
	s_waitcnt vmcnt(1)
	v_pk_fma_f32 v[158:159], v[88:89], v[136:137], v[158:159]
	v_pk_fma_f32 v[156:157], v[86:87], v[134:135], v[156:157]
	s_waitcnt vmcnt(0)
	v_pk_fma_f32 v[162:163], v[84:85], v[132:133], v[162:163]
	v_pk_fma_f32 v[160:161], v[82:83], v[130:131], v[160:161]
	v_bfe_u32 v155, v156, 16, 1
	v_bfe_u32 v193, v157, 16, 1
	v_bfe_u32 v212, v160, 16, 1
	v_bfe_u32 v213, v161, 16, 1
	v_bfe_u32 v214, v158, 16, 1
	v_bfe_u32 v216, v162, 16, 1
	v_bfe_u32 v215, v159, 16, 1
	v_bfe_u32 v217, v163, 16, 1
	v_add3_u32 v155, v156, v155, s66
	v_add3_u32 v156, v157, v193, s66
	v_add3_u32 v157, v160, v212, s66
	v_add3_u32 v160, v161, v213, s66
	v_add3_u32 v158, v158, v214, s66
	v_add3_u32 v161, v162, v216, s66
	v_add3_u32 v159, v159, v215, s66
	v_add3_u32 v162, v163, v217, s66
	v_lshrrev_b32_e32 v155, 16, v155
	v_lshrrev_b32_e32 v157, 16, v157
	v_lshrrev_b32_e32 v163, 16, v158
	v_lshrrev_b32_e32 v161, 16, v161
	v_and_or_b32 v156, v156, s67, v155
	v_and_or_b32 v158, v160, s67, v157
	v_and_or_b32 v157, v159, s67, v163
	v_and_or_b32 v159, v162, s67, v161
	v_permlane16_swap_b32_e32 v156, v158
	s_nop 0
	v_permlane16_swap_b32_e32 v157, v159
	global_store_dwordx4 v[164:165], v[156:159], off offset:256
	global_load_dwordx4 v[156:159], v[210:211], off
	s_nop 0
	global_load_dwordx4 v[160:163], v[210:211], off offset:64
	v_lshlrev_b64 v[164:165], 11, v[198:199]
	v_lshl_add_u64 v[164:165], v[176:177], 0, v[164:165]
	v_lshl_add_u64 v[164:165], v[164:165], 0, v[148:149]
	s_waitcnt vmcnt(1)
	v_pk_fma_f32 v[158:159], v[112:113], v[144:145], v[158:159]
	v_pk_fma_f32 v[156:157], v[110:111], v[142:143], v[156:157]
	s_waitcnt vmcnt(0)
	v_pk_fma_f32 v[162:163], v[108:109], v[140:141], v[162:163]
	v_pk_fma_f32 v[160:161], v[106:107], v[138:139], v[160:161]
	v_bfe_u32 v155, v156, 16, 1
	v_bfe_u32 v193, v157, 16, 1
	v_bfe_u32 v198, v160, 16, 1
	v_bfe_u32 v199, v161, 16, 1
	v_bfe_u32 v212, v158, 16, 1
	v_bfe_u32 v214, v162, 16, 1
	v_bfe_u32 v213, v159, 16, 1
	v_bfe_u32 v215, v163, 16, 1
	v_add3_u32 v155, v156, v155, s66
	v_add3_u32 v156, v157, v193, s66
	v_add3_u32 v157, v160, v198, s66
	v_add3_u32 v160, v161, v199, s66
	v_add3_u32 v158, v158, v212, s66
	v_add3_u32 v161, v162, v214, s66
	v_add3_u32 v159, v159, v213, s66
	v_add3_u32 v162, v163, v215, s66
	v_lshrrev_b32_e32 v155, 16, v155
	v_lshrrev_b32_e32 v157, 16, v157
	v_lshrrev_b32_e32 v163, 16, v158
	v_lshrrev_b32_e32 v161, 16, v161
	v_and_or_b32 v156, v156, s67, v155
	v_and_or_b32 v158, v160, s67, v157
	v_and_or_b32 v157, v159, s67, v163
	v_and_or_b32 v159, v162, s67, v161
	v_permlane16_swap_b32_e32 v156, v158
	s_nop 0
	v_permlane16_swap_b32_e32 v157, v159
	global_store_dwordx4 v[164:165], v[156:159], off
	global_load_dwordx4 v[156:159], v[210:211], off offset:512
	s_nop 0
	global_load_dwordx4 v[160:163], v[210:211], off offset:576
	v_add_u32_e32 v198, 0xb0, v192
	v_ashrrev_i32_e32 v199, 31, v198
	v_lshlrev_b64 v[210:211], 12, v[198:199]
	v_lshl_add_u64 v[150:151], v[150:151], 0, v[210:211]
	s_waitcnt vmcnt(1)
	v_pk_fma_f32 v[158:159], v[80:81], v[136:137], v[158:159]
	v_pk_fma_f32 v[156:157], v[78:79], v[134:135], v[156:157]
	s_waitcnt vmcnt(0)
	v_pk_fma_f32 v[162:163], v[76:77], v[132:133], v[162:163]
	v_pk_fma_f32 v[160:161], v[74:75], v[130:131], v[160:161]
	v_bfe_u32 v155, v156, 16, 1
	v_bfe_u32 v193, v157, 16, 1
	v_bfe_u32 v210, v160, 16, 1
	v_bfe_u32 v211, v161, 16, 1
	v_bfe_u32 v212, v158, 16, 1
	v_bfe_u32 v214, v162, 16, 1
	v_bfe_u32 v213, v159, 16, 1
	v_bfe_u32 v215, v163, 16, 1
	v_add3_u32 v155, v156, v155, s66
	v_add3_u32 v156, v157, v193, s66
	v_add3_u32 v157, v160, v210, s66
	v_add3_u32 v160, v161, v211, s66
	v_add3_u32 v158, v158, v212, s66
	v_add3_u32 v161, v162, v214, s66
	v_add3_u32 v159, v159, v213, s66
	v_add3_u32 v162, v163, v215, s66
	v_lshrrev_b32_e32 v155, 16, v155
	v_lshrrev_b32_e32 v157, 16, v157
	v_lshrrev_b32_e32 v163, 16, v158
	v_lshrrev_b32_e32 v161, 16, v161
	v_and_or_b32 v156, v156, s67, v155
	v_and_or_b32 v158, v160, s67, v157
	v_and_or_b32 v157, v159, s67, v163
	v_and_or_b32 v159, v162, s67, v161
	v_permlane16_swap_b32_e32 v156, v158
	s_nop 0
	v_permlane16_swap_b32_e32 v157, v159
	global_store_dwordx4 v[164:165], v[156:159], off offset:256
	global_load_dwordx4 v[156:159], v[150:151], off
	s_nop 0
	global_load_dwordx4 v[160:163], v[150:151], off offset:64
	v_lshlrev_b64 v[164:165], 11, v[198:199]
	v_lshl_add_u64 v[164:165], v[176:177], 0, v[164:165]
	v_lshl_add_u64 v[148:149], v[164:165], 0, v[148:149]
	s_waitcnt vmcnt(1)
	v_pk_fma_f32 v[144:145], v[104:105], v[144:145], v[158:159]
	v_pk_fma_f32 v[142:143], v[102:103], v[142:143], v[156:157]
	s_waitcnt vmcnt(0)
	v_pk_fma_f32 v[140:141], v[100:101], v[140:141], v[162:163]
	v_pk_fma_f32 v[138:139], v[98:99], v[138:139], v[160:161]
	v_bfe_u32 v157, v138, 16, 1
	v_bfe_u32 v161, v140, 16, 1
	v_bfe_u32 v158, v139, 16, 1
	v_bfe_u32 v162, v141, 16, 1
	v_add3_u32 v138, v138, v157, s66
	v_add3_u32 v140, v140, v161, s66
	v_add3_u32 v139, v139, v158, s66
	v_add3_u32 v141, v141, v162, s66
	v_lshrrev_b32_e32 v155, 16, v138
	v_lshrrev_b32_e32 v156, 16, v140
	v_cvt_pk_bf16_f32 v138, v142, v143
	v_and_or_b32 v140, v139, s67, v155
	v_cvt_pk_bf16_f32 v139, v144, v145
	v_and_or_b32 v141, v141, s67, v156
	v_permlane16_swap_b32_e32 v138, v140
	s_nop 0
	v_permlane16_swap_b32_e32 v139, v141
	global_store_dwordx4 v[148:149], v[138:141], off
	global_load_dwordx4 v[140:143], v[150:151], off offset:512
	s_nop 0
	global_load_dwordx4 v[148:151], v[150:151], off offset:576
	v_lshlrev_b64 v[138:139], 10, v[198:199]
	s_waitcnt vmcnt(1)
	v_pk_fma_f32 v[136:137], v[72:73], v[136:137], v[142:143]
	v_pk_fma_f32 v[134:135], v[70:71], v[134:135], v[140:141]
	s_waitcnt vmcnt(0)
	v_pk_fma_f32 v[132:133], v[68:69], v[132:133], v[150:151]
	v_pk_fma_f32 v[130:131], v[66:67], v[130:131], v[148:149]
	v_bfe_u32 v142, v130, 16, 1
	v_bfe_u32 v148, v132, 16, 1
	v_bfe_u32 v143, v131, 16, 1
	v_bfe_u32 v149, v133, 16, 1
	v_add3_u32 v130, v130, v142, s66
	v_add3_u32 v132, v132, v148, s66
	v_add3_u32 v131, v131, v143, s66
	v_add3_u32 v133, v133, v149, s66
	v_lshrrev_b32_e32 v140, 16, v130
	v_lshrrev_b32_e32 v141, 16, v132
	v_cvt_pk_bf16_f32 v130, v134, v135
	v_and_or_b32 v132, v131, s67, v140
	v_cvt_pk_bf16_f32 v131, v136, v137
	v_and_or_b32 v133, v133, s67, v141
	v_permlane16_swap_b32_e32 v130, v132
	s_nop 0
	v_permlane16_swap_b32_e32 v131, v133

.LBB0_1084:
	s_add_i32 s47, s3, 1
	s_cmp_gt_u32 s3, 1
	s_mov_b64 s[30:31], -1
	buffer_inv sc1
	s_cbranch_scc0 .LBB0_1086
	s_and_b32 s31, s47, 3
	s_lshl_b32 s30, s72, 2
	s_or_b32 s31, s31, s30
	s_mul_i32 s31, s31, 0x18000
	s_add_i32 s31, s31, s45
	s_add_i32 s49, s31, 0x10000
	buffer_load_dwordx4 v[138:141], v193, s[8:11], s49 offen
	s_add_i32 s49, s31, 0x10400
	buffer_load_dwordx4 v[142:145], v193, s[8:11], s49 offen
	s_add_i32 s49, s31, 0x10800
	buffer_load_dwordx4 v[146:149], v193, s[8:11], s49 offen
	s_add_i32 s49, s31, 0x10c00
	buffer_load_dwordx4 v[150:153], v193, s[8:11], s49 offen
	s_add_i32 s49, s31, 0x11000
	buffer_load_dwordx4 v[154:157], v193, s[8:11], s49 offen
	s_add_i32 s49, s31, 0x11400
	buffer_load_dwordx4 v[158:161], v193, s[8:11], s49 offen
	s_add_i32 s49, s31, 0x11800
	s_add_i32 s31, s31, 0x11c00
	buffer_load_dwordx4 v[134:137], v193, s[8:11], s49 offen
	buffer_load_dwordx4 v[130:133], v193, s[8:11], s31 offen
	s_or_b32 s31, s3, s30
	s_xor_b32 s31, s31, 2
	s_mul_i32 s31, s31, 0x18000
	s_add_i32 s31, s31, s45
	s_add_i32 s49, s31, 0x8000
	s_waitcnt vmcnt(7)
	v_cvt_f32_f16_e32 v164, v140
	v_cvt_f32_f16_sdwa v165, v140 dst_sel:DWORD dst_unused:UNUSED_PAD src0_sel:WORD_1
	v_cvt_f32_f16_e32 v140, v141
	v_cvt_f32_f16_sdwa v141, v141 dst_sel:DWORD dst_unused:UNUSED_PAD src0_sel:WORD_1
	s_waitcnt vmcnt(6)
	v_cvt_f32_f16_e32 v198, v142
	v_cvt_f32_f16_sdwa v199, v142 dst_sel:DWORD dst_unused:UNUSED_PAD src0_sel:WORD_1
	v_cvt_f32_f16_e32 v142, v143
	v_cvt_f32_f16_sdwa v143, v143 dst_sel:DWORD dst_unused:UNUSED_PAD src0_sel:WORD_1
	v_cvt_f32_f16_e32 v210, v144
	v_cvt_f32_f16_sdwa v211, v144 dst_sel:DWORD dst_unused:UNUSED_PAD src0_sel:WORD_1
	v_cvt_f32_f16_e32 v144, v145
	v_cvt_f32_f16_sdwa v145, v145 dst_sel:DWORD dst_unused:UNUSED_PAD src0_sel:WORD_1
	s_waitcnt vmcnt(5)
	v_cvt_f32_f16_e32 v212, v146
	v_cvt_f32_f16_sdwa v213, v146 dst_sel:DWORD dst_unused:UNUSED_PAD src0_sel:WORD_1
	v_cvt_f32_f16_e32 v146, v147
	v_cvt_f32_f16_sdwa v147, v147 dst_sel:DWORD dst_unused:UNUSED_PAD src0_sel:WORD_1
	v_cvt_f32_f16_e32 v214, v148
	v_cvt_f32_f16_sdwa v215, v148 dst_sel:DWORD dst_unused:UNUSED_PAD src0_sel:WORD_1
	v_cvt_f32_f16_e32 v148, v149
	v_cvt_f32_f16_sdwa v149, v149 dst_sel:DWORD dst_unused:UNUSED_PAD src0_sel:WORD_1
	s_waitcnt vmcnt(4)
	v_cvt_f32_f16_e32 v216, v150
	v_cvt_f32_f16_sdwa v217, v150 dst_sel:DWORD dst_unused:UNUSED_PAD src0_sel:WORD_1
	v_cvt_f32_f16_e32 v150, v151
	v_cvt_f32_f16_sdwa v151, v151 dst_sel:DWORD dst_unused:UNUSED_PAD src0_sel:WORD_1
	v_cvt_f32_f16_e32 v218, v152
	v_cvt_f32_f16_sdwa v219, v152 dst_sel:DWORD dst_unused:UNUSED_PAD src0_sel:WORD_1
	v_cvt_f32_f16_e32 v152, v153
	v_cvt_f32_f16_sdwa v153, v153 dst_sel:DWORD dst_unused:UNUSED_PAD src0_sel:WORD_1
	s_waitcnt vmcnt(3)
	v_cvt_f32_f16_e32 v220, v154
	v_cvt_f32_f16_sdwa v221, v154 dst_sel:DWORD dst_unused:UNUSED_PAD src0_sel:WORD_1
	v_cvt_f32_f16_e32 v154, v155
	v_cvt_f32_f16_sdwa v155, v155 dst_sel:DWORD dst_unused:UNUSED_PAD src0_sel:WORD_1
	v_cvt_f32_f16_e32 v222, v156
	v_cvt_f32_f16_sdwa v223, v156 dst_sel:DWORD dst_unused:UNUSED_PAD src0_sel:WORD_1
	v_cvt_f32_f16_e32 v156, v157
	v_cvt_f32_f16_sdwa v157, v157 dst_sel:DWORD dst_unused:UNUSED_PAD src0_sel:WORD_1
	v_cvt_f32_f16_e32 v162, v138
	v_cvt_f32_f16_sdwa v163, v138 dst_sel:DWORD dst_unused:UNUSED_PAD src0_sel:WORD_1
	v_cvt_f32_f16_e32 v138, v139
	v_cvt_f32_f16_sdwa v139, v139 dst_sel:DWORD dst_unused:UNUSED_PAD src0_sel:WORD_1
	v_pk_add_f32 v[124:125], v[124:125], v[140:141]
	v_pk_add_f32 v[120:121], v[120:121], v[142:143]
	v_pk_add_f32 v[140:141], v[116:117], v[144:145]
	v_pk_add_f32 v[144:145], v[112:113], v[146:147]
	v_pk_add_f32 v[142:143], v[110:111], v[212:213]
	v_pk_add_f32 v[148:149], v[108:109], v[148:149]
	v_pk_add_f32 v[146:147], v[106:107], v[214:215]
	v_pk_add_f32 v[112:113], v[104:105], v[150:151]
	v_pk_add_f32 v[110:111], v[102:103], v[216:217]
	v_pk_add_f32 v[108:109], v[100:101], v[152:153]
	v_pk_add_f32 v[106:107], v[98:99], v[218:219]
	v_pk_add_f32 v[100:101], v[96:97], v[154:155]
	v_pk_add_f32 v[98:99], v[94:95], v[220:221]
	v_pk_add_f32 v[104:105], v[92:93], v[156:157]
	v_pk_add_f32 v[102:103], v[90:91], v[222:223]
	s_waitcnt vmcnt(1)
	v_cvt_f32_f16_e32 v90, v134
	v_cvt_f32_f16_sdwa v91, v134 dst_sel:DWORD dst_unused:UNUSED_PAD src0_sel:WORD_1
	v_cvt_f32_f16_e32 v92, v135
	v_cvt_f32_f16_sdwa v93, v135 dst_sel:DWORD dst_unused:UNUSED_PAD src0_sel:WORD_1
	v_cvt_f32_f16_e32 v94, v136
	v_cvt_f32_f16_e32 v96, v137
	v_cvt_f32_f16_sdwa v97, v137 dst_sel:DWORD dst_unused:UNUSED_PAD src0_sel:WORD_1
	v_cvt_f32_f16_sdwa v95, v136 dst_sel:DWORD dst_unused:UNUSED_PAD src0_sel:WORD_1
	v_pk_add_f32 v[128:129], v[128:129], v[138:139]
	v_pk_add_f32 v[126:127], v[126:127], v[162:163]
	v_pk_add_f32 v[122:123], v[122:123], v[164:165]
	v_cvt_f32_f16_e32 v224, v158
	v_cvt_f32_f16_sdwa v225, v158 dst_sel:DWORD dst_unused:UNUSED_PAD src0_sel:WORD_1
	v_cvt_f32_f16_e32 v158, v159
	v_cvt_f32_f16_sdwa v159, v159 dst_sel:DWORD dst_unused:UNUSED_PAD src0_sel:WORD_1
	v_cvt_f32_f16_e32 v226, v160
	v_cvt_f32_f16_sdwa v227, v160 dst_sel:DWORD dst_unused:UNUSED_PAD src0_sel:WORD_1
	v_cvt_f32_f16_e32 v160, v161
	v_cvt_f32_f16_sdwa v161, v161 dst_sel:DWORD dst_unused:UNUSED_PAD src0_sel:WORD_1
	v_pk_add_f32 v[118:119], v[118:119], v[198:199]
	v_pk_add_f32 v[138:139], v[114:115], v[210:211]
	v_pk_add_f32 v[80:81], v[80:81], v[92:93]
	v_pk_add_f32 v[78:79], v[78:79], v[90:91]
	v_pk_add_f32 v[76:77], v[76:77], v[96:97]
	v_pk_add_f32 v[74:75], v[74:75], v[94:95]
	s_waitcnt vmcnt(0)
	v_cvt_f32_f16_e32 v90, v130
	v_cvt_f32_f16_sdwa v91, v130 dst_sel:DWORD dst_unused:UNUSED_PAD src0_sel:WORD_1
	v_cvt_f32_f16_e32 v92, v131
	v_cvt_f32_f16_sdwa v93, v131 dst_sel:DWORD dst_unused:UNUSED_PAD src0_sel:WORD_1
	v_cvt_f32_f16_e32 v94, v132
	v_cvt_f32_f16_e32 v96, v133
	v_cvt_f32_f16_sdwa v97, v133 dst_sel:DWORD dst_unused:UNUSED_PAD src0_sel:WORD_1
	v_cvt_f32_f16_sdwa v95, v132 dst_sel:DWORD dst_unused:UNUSED_PAD src0_sel:WORD_1
	v_pk_add_f32 v[88:89], v[88:89], v[158:159]
	v_pk_add_f32 v[86:87], v[86:87], v[224:225]
	v_pk_add_f32 v[84:85], v[84:85], v[160:161]
	v_pk_add_f32 v[82:83], v[82:83], v[226:227]
	v_pk_add_f32 v[72:73], v[72:73], v[92:93]
	v_pk_add_f32 v[70:71], v[70:71], v[90:91]
	v_pk_add_f32 v[68:69], v[68:69], v[96:97]
	v_pk_add_f32 v[66:67], v[66:67], v[94:95]
	s_nop 0
	buffer_load_dwordx4 v[90:93], v193, s[8:11], s49 offen
	s_add_i32 s49, s31, 0x8400
	buffer_load_dwordx4 v[94:97], v193, s[8:11], s49 offen
	s_add_i32 s49, s31, 0x8800
	buffer_load_dwordx4 v[134:137], v193, s[8:11], s49 offen
	s_add_i32 s49, s31, 0x8c00
	buffer_load_dwordx4 v[154:157], v193, s[8:11], s49 offen
	s_add_i32 s49, s31, 0x9000
	buffer_load_dwordx4 v[210:213], v193, s[8:11], s49 offen
	s_add_i32 s49, s31, 0x9400
	buffer_load_dwordx4 v[214:217], v193, s[8:11], s49 offen
	s_add_i32 s49, s31, 0x9800
	s_add_i32 s31, s31, 0x9c00
	buffer_load_dwordx4 v[130:133], v193, s[8:11], s49 offen
	buffer_load_dwordx4 v[114:117], v193, s[8:11], s31 offen
	s_add_i32 s31, s3, -1
	s_and_b32 s31, s31, 3
	s_or_b32 s30, s31, s30
	s_mul_i32 s30, s30, 0x18000
	s_add_i32 s30, s45, s30
	s_or_b32 s31, s30, 0x400
	s_waitcnt vmcnt(7)
	v_cvt_f32_f16_e32 v150, v90
	v_cvt_f32_f16_sdwa v151, v90 dst_sel:DWORD dst_unused:UNUSED_PAD src0_sel:WORD_1
	v_cvt_f32_f16_e32 v90, v91
	v_cvt_f32_f16_sdwa v91, v91 dst_sel:DWORD dst_unused:UNUSED_PAD src0_sel:WORD_1
	v_cvt_f32_f16_e32 v152, v92
	v_cvt_f32_f16_sdwa v153, v92 dst_sel:DWORD dst_unused:UNUSED_PAD src0_sel:WORD_1
	s_waitcnt vmcnt(6)
	v_cvt_f32_f16_e32 v198, v94
	v_cvt_f32_f16_sdwa v199, v94 dst_sel:DWORD dst_unused:UNUSED_PAD src0_sel:WORD_1
	v_cvt_f32_f16_e32 v94, v95
	v_cvt_f32_f16_sdwa v95, v95 dst_sel:DWORD dst_unused:UNUSED_PAD src0_sel:WORD_1
	v_cvt_f32_f16_e32 v218, v96
	v_cvt_f32_f16_sdwa v219, v96 dst_sel:DWORD dst_unused:UNUSED_PAD src0_sel:WORD_1
	v_cvt_f32_f16_e32 v96, v97
	v_cvt_f32_f16_sdwa v97, v97 dst_sel:DWORD dst_unused:UNUSED_PAD src0_sel:WORD_1
	v_cvt_f32_f16_e32 v92, v93
	v_cvt_f32_f16_sdwa v93, v93 dst_sel:DWORD dst_unused:UNUSED_PAD src0_sel:WORD_1
	s_waitcnt vmcnt(4)
	v_cvt_f32_f16_e32 v224, v154
	v_cvt_f32_f16_sdwa v225, v154 dst_sel:DWORD dst_unused:UNUSED_PAD src0_sel:WORD_1
	v_pk_add_f32 v[164:165], v[128:129], v[90:91]
	v_pk_add_f32 v[158:159], v[122:123], v[152:153]
	v_pk_add_f32 v[152:153], v[120:121], v[94:95]
	v_pk_add_f32 v[120:121], v[140:141], v[96:97]
	v_cvt_f32_f16_e32 v90, v155
	v_cvt_f32_f16_sdwa v91, v155 dst_sel:DWORD dst_unused:UNUSED_PAD src0_sel:WORD_1
	v_cvt_f32_f16_e32 v94, v156
	v_cvt_f32_f16_e32 v96, v157
	v_cvt_f32_f16_sdwa v97, v157 dst_sel:DWORD dst_unused:UNUSED_PAD src0_sel:WORD_1
	v_cvt_f32_f16_sdwa v95, v156 dst_sel:DWORD dst_unused:UNUSED_PAD src0_sel:WORD_1
	v_pk_add_f32 v[160:161], v[124:125], v[92:93]
	v_pk_add_f32 v[92:93], v[112:113], v[90:91]
	v_pk_add_f32 v[90:91], v[110:111], v[224:225]
	v_pk_add_f32 v[96:97], v[108:109], v[96:97]
	v_pk_add_f32 v[94:95], v[106:107], v[94:95]
	s_waitcnt vmcnt(3)
	v_cvt_f32_f16_e32 v106, v210
	v_cvt_f32_f16_sdwa v107, v210 dst_sel:DWORD dst_unused:UNUSED_PAD src0_sel:WORD_1
	v_cvt_f32_f16_e32 v108, v211
	v_cvt_f32_f16_sdwa v109, v211 dst_sel:DWORD dst_unused:UNUSED_PAD src0_sel:WORD_1
	v_cvt_f32_f16_e32 v110, v212
	v_cvt_f32_f16_e32 v112, v213
	v_cvt_f32_f16_sdwa v113, v213 dst_sel:DWORD dst_unused:UNUSED_PAD src0_sel:WORD_1
	v_cvt_f32_f16_sdwa v111, v212 dst_sel:DWORD dst_unused:UNUSED_PAD src0_sel:WORD_1
	v_pk_add_f32 v[100:101], v[100:101], v[108:109]
	v_pk_add_f32 v[98:99], v[98:99], v[106:107]
	v_pk_add_f32 v[104:105], v[104:105], v[112:113]
	v_pk_add_f32 v[102:103], v[102:103], v[110:111]
	s_waitcnt vmcnt(2)
	v_cvt_f32_f16_e32 v106, v214
	v_cvt_f32_f16_sdwa v107, v214 dst_sel:DWORD dst_unused:UNUSED_PAD src0_sel:WORD_1
	v_cvt_f32_f16_e32 v108, v215
	v_cvt_f32_f16_sdwa v109, v215 dst_sel:DWORD dst_unused:UNUSED_PAD src0_sel:WORD_1
	v_cvt_f32_f16_e32 v110, v216
	v_cvt_f32_f16_e32 v112, v217
	v_cvt_f32_f16_sdwa v113, v217 dst_sel:DWORD dst_unused:UNUSED_PAD src0_sel:WORD_1
	v_cvt_f32_f16_sdwa v111, v216 dst_sel:DWORD dst_unused:UNUSED_PAD src0_sel:WORD_1
	v_cvt_f32_f16_e32 v220, v134
	v_cvt_f32_f16_sdwa v221, v134 dst_sel:DWORD dst_unused:UNUSED_PAD src0_sel:WORD_1
	v_cvt_f32_f16_e32 v134, v135
	v_cvt_f32_f16_sdwa v135, v135 dst_sel:DWORD dst_unused:UNUSED_PAD src0_sel:WORD_1
	v_cvt_f32_f16_e32 v222, v136
	v_cvt_f32_f16_sdwa v223, v136 dst_sel:DWORD dst_unused:UNUSED_PAD src0_sel:WORD_1
	v_cvt_f32_f16_e32 v136, v137
	v_cvt_f32_f16_sdwa v137, v137 dst_sel:DWORD dst_unused:UNUSED_PAD src0_sel:WORD_1
	v_pk_add_f32 v[108:109], v[88:89], v[108:109]
	v_pk_add_f32 v[106:107], v[86:87], v[106:107]
	v_pk_add_f32 v[112:113], v[84:85], v[112:113]
	v_pk_add_f32 v[110:111], v[82:83], v[110:111]
	s_waitcnt vmcnt(1)
	v_cvt_f32_f16_e32 v82, v130
	v_cvt_f32_f16_sdwa v83, v130 dst_sel:DWORD dst_unused:UNUSED_PAD src0_sel:WORD_1
	v_cvt_f32_f16_e32 v84, v131
	v_cvt_f32_f16_sdwa v85, v131 dst_sel:DWORD dst_unused:UNUSED_PAD src0_sel:WORD_1
	v_cvt_f32_f16_e32 v86, v132
	v_cvt_f32_f16_e32 v88, v133
	v_cvt_f32_f16_sdwa v89, v133 dst_sel:DWORD dst_unused:UNUSED_PAD src0_sel:WORD_1
	v_cvt_f32_f16_sdwa v87, v132 dst_sel:DWORD dst_unused:UNUSED_PAD src0_sel:WORD_1
	v_pk_add_f32 v[162:163], v[126:127], v[150:151]
	v_pk_add_f32 v[150:151], v[118:119], v[198:199]
	v_pk_add_f32 v[118:119], v[138:139], v[218:219]
	v_pk_add_f32 v[128:129], v[144:145], v[134:135]
	v_pk_add_f32 v[126:127], v[142:143], v[220:221]
	v_pk_add_f32 v[124:125], v[148:149], v[136:137]
	v_pk_add_f32 v[122:123], v[146:147], v[222:223]
	v_pk_add_f32 v[80:81], v[80:81], v[84:85]
	v_pk_add_f32 v[78:79], v[78:79], v[82:83]
	v_pk_add_f32 v[76:77], v[76:77], v[88:89]
	v_pk_add_f32 v[74:75], v[74:75], v[86:87]
	s_waitcnt vmcnt(0)
	v_cvt_f32_f16_e32 v82, v114
	v_cvt_f32_f16_sdwa v83, v114 dst_sel:DWORD dst_unused:UNUSED_PAD src0_sel:WORD_1
	v_cvt_f32_f16_e32 v84, v115
	v_cvt_f32_f16_sdwa v85, v115 dst_sel:DWORD dst_unused:UNUSED_PAD src0_sel:WORD_1
	v_cvt_f32_f16_e32 v86, v116
	v_cvt_f32_f16_e32 v88, v117
	v_cvt_f32_f16_sdwa v89, v117 dst_sel:DWORD dst_unused:UNUSED_PAD src0_sel:WORD_1
	v_cvt_f32_f16_sdwa v87, v116 dst_sel:DWORD dst_unused:UNUSED_PAD src0_sel:WORD_1
	v_pk_add_f32 v[136:137], v[72:73], v[84:85]
	v_pk_add_f32 v[134:135], v[70:71], v[82:83]
	v_pk_add_f32 v[140:141], v[68:69], v[88:89]
	v_pk_add_f32 v[138:139], v[66:67], v[86:87]
	s_nop 0
	buffer_load_dwordx4 v[66:69], v193, s[8:11], s30 offen
	buffer_load_dwordx4 v[70:73], v193, s[8:11], s31 offen
	s_or_b32 s31, s30, 0x800
	buffer_load_dwordx4 v[82:85], v193, s[8:11], s31 offen
	s_or_b32 s31, s30, 0xc00
	buffer_load_dwordx4 v[210:213], v193, s[8:11], s31 offen
	s_or_b32 s31, s30, 0x1000
	buffer_load_dwordx4 v[214:217], v193, s[8:11], s31 offen
	s_or_b32 s31, s30, 0x1400
	buffer_load_dwordx4 v[218:221], v193, s[8:11], s31 offen
	s_or_b32 s31, s30, 0x1800
	s_or_b32 s30, s30, 0x1c00
	buffer_load_dwordx4 v[154:157], v193, s[8:11], s31 offen
	buffer_load_dwordx4 v[146:149], v193, s[8:11], s30 offen
	s_mov_b64 s[30:31], 0
	s_waitcnt vmcnt(7)
	v_cvt_f32_f16_e32 v86, v66
	v_cvt_f32_f16_sdwa v87, v66 dst_sel:DWORD dst_unused:UNUSED_PAD src0_sel:WORD_1
	v_cvt_f32_f16_e32 v66, v67
	v_cvt_f32_f16_sdwa v67, v67 dst_sel:DWORD dst_unused:UNUSED_PAD src0_sel:WORD_1
	v_cvt_f32_f16_e32 v88, v68
	v_cvt_f32_f16_e32 v114, v69
	v_cvt_f32_f16_sdwa v115, v69 dst_sel:DWORD dst_unused:UNUSED_PAD src0_sel:WORD_1
	v_cvt_f32_f16_sdwa v89, v68 dst_sel:DWORD dst_unused:UNUSED_PAD src0_sel:WORD_1
	s_waitcnt vmcnt(6)
	v_cvt_f32_f16_e32 v68, v71
	v_cvt_f32_f16_sdwa v69, v71 dst_sel:DWORD dst_unused:UNUSED_PAD src0_sel:WORD_1
	v_pk_add_f32 v[144:145], v[164:165], v[66:67]
	v_cvt_f32_f16_e32 v66, v70
	v_cvt_f32_f16_sdwa v67, v70 dst_sel:DWORD dst_unused:UNUSED_PAD src0_sel:WORD_1
	v_cvt_f32_f16_e32 v70, v72
	v_cvt_f32_f16_sdwa v71, v72 dst_sel:DWORD dst_unused:UNUSED_PAD src0_sel:WORD_1
	v_pk_add_f32 v[116:117], v[152:153], v[68:69]
	s_waitcnt vmcnt(5)
	v_cvt_f32_f16_e32 v68, v83
	v_cvt_f32_f16_sdwa v69, v83 dst_sel:DWORD dst_unused:UNUSED_PAD src0_sel:WORD_1
	v_pk_add_f32 v[142:143], v[162:163], v[86:87]
	v_pk_add_f32 v[132:133], v[160:161], v[114:115]
	v_cvt_f32_f16_e32 v86, v73
	v_cvt_f32_f16_sdwa v87, v73 dst_sel:DWORD dst_unused:UNUSED_PAD src0_sel:WORD_1
	v_pk_add_f32 v[114:115], v[150:151], v[66:67]
	v_pk_add_f32 v[118:119], v[118:119], v[70:71]
	v_cvt_f32_f16_e32 v66, v82
	v_cvt_f32_f16_sdwa v67, v82 dst_sel:DWORD dst_unused:UNUSED_PAD src0_sel:WORD_1
	v_cvt_f32_f16_e32 v70, v84
	v_cvt_f32_f16_e32 v72, v85
	v_cvt_f32_f16_sdwa v73, v85 dst_sel:DWORD dst_unused:UNUSED_PAD src0_sel:WORD_1
	v_cvt_f32_f16_sdwa v71, v84 dst_sel:DWORD dst_unused:UNUSED_PAD src0_sel:WORD_1
	v_pk_add_f32 v[84:85], v[128:129], v[68:69]
	s_waitcnt vmcnt(4)
	v_cvt_f32_f16_e32 v68, v211
	v_cvt_f32_f16_sdwa v69, v211 dst_sel:DWORD dst_unused:UNUSED_PAD src0_sel:WORD_1
	v_pk_add_f32 v[130:131], v[158:159], v[88:89]
	v_pk_add_f32 v[120:121], v[120:121], v[86:87]
	v_pk_add_f32 v[82:83], v[126:127], v[66:67]
	v_pk_add_f32 v[88:89], v[124:125], v[72:73]
	v_pk_add_f32 v[86:87], v[122:123], v[70:71]
	v_cvt_f32_f16_e32 v66, v210
	v_cvt_f32_f16_sdwa v67, v210 dst_sel:DWORD dst_unused:UNUSED_PAD src0_sel:WORD_1
	v_cvt_f32_f16_e32 v70, v212
	v_cvt_f32_f16_e32 v72, v213
	v_cvt_f32_f16_sdwa v73, v213 dst_sel:DWORD dst_unused:UNUSED_PAD src0_sel:WORD_1
	v_cvt_f32_f16_sdwa v71, v212 dst_sel:DWORD dst_unused:UNUSED_PAD src0_sel:WORD_1
	v_pk_add_f32 v[68:69], v[92:93], v[68:69]
	s_waitcnt vmcnt(3)
	v_cvt_f32_f16_e32 v92, v215
	v_cvt_f32_f16_sdwa v93, v215 dst_sel:DWORD dst_unused:UNUSED_PAD src0_sel:WORD_1
	v_pk_add_f32 v[66:67], v[90:91], v[66:67]
	v_pk_add_f32 v[72:73], v[96:97], v[72:73]
	v_pk_add_f32 v[70:71], v[94:95], v[70:71]
	v_cvt_f32_f16_e32 v90, v214
	v_cvt_f32_f16_sdwa v91, v214 dst_sel:DWORD dst_unused:UNUSED_PAD src0_sel:WORD_1
	v_cvt_f32_f16_e32 v94, v216
	v_cvt_f32_f16_e32 v96, v217
	v_cvt_f32_f16_sdwa v97, v217 dst_sel:DWORD dst_unused:UNUSED_PAD src0_sel:WORD_1
	v_cvt_f32_f16_sdwa v95, v216 dst_sel:DWORD dst_unused:UNUSED_PAD src0_sel:WORD_1
	v_pk_add_f32 v[152:153], v[100:101], v[92:93]
	s_waitcnt vmcnt(2)
	v_cvt_f32_f16_e32 v92, v219
	v_cvt_f32_f16_sdwa v93, v219 dst_sel:DWORD dst_unused:UNUSED_PAD src0_sel:WORD_1
	v_pk_add_f32 v[150:151], v[98:99], v[90:91]
	v_pk_add_f32 v[160:161], v[104:105], v[96:97]
	v_pk_add_f32 v[158:159], v[102:103], v[94:95]
	v_cvt_f32_f16_e32 v90, v218
	v_cvt_f32_f16_sdwa v91, v218 dst_sel:DWORD dst_unused:UNUSED_PAD src0_sel:WORD_1
	v_cvt_f32_f16_e32 v94, v220
	v_cvt_f32_f16_e32 v96, v221
	v_cvt_f32_f16_sdwa v97, v221 dst_sel:DWORD dst_unused:UNUSED_PAD src0_sel:WORD_1
	v_cvt_f32_f16_sdwa v95, v220 dst_sel:DWORD dst_unused:UNUSED_PAD src0_sel:WORD_1
	v_pk_add_f32 v[124:125], v[108:109], v[92:93]
	s_waitcnt vmcnt(1)
	v_cvt_f32_f16_e32 v92, v155
	v_cvt_f32_f16_sdwa v93, v155 dst_sel:DWORD dst_unused:UNUSED_PAD src0_sel:WORD_1
	v_pk_add_f32 v[122:123], v[106:107], v[90:91]
	v_pk_add_f32 v[128:129], v[112:113], v[96:97]
	v_pk_add_f32 v[126:127], v[110:111], v[94:95]
	v_cvt_f32_f16_e32 v90, v154
	v_cvt_f32_f16_sdwa v91, v154 dst_sel:DWORD dst_unused:UNUSED_PAD src0_sel:WORD_1
	v_cvt_f32_f16_e32 v94, v156
	v_cvt_f32_f16_e32 v96, v157
	v_cvt_f32_f16_sdwa v97, v157 dst_sel:DWORD dst_unused:UNUSED_PAD src0_sel:WORD_1
	v_cvt_f32_f16_sdwa v95, v156 dst_sel:DWORD dst_unused:UNUSED_PAD src0_sel:WORD_1
	v_pk_add_f32 v[104:105], v[80:81], v[92:93]
	s_waitcnt vmcnt(0)
	v_cvt_f32_f16_e32 v80, v149
	v_cvt_f32_f16_sdwa v81, v149 dst_sel:DWORD dst_unused:UNUSED_PAD src0_sel:WORD_1
	v_pk_add_f32 v[102:103], v[78:79], v[90:91]
	v_pk_add_f32 v[112:113], v[76:77], v[96:97]
	v_pk_add_f32 v[110:111], v[74:75], v[94:95]
	v_cvt_f32_f16_e32 v74, v146
	v_cvt_f32_f16_sdwa v75, v146 dst_sel:DWORD dst_unused:UNUSED_PAD src0_sel:WORD_1
	v_cvt_f32_f16_e32 v76, v147
	v_cvt_f32_f16_sdwa v77, v147 dst_sel:DWORD dst_unused:UNUSED_PAD src0_sel:WORD_1
	v_cvt_f32_f16_e32 v78, v148
	v_cvt_f32_f16_sdwa v79, v148 dst_sel:DWORD dst_unused:UNUSED_PAD src0_sel:WORD_1
	v_pk_add_f32 v[80:81], v[140:141], v[80:81]
	v_add_u32_e32 v140, 0x80, v192
	v_ashrrev_i32_e32 v141, 31, v140
	v_pk_add_f32 v[76:77], v[136:137], v[76:77]
	v_pk_add_f32 v[74:75], v[134:135], v[74:75]
	v_pk_add_f32 v[78:79], v[138:139], v[78:79]
	v_lshl_add_u64 v[134:135], v[196:197], 2, s[12:13]
	v_lshlrev_b64 v[90:91], 12, v[140:141]
	v_lshl_add_u64 v[148:149], v[134:135], 0, v[90:91]
	global_load_dwordx4 v[136:139], v[148:149], off
	global_load_dwordx4 v[106:109], v[194:195], off
	global_load_dwordx4 v[98:101], v[194:195], off offset:64
	global_load_dwordx4 v[154:157], v[148:149], off offset:64
	global_load_dwordx4 v[94:97], v[194:195], off offset:512
	global_load_dwordx4 v[90:93], v[194:195], off offset:576
	v_and_b32_e32 v146, 1, v1
	v_add_u32_e32 v147, 12, v209
	v_cmp_eq_u32_e32 vcc, 0, v146
	s_waitcnt vmcnt(4)
	v_pk_fma_f32 v[136:137], v[142:143], v[106:107], v[136:137]
	v_pk_fma_f32 v[144:145], v[144:145], v[108:109], v[138:139]
	s_waitcnt vmcnt(2)
	v_pk_fma_f32 v[130:131], v[130:131], v[98:99], v[154:155]
	v_cvt_pk_bf16_f32 v136, v136, v137
	v_cvt_pk_bf16_f32 v138, v130, v131
	v_pk_fma_f32 v[132:133], v[132:133], v[100:101], v[156:157]
	v_cvt_pk_bf16_f32 v137, v144, v145
	v_cndmask_b32_e32 v146, v147, v209, vcc
	v_add_u32_e32 v146, v146, v208
	v_ashrrev_i32_e32 v147, 31, v146
	v_cvt_pk_bf16_f32 v139, v132, v133
	v_lshlrev_b64 v[130:131], 11, v[140:141]
	v_lshl_add_u64 v[132:133], v[176:177], 0, v[130:131]
	v_lshlrev_b64 v[130:131], 1, v[146:147]
	v_permlane16_swap_b32_e32 v136, v138
	v_permlane16_swap_b32_e32 v137, v139
	v_lshl_add_u64 v[132:133], v[132:133], 0, v[130:131]
	global_store_dwordx4 v[132:133], v[136:139], off
	global_load_dwordx4 v[136:139], v[148:149], off offset:512
	s_nop 0
	global_load_dwordx4 v[140:143], v[148:149], off offset:576
	s_waitcnt vmcnt(1)
	v_pk_fma_f32 v[138:139], v[152:153], v[96:97], v[138:139]
	v_pk_fma_f32 v[136:137], v[150:151], v[94:95], v[136:137]
	s_waitcnt vmcnt(0)
	v_pk_fma_f32 v[142:143], v[160:161], v[92:93], v[142:143]
	v_pk_fma_f32 v[140:141], v[158:159], v[90:91], v[140:141]
	v_cvt_pk_bf16_f32 v136, v136, v137
	v_cvt_pk_bf16_f32 v137, v138, v139
	v_cvt_pk_bf16_f32 v138, v140, v141
	v_cvt_pk_bf16_f32 v139, v142, v143
	s_nop 0
	v_permlane16_swap_b32_e32 v136, v138
	v_permlane16_swap_b32_e32 v137, v139
	global_store_dwordx4 v[132:133], v[136:139], off offset:256
	v_add_u32_e32 v132, 0x90, v192
	v_ashrrev_i32_e32 v133, 31, v132
	v_lshlrev_b64 v[136:137], 12, v[132:133]
	v_lshl_add_u64 v[144:145], v[134:135], 0, v[136:137]
	global_load_dwordx4 v[136:139], v[144:145], off
	global_load_dwordx4 v[140:143], v[144:145], off offset:64
	v_lshlrev_b64 v[132:133], 11, v[132:133]
	v_lshl_add_u64 v[132:133], v[176:177], 0, v[132:133]
	v_lshl_add_u64 v[132:133], v[132:133], 0, v[130:131]
	s_waitcnt vmcnt(1)
	v_pk_fma_f32 v[116:117], v[116:117], v[108:109], v[138:139]
	v_pk_fma_f32 v[114:115], v[114:115], v[106:107], v[136:137]
	s_waitcnt vmcnt(0)
	v_pk_fma_f32 v[120:121], v[120:121], v[100:101], v[142:143]
	v_pk_fma_f32 v[118:119], v[118:119], v[98:99], v[140:141]
	v_bfe_u32 v140, v116, 16, 1
	v_bfe_u32 v141, v117, 16, 1
	v_add3_u32 v116, v116, v140, s66
	v_add3_u32 v117, v117, v141, s66
	v_lshrrev_b32_e32 v136, 16, v116
	v_cvt_pk_bf16_f32 v114, v114, v115
	v_cvt_pk_bf16_f32 v116, v118, v119
	v_and_or_b32 v115, v117, s67, v136
	v_cvt_pk_bf16_f32 v117, v120, v121
	v_permlane16_swap_b32_e32 v114, v116
	s_nop 0
	v_permlane16_swap_b32_e32 v115, v117
	global_store_dwordx4 v[132:133], v[114:117], off
	global_load_dwordx4 v[114:117], v[144:145], off offset:512
	s_nop 0
	global_load_dwordx4 v[118:121], v[144:145], off offset:576
	v_add_u32_e32 v136, 0xa0, v192
	v_ashrrev_i32_e32 v137, 31, v136
	v_lshlrev_b64 v[138:139], 12, v[136:137]
	v_lshl_add_u64 v[138:139], v[134:135], 0, v[138:139]
	s_waitcnt vmcnt(1)
	v_pk_fma_f32 v[116:117], v[124:125], v[96:97], v[116:117]
	v_pk_fma_f32 v[114:115], v[122:123], v[94:95], v[114:115]
	s_waitcnt vmcnt(0)
	v_pk_fma_f32 v[120:121], v[128:129], v[92:93], v[120:121]
	v_pk_fma_f32 v[118:119], v[126:127], v[90:91], v[118:119]
	v_bfe_u32 v126, v116, 16, 1
	v_bfe_u32 v127, v117, 16, 1
	v_add3_u32 v116, v116, v126, s66
	v_add3_u32 v117, v117, v127, s66
	v_lshrrev_b32_e32 v122, 16, v116
	v_cvt_pk_bf16_f32 v114, v114, v115
	v_cvt_pk_bf16_f32 v116, v118, v119
	v_and_or_b32 v115, v117, s67, v122
	v_cvt_pk_bf16_f32 v117, v120, v121
	v_permlane16_swap_b32_e32 v114, v116
	s_nop 0
	v_permlane16_swap_b32_e32 v115, v117
	global_store_dwordx4 v[132:133], v[114:117], off offset:256
	global_load_dwordx4 v[114:117], v[138:139], off
	s_nop 0
	global_load_dwordx4 v[118:121], v[138:139], off offset:64
	v_lshlrev_b64 v[122:123], 11, v[136:137]
	v_lshl_add_u64 v[122:123], v[176:177], 0, v[122:123]
	v_lshl_add_u64 v[122:123], v[122:123], 0, v[130:131]
	s_waitcnt vmcnt(1)
	v_pk_fma_f32 v[84:85], v[84:85], v[108:109], v[116:117]
	v_pk_fma_f32 v[82:83], v[82:83], v[106:107], v[114:115]
	s_waitcnt vmcnt(0)
	v_pk_fma_f32 v[88:89], v[88:89], v[100:101], v[120:121]
	v_pk_fma_f32 v[86:87], v[86:87], v[98:99], v[118:119]
	v_bfe_u32 v118, v84, 16, 1
	v_bfe_u32 v120, v88, 16, 1
	v_bfe_u32 v119, v85, 16, 1
	v_bfe_u32 v121, v89, 16, 1
	v_add3_u32 v84, v84, v118, s66
	v_add3_u32 v88, v88, v120, s66
	v_add3_u32 v85, v85, v119, s66
	v_add3_u32 v89, v89, v121, s66
	v_lshrrev_b32_e32 v114, 16, v84
	v_lshrrev_b32_e32 v88, 16, v88
	v_cvt_pk_bf16_f32 v82, v82, v83
	v_cvt_pk_bf16_f32 v84, v86, v87
	v_and_or_b32 v83, v85, s67, v114
	v_and_or_b32 v85, v89, s67, v88
	v_permlane16_swap_b32_e32 v82, v84
	s_nop 0
	v_permlane16_swap_b32_e32 v83, v85
	global_store_dwordx4 v[122:123], v[82:85], off
	global_load_dwordx4 v[82:85], v[138:139], off offset:512
	s_nop 0
	global_load_dwordx4 v[86:89], v[138:139], off offset:576
	v_add_u32_e32 v114, 0xb0, v192
	v_ashrrev_i32_e32 v115, 31, v114
	v_lshlrev_b64 v[116:117], 12, v[114:115]
	v_lshl_add_u64 v[116:117], v[134:135], 0, v[116:117]
	v_lshlrev_b64 v[138:139], 10, v[114:115]
	s_waitcnt vmcnt(1)
	v_pk_fma_f32 v[84:85], v[104:105], v[96:97], v[84:85]
	v_pk_fma_f32 v[82:83], v[102:103], v[94:95], v[82:83]
	s_waitcnt vmcnt(0)
	v_pk_fma_f32 v[88:89], v[112:113], v[92:93], v[88:89]
	v_pk_fma_f32 v[86:87], v[110:111], v[90:91], v[86:87]
	v_bfe_u32 v104, v86, 16, 1
	v_bfe_u32 v110, v84, 16, 1
	v_bfe_u32 v112, v88, 16, 1
	v_bfe_u32 v105, v87, 16, 1
	v_bfe_u32 v111, v85, 16, 1
	v_bfe_u32 v113, v89, 16, 1
	v_add3_u32 v86, v86, v104, s66
	v_add3_u32 v84, v84, v110, s66
	v_add3_u32 v88, v88, v112, s66
	v_add3_u32 v87, v87, v105, s66
	v_add3_u32 v85, v85, v111, s66
	v_add3_u32 v89, v89, v113, s66
	v_lshrrev_b32_e32 v86, 16, v86
	v_lshrrev_b32_e32 v102, 16, v84
	v_lshrrev_b32_e32 v88, 16, v88
	v_cvt_pk_bf16_f32 v82, v82, v83
	v_and_or_b32 v84, v87, s67, v86
	v_and_or_b32 v83, v85, s67, v102
	v_and_or_b32 v85, v89, s67, v88
	v_permlane16_swap_b32_e32 v82, v84
	s_nop 0
	v_permlane16_swap_b32_e32 v83, v85
	global_store_dwordx4 v[122:123], v[82:85], off offset:256
	global_load_dwordx4 v[82:85], v[116:117], off
	s_nop 0
	global_load_dwordx4 v[86:89], v[116:117], off offset:64
	v_lshlrev_b64 v[102:103], 11, v[114:115]
	v_lshl_add_u64 v[102:103], v[176:177], 0, v[102:103]
	v_lshl_add_u64 v[102:103], v[102:103], 0, v[130:131]
	s_waitcnt vmcnt(1)
	v_pk_fma_f32 v[68:69], v[68:69], v[108:109], v[84:85]
	v_pk_fma_f32 v[66:67], v[66:67], v[106:107], v[82:83]
	s_waitcnt vmcnt(0)
	v_pk_fma_f32 v[72:73], v[72:73], v[100:101], v[88:89]
	v_pk_fma_f32 v[70:71], v[70:71], v[98:99], v[86:87]
	v_bfe_u32 v86, v68, 16, 1
	v_bfe_u32 v87, v69, 16, 1
	v_add3_u32 v68, v68, v86, s66
	v_add3_u32 v69, v69, v87, s66
	v_lshrrev_b32_e32 v82, 16, v68
	v_cvt_pk_bf16_f32 v66, v66, v67
	v_cvt_pk_bf16_f32 v68, v70, v71
	v_and_or_b32 v67, v69, s67, v82
	v_cvt_pk_bf16_f32 v69, v72, v73
	v_permlane16_swap_b32_e32 v66, v68
	s_nop 0
	v_permlane16_swap_b32_e32 v67, v69
	global_store_dwordx4 v[102:103], v[66:69], off
	global_load_dwordx4 v[66:69], v[116:117], off offset:512
	s_nop 0
	global_load_dwordx4 v[70:73], v[116:117], off offset:576
	s_waitcnt vmcnt(1)
	v_pk_fma_f32 v[68:69], v[76:77], v[96:97], v[68:69]
	v_pk_fma_f32 v[66:67], v[74:75], v[94:95], v[66:67]
	s_waitcnt vmcnt(0)
	v_pk_fma_f32 v[72:73], v[80:81], v[92:93], v[72:73]
	v_pk_fma_f32 v[70:71], v[78:79], v[90:91], v[70:71]
	v_cvt_pk_bf16_f32 v130, v66, v67
	v_cvt_pk_bf16_f32 v132, v70, v71
	v_cvt_pk_bf16_f32 v131, v68, v69
	v_cvt_pk_bf16_f32 v133, v72, v73
	v_permlane16_swap_b32_e32 v130, v132
	s_nop 0
	v_permlane16_swap_b32_e32 v131, v133
.LBB0_1086:
	s_andn2_b64 vcc, exec, s[30:31]
	s_cbranch_vccnz .LBB0_1088
	s_lshl_b32 s30, s72, 2
	s_or_b32 s31, s47, s30
	s_mul_i32 s31, s31, 0x18000
	s_add_i32 s31, s31, s45
	s_add_i32 s47, s31, 0x10000
	buffer_load_dwordx4 v[74:77], v193, s[8:11], s47 offen
	s_add_i32 s47, s31, 0x10400
	buffer_load_dwordx4 v[78:81], v193, s[8:11], s47 offen
	s_add_i32 s47, s31, 0x10800
	buffer_load_dwordx4 v[82:85], v193, s[8:11], s47 offen
	s_add_i32 s47, s31, 0x10c00
	buffer_load_dwordx4 v[86:89], v193, s[8:11], s47 offen
	s_add_i32 s47, s31, 0x11000
	buffer_load_dwordx4 v[90:93], v193, s[8:11], s47 offen
	s_add_i32 s47, s31, 0x11400
	buffer_load_dwordx4 v[94:97], v193, s[8:11], s47 offen
	s_add_i32 s47, s31, 0x11800
	s_add_i32 s31, s31, 0x11c00
	buffer_load_dwordx4 v[70:73], v193, s[8:11], s47 offen
	buffer_load_dwordx4 v[66:69], v193, s[8:11], s31 offen
	s_or_b32 s31, s30, s3
	s_mul_i32 s31, s31, 0x18000
	s_add_i32 s31, s31, s45
	s_add_i32 s47, s31, 0x38000
	s_add_i32 s3, s3, -1
	s_and_b32 s3, s3, 3
	s_or_b32 s3, s3, s30
	s_mul_i32 s3, s3, 0x18000
	s_add_i32 s3, s45, s3
	s_or_b32 s30, s3, 0x400
	v_and_b32_e32 v1, 1, v1
	v_cmp_eq_u32_e32 vcc, 0, v1
	s_waitcnt vmcnt(7)
	v_cvt_f32_f16_e32 v100, v76
	v_cvt_f32_f16_sdwa v101, v76 dst_sel:DWORD dst_unused:UNUSED_PAD src0_sel:WORD_1
	v_cvt_f32_f16_e32 v76, v77
	v_cvt_f32_f16_sdwa v77, v77 dst_sel:DWORD dst_unused:UNUSED_PAD src0_sel:WORD_1
	s_waitcnt vmcnt(6)
	v_cvt_f32_f16_e32 v102, v78
	v_cvt_f32_f16_sdwa v103, v78 dst_sel:DWORD dst_unused:UNUSED_PAD src0_sel:WORD_1
	v_cvt_f32_f16_e32 v78, v79
	v_cvt_f32_f16_sdwa v79, v79 dst_sel:DWORD dst_unused:UNUSED_PAD src0_sel:WORD_1
	v_cvt_f32_f16_e32 v104, v80
	v_cvt_f32_f16_sdwa v105, v80 dst_sel:DWORD dst_unused:UNUSED_PAD src0_sel:WORD_1
	v_cvt_f32_f16_e32 v80, v81
	v_cvt_f32_f16_sdwa v81, v81 dst_sel:DWORD dst_unused:UNUSED_PAD src0_sel:WORD_1
	s_waitcnt vmcnt(5)
	v_cvt_f32_f16_e32 v106, v82
	v_cvt_f32_f16_sdwa v107, v82 dst_sel:DWORD dst_unused:UNUSED_PAD src0_sel:WORD_1
	v_cvt_f32_f16_e32 v82, v83
	v_cvt_f32_f16_sdwa v83, v83 dst_sel:DWORD dst_unused:UNUSED_PAD src0_sel:WORD_1
	v_cvt_f32_f16_e32 v108, v84
	v_cvt_f32_f16_sdwa v109, v84 dst_sel:DWORD dst_unused:UNUSED_PAD src0_sel:WORD_1
	v_cvt_f32_f16_e32 v84, v85
	v_cvt_f32_f16_sdwa v85, v85 dst_sel:DWORD dst_unused:UNUSED_PAD src0_sel:WORD_1
	s_waitcnt vmcnt(4)
	v_cvt_f32_f16_e32 v110, v86
	v_cvt_f32_f16_sdwa v111, v86 dst_sel:DWORD dst_unused:UNUSED_PAD src0_sel:WORD_1
	v_cvt_f32_f16_e32 v86, v87
	v_cvt_f32_f16_sdwa v87, v87 dst_sel:DWORD dst_unused:UNUSED_PAD src0_sel:WORD_1
	v_cvt_f32_f16_e32 v112, v88
	v_cvt_f32_f16_sdwa v113, v88 dst_sel:DWORD dst_unused:UNUSED_PAD src0_sel:WORD_1
	v_cvt_f32_f16_e32 v88, v89
	v_cvt_f32_f16_sdwa v89, v89 dst_sel:DWORD dst_unused:UNUSED_PAD src0_sel:WORD_1
	s_waitcnt vmcnt(3)
	v_cvt_f32_f16_e32 v114, v90
	v_cvt_f32_f16_sdwa v115, v90 dst_sel:DWORD dst_unused:UNUSED_PAD src0_sel:WORD_1
	v_cvt_f32_f16_e32 v90, v91
	v_cvt_f32_f16_sdwa v91, v91 dst_sel:DWORD dst_unused:UNUSED_PAD src0_sel:WORD_1
	v_cvt_f32_f16_e32 v116, v92
	v_cvt_f32_f16_sdwa v117, v92 dst_sel:DWORD dst_unused:UNUSED_PAD src0_sel:WORD_1
	v_cvt_f32_f16_e32 v92, v93
	v_cvt_f32_f16_sdwa v93, v93 dst_sel:DWORD dst_unused:UNUSED_PAD src0_sel:WORD_1
	v_cvt_f32_f16_e32 v98, v74
	v_cvt_f32_f16_sdwa v99, v74 dst_sel:DWORD dst_unused:UNUSED_PAD src0_sel:WORD_1
	v_cvt_f32_f16_e32 v74, v75
	v_cvt_f32_f16_sdwa v75, v75 dst_sel:DWORD dst_unused:UNUSED_PAD src0_sel:WORD_1
	v_pk_add_f32 v[60:61], v[60:61], v[76:77]
	v_pk_add_f32 v[56:57], v[56:57], v[78:79]
	v_pk_add_f32 v[76:77], v[52:53], v[80:81]
	v_pk_add_f32 v[80:81], v[48:49], v[82:83]
	v_pk_add_f32 v[78:79], v[46:47], v[106:107]
	v_pk_add_f32 v[84:85], v[44:45], v[84:85]
	v_pk_add_f32 v[82:83], v[42:43], v[108:109]
	v_pk_add_f32 v[48:49], v[40:41], v[86:87]
	v_pk_add_f32 v[46:47], v[38:39], v[110:111]
	v_pk_add_f32 v[44:45], v[36:37], v[88:89]
	v_pk_add_f32 v[42:43], v[34:35], v[112:113]
	v_pk_add_f32 v[36:37], v[32:33], v[90:91]
	v_pk_add_f32 v[34:35], v[30:31], v[114:115]
	v_pk_add_f32 v[40:41], v[28:29], v[92:93]
	v_pk_add_f32 v[38:39], v[26:27], v[116:117]
	s_waitcnt vmcnt(1)
	v_cvt_f32_f16_e32 v26, v70
	v_cvt_f32_f16_sdwa v27, v70 dst_sel:DWORD dst_unused:UNUSED_PAD src0_sel:WORD_1
	v_cvt_f32_f16_e32 v28, v71
	v_cvt_f32_f16_sdwa v29, v71 dst_sel:DWORD dst_unused:UNUSED_PAD src0_sel:WORD_1
	v_cvt_f32_f16_e32 v30, v72
	v_cvt_f32_f16_e32 v32, v73
	v_cvt_f32_f16_sdwa v33, v73 dst_sel:DWORD dst_unused:UNUSED_PAD src0_sel:WORD_1
	v_cvt_f32_f16_sdwa v31, v72 dst_sel:DWORD dst_unused:UNUSED_PAD src0_sel:WORD_1
	v_pk_add_f32 v[64:65], v[64:65], v[74:75]
	v_pk_add_f32 v[62:63], v[62:63], v[98:99]
	v_pk_add_f32 v[58:59], v[58:59], v[100:101]
	v_cvt_f32_f16_e32 v118, v94
	v_cvt_f32_f16_sdwa v119, v94 dst_sel:DWORD dst_unused:UNUSED_PAD src0_sel:WORD_1
	v_cvt_f32_f16_e32 v94, v95
	v_cvt_f32_f16_sdwa v95, v95 dst_sel:DWORD dst_unused:UNUSED_PAD src0_sel:WORD_1
	v_cvt_f32_f16_e32 v120, v96
	v_cvt_f32_f16_sdwa v121, v96 dst_sel:DWORD dst_unused:UNUSED_PAD src0_sel:WORD_1
	v_cvt_f32_f16_e32 v96, v97
	v_cvt_f32_f16_sdwa v97, v97 dst_sel:DWORD dst_unused:UNUSED_PAD src0_sel:WORD_1
	v_pk_add_f32 v[54:55], v[54:55], v[102:103]
	v_pk_add_f32 v[74:75], v[50:51], v[104:105]
	v_pk_add_f32 v[16:17], v[16:17], v[28:29]
	v_pk_add_f32 v[14:15], v[14:15], v[26:27]
	v_pk_add_f32 v[12:13], v[12:13], v[32:33]
	v_pk_add_f32 v[10:11], v[10:11], v[30:31]
	s_waitcnt vmcnt(0)
	v_cvt_f32_f16_e32 v26, v66
	v_cvt_f32_f16_sdwa v27, v66 dst_sel:DWORD dst_unused:UNUSED_PAD src0_sel:WORD_1
	v_cvt_f32_f16_e32 v28, v67
	v_cvt_f32_f16_sdwa v29, v67 dst_sel:DWORD dst_unused:UNUSED_PAD src0_sel:WORD_1
	v_cvt_f32_f16_e32 v30, v68
	v_cvt_f32_f16_e32 v32, v69
	v_cvt_f32_f16_sdwa v33, v69 dst_sel:DWORD dst_unused:UNUSED_PAD src0_sel:WORD_1
	v_cvt_f32_f16_sdwa v31, v68 dst_sel:DWORD dst_unused:UNUSED_PAD src0_sel:WORD_1
	v_pk_add_f32 v[24:25], v[24:25], v[94:95]
	v_pk_add_f32 v[22:23], v[22:23], v[118:119]
	v_pk_add_f32 v[20:21], v[20:21], v[96:97]
	v_pk_add_f32 v[18:19], v[18:19], v[120:121]
	v_pk_add_f32 v[8:9], v[8:9], v[28:29]
	v_pk_add_f32 v[6:7], v[6:7], v[26:27]
	v_pk_add_f32 v[4:5], v[4:5], v[32:33]
	v_pk_add_f32 v[2:3], v[2:3], v[30:31]
	s_nop 0
	buffer_load_dwordx4 v[26:29], v193, s[8:11], s47 offen
	s_add_i32 s47, s31, 0x38400
	buffer_load_dwordx4 v[30:33], v193, s[8:11], s47 offen
	s_add_i32 s47, s31, 0x38800
	buffer_load_dwordx4 v[70:73], v193, s[8:11], s47 offen
	s_add_i32 s47, s31, 0x38c00
	buffer_load_dwordx4 v[88:91], v193, s[8:11], s47 offen
	s_add_i32 s47, s31, 0x39000
	buffer_load_dwordx4 v[98:101], v193, s[8:11], s47 offen
	s_add_i32 s47, s31, 0x39400
	buffer_load_dwordx4 v[102:105], v193, s[8:11], s47 offen
	s_add_i32 s47, s31, 0x39800
	s_add_i32 s31, s31, 0x39c00
	buffer_load_dwordx4 v[66:69], v193, s[8:11], s47 offen
	buffer_load_dwordx4 v[50:53], v193, s[8:11], s31 offen
	s_waitcnt vmcnt(7)
	v_cvt_f32_f16_e32 v86, v26
	v_cvt_f32_f16_sdwa v87, v26 dst_sel:DWORD dst_unused:UNUSED_PAD src0_sel:WORD_1
	s_waitcnt vmcnt(6)
	v_cvt_f32_f16_e32 v110, v30
	v_cvt_f32_f16_sdwa v111, v30 dst_sel:DWORD dst_unused:UNUSED_PAD src0_sel:WORD_1
	v_cvt_f32_f16_e32 v30, v31
	v_cvt_f32_f16_sdwa v31, v31 dst_sel:DWORD dst_unused:UNUSED_PAD src0_sel:WORD_1
	v_cvt_f32_f16_e32 v112, v32
	v_cvt_f32_f16_sdwa v113, v32 dst_sel:DWORD dst_unused:UNUSED_PAD src0_sel:WORD_1
	v_cvt_f32_f16_e32 v32, v33
	v_cvt_f32_f16_sdwa v33, v33 dst_sel:DWORD dst_unused:UNUSED_PAD src0_sel:WORD_1
	v_cvt_f32_f16_e32 v26, v27
	v_cvt_f32_f16_sdwa v27, v27 dst_sel:DWORD dst_unused:UNUSED_PAD src0_sel:WORD_1
	v_cvt_f32_f16_e32 v92, v28
	v_cvt_f32_f16_sdwa v93, v28 dst_sel:DWORD dst_unused:UNUSED_PAD src0_sel:WORD_1
	v_cvt_f32_f16_e32 v28, v29
	v_cvt_f32_f16_sdwa v29, v29 dst_sel:DWORD dst_unused:UNUSED_PAD src0_sel:WORD_1
	s_waitcnt vmcnt(4)
	v_cvt_f32_f16_e32 v118, v88
	v_cvt_f32_f16_sdwa v119, v88 dst_sel:DWORD dst_unused:UNUSED_PAD src0_sel:WORD_1
	v_cvt_f32_f16_e32 v120, v89
	v_cvt_f32_f16_sdwa v121, v89 dst_sel:DWORD dst_unused:UNUSED_PAD src0_sel:WORD_1
	v_pk_add_f32 v[88:89], v[56:57], v[30:31]
	v_pk_add_f32 v[56:57], v[76:77], v[32:33]
	v_cvt_f32_f16_e32 v30, v90
	v_cvt_f32_f16_e32 v32, v91
	v_cvt_f32_f16_sdwa v33, v91 dst_sel:DWORD dst_unused:UNUSED_PAD src0_sel:WORD_1
	v_cvt_f32_f16_sdwa v31, v90 dst_sel:DWORD dst_unused:UNUSED_PAD src0_sel:WORD_1
	v_pk_add_f32 v[108:109], v[64:65], v[26:27]
	v_pk_add_f32 v[96:97], v[60:61], v[28:29]
	v_pk_add_f32 v[28:29], v[48:49], v[120:121]
	v_pk_add_f32 v[26:27], v[46:47], v[118:119]
	v_pk_add_f32 v[32:33], v[44:45], v[32:33]
	v_pk_add_f32 v[30:31], v[42:43], v[30:31]
	s_waitcnt vmcnt(3)
	v_cvt_f32_f16_e32 v42, v98
	v_cvt_f32_f16_sdwa v43, v98 dst_sel:DWORD dst_unused:UNUSED_PAD src0_sel:WORD_1
	v_cvt_f32_f16_e32 v44, v99
	v_cvt_f32_f16_sdwa v45, v99 dst_sel:DWORD dst_unused:UNUSED_PAD src0_sel:WORD_1
	v_cvt_f32_f16_e32 v46, v100
	v_cvt_f32_f16_e32 v48, v101
	v_cvt_f32_f16_sdwa v49, v101 dst_sel:DWORD dst_unused:UNUSED_PAD src0_sel:WORD_1
	v_cvt_f32_f16_sdwa v47, v100 dst_sel:DWORD dst_unused:UNUSED_PAD src0_sel:WORD_1
	v_pk_add_f32 v[36:37], v[36:37], v[44:45]
	v_pk_add_f32 v[34:35], v[34:35], v[42:43]
	v_pk_add_f32 v[40:41], v[40:41], v[48:49]
	v_pk_add_f32 v[38:39], v[38:39], v[46:47]
	s_waitcnt vmcnt(2)
	v_cvt_f32_f16_e32 v42, v102
	v_cvt_f32_f16_sdwa v43, v102 dst_sel:DWORD dst_unused:UNUSED_PAD src0_sel:WORD_1
	v_cvt_f32_f16_e32 v44, v103
	v_cvt_f32_f16_sdwa v45, v103 dst_sel:DWORD dst_unused:UNUSED_PAD src0_sel:WORD_1
	v_cvt_f32_f16_e32 v46, v104
	v_cvt_f32_f16_e32 v48, v105
	v_cvt_f32_f16_sdwa v49, v105 dst_sel:DWORD dst_unused:UNUSED_PAD src0_sel:WORD_1
	v_cvt_f32_f16_sdwa v47, v104 dst_sel:DWORD dst_unused:UNUSED_PAD src0_sel:WORD_1
	v_cvt_f32_f16_e32 v114, v70
	v_cvt_f32_f16_sdwa v115, v70 dst_sel:DWORD dst_unused:UNUSED_PAD src0_sel:WORD_1
	v_cvt_f32_f16_e32 v70, v71
	v_cvt_f32_f16_sdwa v71, v71 dst_sel:DWORD dst_unused:UNUSED_PAD src0_sel:WORD_1
	v_cvt_f32_f16_e32 v116, v72
	v_cvt_f32_f16_sdwa v117, v72 dst_sel:DWORD dst_unused:UNUSED_PAD src0_sel:WORD_1
	v_cvt_f32_f16_e32 v72, v73
	v_cvt_f32_f16_sdwa v73, v73 dst_sel:DWORD dst_unused:UNUSED_PAD src0_sel:WORD_1
	v_pk_add_f32 v[44:45], v[24:25], v[44:45]
	v_pk_add_f32 v[42:43], v[22:23], v[42:43]
	v_pk_add_f32 v[48:49], v[20:21], v[48:49]
	v_pk_add_f32 v[46:47], v[18:19], v[46:47]
	s_waitcnt vmcnt(1)
	v_cvt_f32_f16_e32 v18, v66
	v_cvt_f32_f16_sdwa v19, v66 dst_sel:DWORD dst_unused:UNUSED_PAD src0_sel:WORD_1
	v_cvt_f32_f16_e32 v20, v67
	v_cvt_f32_f16_sdwa v21, v67 dst_sel:DWORD dst_unused:UNUSED_PAD src0_sel:WORD_1
	v_cvt_f32_f16_e32 v22, v68
	v_cvt_f32_f16_e32 v24, v69
	v_cvt_f32_f16_sdwa v25, v69 dst_sel:DWORD dst_unused:UNUSED_PAD src0_sel:WORD_1
	v_cvt_f32_f16_sdwa v23, v68 dst_sel:DWORD dst_unused:UNUSED_PAD src0_sel:WORD_1
	v_pk_add_f32 v[106:107], v[62:63], v[86:87]
	v_pk_add_f32 v[94:95], v[58:59], v[92:93]
	v_pk_add_f32 v[86:87], v[54:55], v[110:111]
	v_pk_add_f32 v[54:55], v[74:75], v[112:113]
	v_pk_add_f32 v[64:65], v[80:81], v[70:71]
	v_pk_add_f32 v[62:63], v[78:79], v[114:115]
	v_pk_add_f32 v[60:61], v[84:85], v[72:73]
	v_pk_add_f32 v[58:59], v[82:83], v[116:117]
	v_pk_add_f32 v[16:17], v[16:17], v[20:21]
	v_pk_add_f32 v[14:15], v[14:15], v[18:19]
	v_pk_add_f32 v[12:13], v[12:13], v[24:25]
	v_pk_add_f32 v[10:11], v[10:11], v[22:23]
	s_waitcnt vmcnt(0)
	v_cvt_f32_f16_e32 v18, v50
	v_cvt_f32_f16_sdwa v19, v50 dst_sel:DWORD dst_unused:UNUSED_PAD src0_sel:WORD_1
	v_cvt_f32_f16_e32 v20, v51
	v_cvt_f32_f16_sdwa v21, v51 dst_sel:DWORD dst_unused:UNUSED_PAD src0_sel:WORD_1
	v_cvt_f32_f16_e32 v22, v52
	v_cvt_f32_f16_e32 v24, v53
	v_cvt_f32_f16_sdwa v25, v53 dst_sel:DWORD dst_unused:UNUSED_PAD src0_sel:WORD_1
	v_cvt_f32_f16_sdwa v23, v52 dst_sel:DWORD dst_unused:UNUSED_PAD src0_sel:WORD_1
	v_pk_add_f32 v[72:73], v[8:9], v[20:21]
	v_pk_add_f32 v[70:71], v[6:7], v[18:19]
	v_pk_add_f32 v[76:77], v[4:5], v[24:25]
	v_pk_add_f32 v[74:75], v[2:3], v[22:23]
	s_nop 0
	buffer_load_dwordx4 v[2:5], v193, s[8:11], s3 offen
	buffer_load_dwordx4 v[6:9], v193, s[8:11], s30 offen
	s_or_b32 s30, s3, 0x800
	buffer_load_dwordx4 v[18:21], v193, s[8:11], s30 offen
	s_or_b32 s30, s3, 0xc00
	buffer_load_dwordx4 v[98:101], v193, s[8:11], s30 offen
	s_or_b32 s30, s3, 0x1000
	buffer_load_dwordx4 v[102:105], v193, s[8:11], s30 offen
	s_or_b32 s30, s3, 0x1400
	buffer_load_dwordx4 v[110:113], v193, s[8:11], s30 offen
	s_or_b32 s30, s3, 0x1800
	s_or_b32 s3, s3, 0x1c00
	buffer_load_dwordx4 v[90:93], v193, s[8:11], s30 offen
	buffer_load_dwordx4 v[82:85], v193, s[8:11], s3 offen
	v_ashrrev_i32_e32 v193, 31, v192
	s_waitcnt vmcnt(7)
	v_cvt_f32_f16_e32 v22, v2
	v_cvt_f32_f16_sdwa v23, v2 dst_sel:DWORD dst_unused:UNUSED_PAD src0_sel:WORD_1
	v_cvt_f32_f16_e32 v2, v3
	v_cvt_f32_f16_sdwa v3, v3 dst_sel:DWORD dst_unused:UNUSED_PAD src0_sel:WORD_1
	v_cvt_f32_f16_e32 v24, v4
	v_cvt_f32_f16_e32 v50, v5
	v_cvt_f32_f16_sdwa v51, v5 dst_sel:DWORD dst_unused:UNUSED_PAD src0_sel:WORD_1
	v_cvt_f32_f16_sdwa v25, v4 dst_sel:DWORD dst_unused:UNUSED_PAD src0_sel:WORD_1
	v_pk_add_f32 v[80:81], v[108:109], v[2:3]
	s_waitcnt vmcnt(6)
	v_cvt_f32_f16_e32 v2, v6
	v_cvt_f32_f16_sdwa v3, v6 dst_sel:DWORD dst_unused:UNUSED_PAD src0_sel:WORD_1
	v_cvt_f32_f16_e32 v4, v7
	v_cvt_f32_f16_sdwa v5, v7 dst_sel:DWORD dst_unused:UNUSED_PAD src0_sel:WORD_1
	v_cvt_f32_f16_e32 v6, v8
	v_cvt_f32_f16_sdwa v7, v8 dst_sel:DWORD dst_unused:UNUSED_PAD src0_sel:WORD_1
	v_pk_add_f32 v[78:79], v[106:107], v[22:23]
	v_pk_add_f32 v[68:69], v[96:97], v[50:51]
	v_cvt_f32_f16_e32 v22, v9
	v_cvt_f32_f16_sdwa v23, v9 dst_sel:DWORD dst_unused:UNUSED_PAD src0_sel:WORD_1
	v_pk_add_f32 v[52:53], v[88:89], v[4:5]
	v_pk_add_f32 v[50:51], v[86:87], v[2:3]
	v_pk_add_f32 v[54:55], v[54:55], v[6:7]
	s_waitcnt vmcnt(5)
	v_cvt_f32_f16_e32 v2, v18
	v_cvt_f32_f16_sdwa v3, v18 dst_sel:DWORD dst_unused:UNUSED_PAD src0_sel:WORD_1
	v_cvt_f32_f16_e32 v4, v19
	v_cvt_f32_f16_sdwa v5, v19 dst_sel:DWORD dst_unused:UNUSED_PAD src0_sel:WORD_1
	v_cvt_f32_f16_e32 v6, v20
	v_cvt_f32_f16_e32 v8, v21
	v_cvt_f32_f16_sdwa v9, v21 dst_sel:DWORD dst_unused:UNUSED_PAD src0_sel:WORD_1
	v_cvt_f32_f16_sdwa v7, v20 dst_sel:DWORD dst_unused:UNUSED_PAD src0_sel:WORD_1
	v_pk_add_f32 v[66:67], v[94:95], v[24:25]
	v_pk_add_f32 v[56:57], v[56:57], v[22:23]
	v_pk_add_f32 v[20:21], v[64:65], v[4:5]
	v_pk_add_f32 v[18:19], v[62:63], v[2:3]
	v_pk_add_f32 v[24:25], v[60:61], v[8:9]
	v_pk_add_f32 v[22:23], v[58:59], v[6:7]
	s_waitcnt vmcnt(4)
	v_cvt_f32_f16_e32 v2, v98
	v_cvt_f32_f16_sdwa v3, v98 dst_sel:DWORD dst_unused:UNUSED_PAD src0_sel:WORD_1
	v_cvt_f32_f16_e32 v4, v99
	v_cvt_f32_f16_sdwa v5, v99 dst_sel:DWORD dst_unused:UNUSED_PAD src0_sel:WORD_1
	v_cvt_f32_f16_e32 v6, v100
	v_cvt_f32_f16_e32 v8, v101
	v_cvt_f32_f16_sdwa v9, v101 dst_sel:DWORD dst_unused:UNUSED_PAD src0_sel:WORD_1
	v_cvt_f32_f16_sdwa v7, v100 dst_sel:DWORD dst_unused:UNUSED_PAD src0_sel:WORD_1
	v_pk_add_f32 v[4:5], v[28:29], v[4:5]
	v_pk_add_f32 v[2:3], v[26:27], v[2:3]
	v_pk_add_f32 v[8:9], v[32:33], v[8:9]
	v_pk_add_f32 v[6:7], v[30:31], v[6:7]
	s_waitcnt vmcnt(3)
	v_cvt_f32_f16_e32 v26, v102
	v_cvt_f32_f16_sdwa v27, v102 dst_sel:DWORD dst_unused:UNUSED_PAD src0_sel:WORD_1
	v_cvt_f32_f16_e32 v28, v103
	v_cvt_f32_f16_sdwa v29, v103 dst_sel:DWORD dst_unused:UNUSED_PAD src0_sel:WORD_1
	v_cvt_f32_f16_e32 v30, v104
	v_cvt_f32_f16_e32 v32, v105
	v_cvt_f32_f16_sdwa v33, v105 dst_sel:DWORD dst_unused:UNUSED_PAD src0_sel:WORD_1
	v_cvt_f32_f16_sdwa v31, v104 dst_sel:DWORD dst_unused:UNUSED_PAD src0_sel:WORD_1
	v_pk_add_f32 v[88:89], v[36:37], v[28:29]
	v_pk_add_f32 v[86:87], v[34:35], v[26:27]
	v_pk_add_f32 v[96:97], v[40:41], v[32:33]
	v_pk_add_f32 v[94:95], v[38:39], v[30:31]
	s_waitcnt vmcnt(2)
	v_cvt_f32_f16_e32 v26, v110
	v_cvt_f32_f16_sdwa v27, v110 dst_sel:DWORD dst_unused:UNUSED_PAD src0_sel:WORD_1
	v_cvt_f32_f16_e32 v28, v111
	v_cvt_f32_f16_sdwa v29, v111 dst_sel:DWORD dst_unused:UNUSED_PAD src0_sel:WORD_1
	v_cvt_f32_f16_e32 v30, v112
	v_cvt_f32_f16_e32 v32, v113
	v_cvt_f32_f16_sdwa v33, v113 dst_sel:DWORD dst_unused:UNUSED_PAD src0_sel:WORD_1
	v_cvt_f32_f16_sdwa v31, v112 dst_sel:DWORD dst_unused:UNUSED_PAD src0_sel:WORD_1
	v_pk_add_f32 v[60:61], v[44:45], v[28:29]
	v_pk_add_f32 v[58:59], v[42:43], v[26:27]
	v_pk_add_f32 v[64:65], v[48:49], v[32:33]
	v_pk_add_f32 v[62:63], v[46:47], v[30:31]
	s_waitcnt vmcnt(1)
	v_cvt_f32_f16_e32 v26, v90
	v_cvt_f32_f16_sdwa v27, v90 dst_sel:DWORD dst_unused:UNUSED_PAD src0_sel:WORD_1
	v_cvt_f32_f16_e32 v28, v91
	v_cvt_f32_f16_sdwa v29, v91 dst_sel:DWORD dst_unused:UNUSED_PAD src0_sel:WORD_1
	v_cvt_f32_f16_e32 v30, v92
	v_cvt_f32_f16_e32 v32, v93
	v_cvt_f32_f16_sdwa v33, v93 dst_sel:DWORD dst_unused:UNUSED_PAD src0_sel:WORD_1
	v_cvt_f32_f16_sdwa v31, v92 dst_sel:DWORD dst_unused:UNUSED_PAD src0_sel:WORD_1
	v_pk_add_f32 v[44:45], v[16:17], v[28:29]
	v_pk_add_f32 v[42:43], v[14:15], v[26:27]
	v_pk_add_f32 v[48:49], v[12:13], v[32:33]
	v_pk_add_f32 v[46:47], v[10:11], v[30:31]
	s_waitcnt vmcnt(0)
	v_cvt_f32_f16_e32 v10, v82
	v_cvt_f32_f16_sdwa v11, v82 dst_sel:DWORD dst_unused:UNUSED_PAD src0_sel:WORD_1
	v_cvt_f32_f16_e32 v12, v83
	v_cvt_f32_f16_sdwa v13, v83 dst_sel:DWORD dst_unused:UNUSED_PAD src0_sel:WORD_1
	v_cvt_f32_f16_e32 v14, v84
	v_cvt_f32_f16_e32 v16, v85
	v_cvt_f32_f16_sdwa v17, v85 dst_sel:DWORD dst_unused:UNUSED_PAD src0_sel:WORD_1
	v_cvt_f32_f16_sdwa v15, v84 dst_sel:DWORD dst_unused:UNUSED_PAD src0_sel:WORD_1
	v_pk_add_f32 v[12:13], v[72:73], v[12:13]
	v_pk_add_f32 v[10:11], v[70:71], v[10:11]
	v_pk_add_f32 v[16:17], v[76:77], v[16:17]
	v_pk_add_f32 v[14:15], v[74:75], v[14:15]
	v_lshl_add_u64 v[70:71], v[196:197], 2, s[12:13]
	v_lshlrev_b64 v[26:27], 12, v[192:193]
	v_lshl_add_u64 v[76:77], v[70:71], 0, v[26:27]
	global_load_dwordx4 v[72:75], v[76:77], off
	global_load_dwordx4 v[38:41], v[194:195], off
	global_load_dwordx4 v[34:37], v[194:195], off offset:64
	global_load_dwordx4 v[82:85], v[76:77], off offset:64
	global_load_dwordx4 v[30:33], v[194:195], off offset:512
	global_load_dwordx4 v[26:29], v[194:195], off offset:576
	v_add_u32_e32 v90, 12, v209
	v_cndmask_b32_e32 v1, v90, v209, vcc
	v_add_u32_e32 v146, v1, v208
	v_ashrrev_i32_e32 v147, 31, v146
	s_waitcnt vmcnt(4)
	v_pk_fma_f32 v[72:73], v[78:79], v[38:39], v[72:73]
	s_nop 0
	s_waitcnt vmcnt(2)
	v_pk_fma_f32 v[66:67], v[66:67], v[34:35], v[82:83]
	v_cvt_pk_bf16_f32 v72, v72, v73
	v_pk_fma_f32 v[80:81], v[80:81], v[40:41], v[74:75]
	v_cvt_pk_bf16_f32 v74, v66, v67
	v_pk_fma_f32 v[68:69], v[68:69], v[36:37], v[84:85]
	v_cvt_pk_bf16_f32 v73, v80, v81
	v_cvt_pk_bf16_f32 v75, v68, v69
	v_lshlrev_b64 v[66:67], 11, v[192:193]
	v_lshl_add_u64 v[68:69], v[176:177], 0, v[66:67]
	v_lshlrev_b64 v[66:67], 1, v[146:147]
	v_permlane16_swap_b32_e32 v72, v74
	v_permlane16_swap_b32_e32 v73, v75
	v_lshl_add_u64 v[68:69], v[68:69], 0, v[66:67]
	global_store_dwordx4 v[68:69], v[72:75], off
	global_load_dwordx4 v[72:75], v[76:77], off offset:512
	s_nop 0
	global_load_dwordx4 v[76:79], v[76:77], off offset:576
	s_waitcnt vmcnt(1)
	v_pk_fma_f32 v[74:75], v[88:89], v[32:33], v[74:75]
	v_pk_fma_f32 v[72:73], v[86:87], v[30:31], v[72:73]
	s_waitcnt vmcnt(0)
	v_pk_fma_f32 v[78:79], v[96:97], v[28:29], v[78:79]
	v_pk_fma_f32 v[76:77], v[94:95], v[26:27], v[76:77]
	v_bfe_u32 v1, v72, 16, 1
	v_bfe_u32 v80, v73, 16, 1
	v_bfe_u32 v81, v76, 16, 1
	v_bfe_u32 v82, v77, 16, 1
	v_bfe_u32 v83, v74, 16, 1
	v_bfe_u32 v85, v78, 16, 1
	v_bfe_u32 v84, v75, 16, 1
	v_bfe_u32 v86, v79, 16, 1
	v_add3_u32 v1, v72, v1, s66
	v_add3_u32 v72, v73, v80, s66
	v_add3_u32 v73, v76, v81, s66
	v_add3_u32 v76, v77, v82, s66
	v_add3_u32 v74, v74, v83, s66
	v_add3_u32 v77, v78, v85, s66
	v_add3_u32 v75, v75, v84, s66
	v_add3_u32 v78, v79, v86, s66
	v_lshrrev_b32_e32 v1, 16, v1
	v_lshrrev_b32_e32 v73, 16, v73
	v_lshrrev_b32_e32 v79, 16, v74
	v_lshrrev_b32_e32 v77, 16, v77
	v_and_or_b32 v72, v72, s67, v1
	v_and_or_b32 v74, v76, s67, v73
	v_and_or_b32 v73, v75, s67, v79
	v_and_or_b32 v75, v78, s67, v77
	v_permlane16_swap_b32_e32 v72, v74
	s_nop 0
	v_permlane16_swap_b32_e32 v73, v75
	global_store_dwordx4 v[68:69], v[72:75], off offset:256
	v_add_u32_e32 v68, 16, v192
	v_ashrrev_i32_e32 v69, 31, v68
	v_lshlrev_b64 v[72:73], 12, v[68:69]
	v_lshl_add_u64 v[80:81], v[70:71], 0, v[72:73]
	global_load_dwordx4 v[72:75], v[80:81], off
	global_load_dwordx4 v[76:79], v[80:81], off offset:64
	v_lshlrev_b64 v[68:69], 11, v[68:69]
	v_lshl_add_u64 v[68:69], v[176:177], 0, v[68:69]
	v_lshl_add_u64 v[68:69], v[68:69], 0, v[66:67]
	s_waitcnt vmcnt(1)
	v_pk_fma_f32 v[52:53], v[52:53], v[40:41], v[74:75]
	v_pk_fma_f32 v[50:51], v[50:51], v[38:39], v[72:73]
	s_waitcnt vmcnt(0)
	v_pk_fma_f32 v[56:57], v[56:57], v[36:37], v[78:79]
	v_pk_fma_f32 v[54:55], v[54:55], v[34:35], v[76:77]
	v_bfe_u32 v1, v50, 16, 1
	v_bfe_u32 v72, v51, 16, 1
	v_bfe_u32 v73, v54, 16, 1
	v_bfe_u32 v74, v55, 16, 1
	v_bfe_u32 v75, v52, 16, 1
	v_bfe_u32 v77, v56, 16, 1
	v_bfe_u32 v76, v53, 16, 1
	v_bfe_u32 v78, v57, 16, 1
	v_add3_u32 v1, v50, v1, s66
	v_add3_u32 v50, v51, v72, s66
	v_add3_u32 v51, v54, v73, s66
	v_add3_u32 v54, v55, v74, s66
	v_add3_u32 v52, v52, v75, s66
	v_add3_u32 v55, v56, v77, s66
	v_add3_u32 v53, v53, v76, s66
	v_add3_u32 v56, v57, v78, s66
	v_lshrrev_b32_e32 v1, 16, v1
	v_lshrrev_b32_e32 v51, 16, v51
	v_lshrrev_b32_e32 v57, 16, v52
	v_lshrrev_b32_e32 v55, 16, v55
	v_and_or_b32 v50, v50, s67, v1
	v_and_or_b32 v52, v54, s67, v51
	v_and_or_b32 v51, v53, s67, v57
	v_and_or_b32 v53, v56, s67, v55
	v_permlane16_swap_b32_e32 v50, v52
	s_nop 0
	v_permlane16_swap_b32_e32 v51, v53
	global_store_dwordx4 v[68:69], v[50:53], off
	global_load_dwordx4 v[50:53], v[80:81], off offset:512
	s_nop 0
	global_load_dwordx4 v[54:57], v[80:81], off offset:576
	v_add_u32_e32 v72, 32, v192
	v_ashrrev_i32_e32 v73, 31, v72
	v_lshlrev_b64 v[74:75], 12, v[72:73]
	v_lshl_add_u64 v[74:75], v[70:71], 0, v[74:75]
	s_waitcnt vmcnt(1)
	v_pk_fma_f32 v[52:53], v[60:61], v[32:33], v[52:53]
	v_pk_fma_f32 v[50:51], v[58:59], v[30:31], v[50:51]
	s_waitcnt vmcnt(0)
	v_pk_fma_f32 v[56:57], v[64:65], v[28:29], v[56:57]
	v_pk_fma_f32 v[54:55], v[62:63], v[26:27], v[54:55]
	v_bfe_u32 v1, v50, 16, 1
	v_bfe_u32 v58, v51, 16, 1
	v_bfe_u32 v59, v54, 16, 1
	v_bfe_u32 v60, v55, 16, 1
	v_bfe_u32 v61, v52, 16, 1
	v_bfe_u32 v63, v56, 16, 1
	v_bfe_u32 v62, v53, 16, 1
	v_bfe_u32 v64, v57, 16, 1
	v_add3_u32 v1, v50, v1, s66
	v_add3_u32 v50, v51, v58, s66
	v_add3_u32 v51, v54, v59, s66
	v_add3_u32 v54, v55, v60, s66
	v_add3_u32 v52, v52, v61, s66
	v_add3_u32 v55, v56, v63, s66
	v_add3_u32 v53, v53, v62, s66
	v_add3_u32 v56, v57, v64, s66
	v_lshrrev_b32_e32 v1, 16, v1
	v_lshrrev_b32_e32 v51, 16, v51
	v_lshrrev_b32_e32 v57, 16, v52
	v_lshrrev_b32_e32 v55, 16, v55
	v_and_or_b32 v50, v50, s67, v1
	v_and_or_b32 v52, v54, s67, v51
	v_and_or_b32 v51, v53, s67, v57
	v_and_or_b32 v53, v56, s67, v55
	v_permlane16_swap_b32_e32 v50, v52
	s_nop 0
	v_permlane16_swap_b32_e32 v51, v53
	global_store_dwordx4 v[68:69], v[50:53], off offset:256
	global_load_dwordx4 v[50:53], v[74:75], off
	s_nop 0
	global_load_dwordx4 v[54:57], v[74:75], off offset:64
	v_lshlrev_b64 v[58:59], 11, v[72:73]
	v_lshl_add_u64 v[58:59], v[176:177], 0, v[58:59]
	v_lshl_add_u64 v[58:59], v[58:59], 0, v[66:67]
	s_waitcnt vmcnt(1)
	v_pk_fma_f32 v[20:21], v[20:21], v[40:41], v[52:53]
	v_pk_fma_f32 v[18:19], v[18:19], v[38:39], v[50:51]
	s_waitcnt vmcnt(0)
	v_pk_fma_f32 v[24:25], v[24:25], v[36:37], v[56:57]
	v_pk_fma_f32 v[22:23], v[22:23], v[34:35], v[54:55]
	v_bfe_u32 v1, v18, 16, 1
	v_bfe_u32 v50, v19, 16, 1
	v_bfe_u32 v51, v22, 16, 1
	v_bfe_u32 v52, v23, 16, 1
	v_bfe_u32 v53, v20, 16, 1
	v_bfe_u32 v55, v24, 16, 1
	v_bfe_u32 v54, v21, 16, 1
	v_bfe_u32 v56, v25, 16, 1
	v_add3_u32 v1, v18, v1, s66
	v_add3_u32 v18, v19, v50, s66
	v_add3_u32 v19, v22, v51, s66
	v_add3_u32 v22, v23, v52, s66
	v_add3_u32 v20, v20, v53, s66
	v_add3_u32 v23, v24, v55, s66
	v_add3_u32 v21, v21, v54, s66
	v_add3_u32 v24, v25, v56, s66
	v_lshrrev_b32_e32 v1, 16, v1
	v_lshrrev_b32_e32 v19, 16, v19
	v_lshrrev_b32_e32 v25, 16, v20
	v_lshrrev_b32_e32 v23, 16, v23
	v_and_or_b32 v18, v18, s67, v1
	v_and_or_b32 v20, v22, s67, v19
	v_and_or_b32 v19, v21, s67, v25
	v_and_or_b32 v21, v24, s67, v23
	v_permlane16_swap_b32_e32 v18, v20
	s_nop 0
	v_permlane16_swap_b32_e32 v19, v21
	global_store_dwordx4 v[58:59], v[18:21], off
	global_load_dwordx4 v[18:21], v[74:75], off offset:512
	s_nop 0
	global_load_dwordx4 v[22:25], v[74:75], off offset:576
	v_add_u32_e32 v50, 48, v192
	v_ashrrev_i32_e32 v51, 31, v50
	v_lshlrev_b64 v[52:53], 12, v[50:51]
	v_lshl_add_u64 v[52:53], v[70:71], 0, v[52:53]
	v_lshlrev_b64 v[138:139], 10, v[50:51]
	s_waitcnt vmcnt(1)
	v_pk_fma_f32 v[20:21], v[44:45], v[32:33], v[20:21]
	v_pk_fma_f32 v[18:19], v[42:43], v[30:31], v[18:19]
	s_waitcnt vmcnt(0)
	v_pk_fma_f32 v[24:25], v[48:49], v[28:29], v[24:25]
	v_pk_fma_f32 v[22:23], v[46:47], v[26:27], v[22:23]
	v_bfe_u32 v1, v18, 16, 1
	v_bfe_u32 v42, v19, 16, 1
	v_bfe_u32 v43, v22, 16, 1
	v_bfe_u32 v44, v23, 16, 1
	v_bfe_u32 v45, v20, 16, 1
	v_bfe_u32 v47, v24, 16, 1
	v_bfe_u32 v46, v21, 16, 1
	v_bfe_u32 v48, v25, 16, 1
	v_add3_u32 v1, v18, v1, s66
	v_add3_u32 v18, v19, v42, s66
	v_add3_u32 v19, v22, v43, s66
	v_add3_u32 v22, v23, v44, s66
	v_add3_u32 v20, v20, v45, s66
	v_add3_u32 v23, v24, v47, s66
	v_add3_u32 v21, v21, v46, s66
	v_add3_u32 v24, v25, v48, s66
	v_lshrrev_b32_e32 v1, 16, v1
	v_lshrrev_b32_e32 v19, 16, v19
	v_lshrrev_b32_e32 v25, 16, v20
	v_lshrrev_b32_e32 v23, 16, v23
	v_and_or_b32 v18, v18, s67, v1
	v_and_or_b32 v20, v22, s67, v19
	v_and_or_b32 v19, v21, s67, v25
	v_and_or_b32 v21, v24, s67, v23
	v_permlane16_swap_b32_e32 v18, v20
	s_nop 0
	v_permlane16_swap_b32_e32 v19, v21
	global_store_dwordx4 v[58:59], v[18:21], off offset:256
	global_load_dwordx4 v[18:21], v[52:53], off
	s_nop 0
	global_load_dwordx4 v[22:25], v[52:53], off offset:64
	v_lshlrev_b64 v[42:43], 11, v[50:51]
	v_lshl_add_u64 v[42:43], v[176:177], 0, v[42:43]
	v_lshl_add_u64 v[42:43], v[42:43], 0, v[66:67]
	s_waitcnt vmcnt(1)
	v_pk_fma_f32 v[4:5], v[4:5], v[40:41], v[20:21]
	v_pk_fma_f32 v[2:3], v[2:3], v[38:39], v[18:19]
	s_waitcnt vmcnt(0)
	v_pk_fma_f32 v[8:9], v[8:9], v[36:37], v[24:25]
	v_pk_fma_f32 v[6:7], v[6:7], v[34:35], v[22:23]
	v_bfe_u32 v1, v2, 16, 1
	v_bfe_u32 v18, v3, 16, 1
	v_bfe_u32 v19, v6, 16, 1
	v_bfe_u32 v20, v7, 16, 1
	v_bfe_u32 v21, v4, 16, 1
	v_bfe_u32 v23, v8, 16, 1
	v_bfe_u32 v22, v5, 16, 1
	v_bfe_u32 v24, v9, 16, 1
	v_add3_u32 v1, v2, v1, s66
	v_add3_u32 v2, v3, v18, s66
	v_add3_u32 v3, v6, v19, s66
	v_add3_u32 v6, v7, v20, s66
	v_add3_u32 v4, v4, v21, s66
	v_add3_u32 v7, v8, v23, s66
	v_add3_u32 v5, v5, v22, s66
	v_add3_u32 v8, v9, v24, s66
	v_lshrrev_b32_e32 v1, 16, v1
	v_lshrrev_b32_e32 v3, 16, v3
	v_lshrrev_b32_e32 v9, 16, v4
	v_lshrrev_b32_e32 v7, 16, v7
	v_and_or_b32 v2, v2, s67, v1
	v_and_or_b32 v4, v6, s67, v3
	v_and_or_b32 v3, v5, s67, v9
	v_and_or_b32 v5, v8, s67, v7
	v_permlane16_swap_b32_e32 v2, v4
	s_nop 0
	v_permlane16_swap_b32_e32 v3, v5
	global_store_dwordx4 v[42:43], v[2:5], off
	global_load_dwordx4 v[2:5], v[52:53], off offset:512
	s_nop 0
	global_load_dwordx4 v[6:9], v[52:53], off offset:576
	s_waitcnt vmcnt(1)
	v_pk_fma_f32 v[4:5], v[12:13], v[32:33], v[4:5]
	v_pk_fma_f32 v[2:3], v[10:11], v[30:31], v[2:3]
	s_waitcnt vmcnt(0)
	v_pk_fma_f32 v[8:9], v[16:17], v[28:29], v[8:9]
	v_pk_fma_f32 v[6:7], v[14:15], v[26:27], v[6:7]
	v_bfe_u32 v1, v2, 16, 1
	v_bfe_u32 v10, v3, 16, 1
	v_bfe_u32 v11, v6, 16, 1
	v_bfe_u32 v12, v7, 16, 1
	v_add3_u32 v1, v2, v1, s66
	v_add3_u32 v2, v3, v10, s66
	v_add3_u32 v3, v6, v11, s66
	v_add3_u32 v6, v7, v12, s66
	v_lshrrev_b32_e32 v1, 16, v1
	v_lshrrev_b32_e32 v3, 16, v3
	v_and_or_b32 v130, v2, s67, v1
	v_and_or_b32 v132, v6, s67, v3
	v_cvt_pk_bf16_f32 v131, v4, v5
	v_cvt_pk_bf16_f32 v133, v8, v9
	v_permlane16_swap_b32_e32 v130, v132
	s_nop 0
	v_permlane16_swap_b32_e32 v131, v133

.LBB0_1097:
	v_add_u32_e32 v20, 0x8000, v7
	s_waitcnt lgkmcnt(0)
	s_barrier
	ds_read2_b32 v[18:19], v20 offset1:65
	s_ashr_i32 s13, s12, 31
	s_lshr_b32 s13, s13, 28
	s_add_i32 s12, s12, s13
	s_ashr_i32 s13, s12, 4
	s_waitcnt lgkmcnt(0)
	ds_read2_b32 v[20:21], v20 offset0:130 offset1:195
	v_cvt_pk_bf16_f32 v18, v18, v19
	s_waitcnt lgkmcnt(0)
	v_bfe_u32 v19, v20, 16, 1
	v_add3_u32 v19, v20, v19, s9
	v_add_u32_e32 v20, 0x8400, v7
	ds_read2_b32 v[22:23], v20 offset0:4 offset1:69
	v_bfe_u32 v24, v21, 16, 1
	v_lshrrev_b32_e32 v19, 16, v19
	v_add3_u32 v21, v21, v24, s9
	ds_read2_b32 v[24:25], v20 offset0:134 offset1:199
	v_and_or_b32 v19, v21, s10, v19
	s_waitcnt lgkmcnt(1)
	v_cvt_pk_bf16_f32 v20, v22, v23
	s_waitcnt lgkmcnt(0)
	v_cvt_pk_bf16_f32 v21, v24, v25
	v_lshl_or_b32 v22, s13, 6, v200
	s_lshl_b32 s12, s13, 10
	v_ashrrev_i32_e32 v23, 31, v22
	s_sub_i32 s12, s3, s12
	v_lshlrev_b64 v[22:23], 11, v[22:23]
	v_lshl_add_u64 v[22:23], v[2:3], 0, v[22:23]
	s_ashr_i32 s13, s12, 31
	v_lshl_add_u64 v[22:23], s[12:13], 1, v[22:23]
	v_lshl_add_u64 v[22:23], v[22:23], 0, v[4:5]
	global_store_dwordx4 v[22:23], v[18:21], off
	s_add_i32 s3, s3, s8
	s_and_b64 vcc, exec, s[6:7]
	s_mov_b32 s12, s11
	s_waitcnt vmcnt(8)
	v_mov_b32_e32 v18, v10
	s_waitcnt vmcnt(7)
	v_mov_b32_e32 v19, v11
	s_waitcnt vmcnt(6)
	v_mov_b32_e32 v20, v12
	s_waitcnt vmcnt(5)
	v_mov_b32_e32 v21, v13
	s_waitcnt vmcnt(4)
	v_mov_b32_e32 v22, v14
	s_waitcnt vmcnt(3)
	v_mov_b32_e32 v23, v15
	s_waitcnt vmcnt(2)
	v_mov_b32_e32 v24, v16
	s_waitcnt vmcnt(1)
	v_mov_b32_e32 v25, v17
	s_barrier
	s_cbranch_vccnz .LBB0_1102

.LBB0_1106:
	v_add_u32_e32 v20, 0x8000, v7
	s_waitcnt lgkmcnt(0)
	s_barrier
	ds_read2_b32 v[18:19], v20 offset1:65
	s_ashr_i32 s18, s3, 31
	s_lshr_b32 s18, s18, 28
	s_add_i32 s3, s3, s18
	s_ashr_i32 s3, s3, 4
	s_waitcnt lgkmcnt(0)
	ds_read2_b32 v[20:21], v20 offset0:130 offset1:195
	v_cvt_pk_bf16_f32 v18, v18, v19
	s_waitcnt lgkmcnt(0)
	v_bfe_u32 v19, v20, 16, 1
	v_add3_u32 v19, v20, v19, s13
	v_add_u32_e32 v20, 0x8400, v7
	ds_read2_b32 v[22:23], v20 offset0:4 offset1:69
	v_bfe_u32 v24, v21, 16, 1
	v_lshrrev_b32_e32 v19, 16, v19
	v_add3_u32 v21, v21, v24, s13
	ds_read2_b32 v[24:25], v20 offset0:134 offset1:199
	v_and_or_b32 v19, v21, s16, v19
	s_waitcnt lgkmcnt(1)
	v_cvt_pk_bf16_f32 v20, v22, v23
	s_waitcnt lgkmcnt(0)
	v_cvt_pk_bf16_f32 v21, v24, v25
	v_lshl_or_b32 v22, s3, 6, v200
	s_lshl_b32 s18, s3, 10
	v_ashrrev_i32_e32 v23, 31, v22
	s_sub_i32 s18, s11, s18
	v_lshlrev_b64 v[22:23], 11, v[22:23]
	v_lshl_add_u64 v[22:23], v[2:3], 0, v[22:23]
	s_ashr_i32 s19, s18, 31
	v_lshl_add_u64 v[22:23], s[18:19], 1, v[22:23]
	v_lshl_add_u64 v[22:23], v[22:23], 0, v[4:5]
	global_store_dwordx4 v[22:23], v[18:21], off
	s_add_i32 s11, s11, s12
	s_and_b64 vcc, exec, s[8:9]
	s_mov_b32 s3, s17
	s_waitcnt vmcnt(8)
	v_mov_b32_e32 v18, v10
	s_waitcnt vmcnt(7)
	v_mov_b32_e32 v19, v11
	s_waitcnt vmcnt(6)
	v_mov_b32_e32 v20, v12
	s_waitcnt vmcnt(5)
	v_mov_b32_e32 v21, v13
	s_waitcnt vmcnt(4)
	v_mov_b32_e32 v22, v14
	s_waitcnt vmcnt(3)
	v_mov_b32_e32 v23, v15
	s_waitcnt vmcnt(2)
	v_mov_b32_e32 v24, v16
	s_waitcnt vmcnt(1)
	v_mov_b32_e32 v25, v17
	s_barrier
	s_cbranch_vccnz .LBB0_1109

.LBB0_1174:
	s_or_b64 exec, exec, s[18:19]
	v_and_b32_e32 v91, 0xffff0000, v40
	v_and_b32_e32 v90, 0xffff0000, v38
	v_lshlrev_b32_e32 v81, 16, v40
	v_lshlrev_b32_e32 v80, 16, v38
	v_lshlrev_b32_e32 v92, 16, v39
	v_and_b32_e32 v40, 0xffff0000, v39
	v_pk_mul_f32 v[38:39], v[90:91], v[90:91]
	v_and_b32_e32 v97, 0xffff0000, v26
	v_and_b32_e32 v96, 0xffff0000, v28
	v_lshlrev_b32_e32 v93, 16, v41
	v_pk_fma_f32 v[38:39], v[80:81], v[80:81], v[38:39]
	v_lshlrev_b32_e32 v95, 16, v26
	v_lshlrev_b32_e32 v94, 16, v28
	v_lshlrev_b32_e32 v99, 16, v27
	v_and_b32_e32 v101, 0xffff0000, v27
	v_pk_mul_f32 v[26:27], v[96:97], v[96:97]
	v_and_b32_e32 v41, 0xffff0000, v41
	v_pk_fma_f32 v[38:39], v[92:93], v[92:93], v[38:39]
	v_lshlrev_b32_e32 v98, 16, v29
	v_pk_fma_f32 v[26:27], v[94:95], v[94:95], v[26:27]
	v_pk_fma_f32 v[38:39], v[40:41], v[40:41], v[38:39]
	v_and_b32_e32 v100, 0xffff0000, v29
	v_pk_fma_f32 v[26:27], v[98:99], v[98:99], v[26:27]
	v_add_f32_e32 v28, v38, v39
	v_pk_fma_f32 v[26:27], v[100:101], v[100:101], v[26:27]
	v_mov_b32_e32 v29, v40
	v_add_f32_e32 v27, v28, v27
	v_add_f32_e32 v26, v26, v27
	ds_bpermute_b32 v27, v67, v26
	v_lshl_add_u64 v[38:39], v[76:77], 0, v[72:73]
	s_waitcnt lgkmcnt(0)
	v_add_f32_e32 v26, v26, v27
	ds_bpermute_b32 v27, v82, v26
	s_waitcnt lgkmcnt(0)
	v_add_f32_e32 v26, v26, v27
	ds_bpermute_b32 v27, v83, v26
	s_waitcnt lgkmcnt(0)
	v_add_f32_e32 v26, v26, v27
	ds_bpermute_b32 v27, v84, v26
	s_waitcnt lgkmcnt(0)
	v_add_f32_e32 v26, v26, v27
	ds_bpermute_b32 v27, v85, v26
	s_waitcnt lgkmcnt(0)
	v_add_f32_e32 v27, v26, v27
	ds_bpermute_b32 v28, v86, v27
	v_mov_b32_e32 v26, v80
	s_waitcnt lgkmcnt(0)
	v_add_f32_e32 v27, v27, v28
	v_fmamk_f32 v27, v27, 0x3a800000, v79
	v_mul_f32_e32 v28, 0x4b800000, v27
	v_cmp_gt_f32_e32 vcc, s3, v27
	s_nop 1
	v_cndmask_b32_e32 v27, v27, v28, vcc
	v_rsq_f32_e32 v58, v27
	v_mov_b32_e32 v27, v90
	v_mov_b32_e32 v28, v92
	v_mov_b32_e32 v90, v81
	v_mul_f32_e32 v40, 0x45800000, v58
	v_cndmask_b32_e32 v58, v58, v40, vcc
	v_pk_mul_f32 v[26:27], v[58:59], v[26:27] op_sel_hi:[0,1]
	s_waitcnt vmcnt(2)
	v_pk_fma_f32 v[26:27], v[42:43], v[26:27], v[22:23]
	v_pk_mul_f32 v[28:29], v[58:59], v[28:29] op_sel_hi:[0,1]
	v_pk_fma_f32 v[28:29], v[44:45], v[28:29], v[24:25]
	v_cvt_pk_bf16_f32 v26, v26, v27
	v_pk_mul_f32 v[80:81], v[58:59], v[90:91] op_sel_hi:[0,1]
	v_pk_fma_f32 v[80:81], v[46:47], v[80:81], v[18:19]
	v_mov_b32_e32 v40, v93
	v_cvt_pk_bf16_f32 v27, v28, v29
	v_pk_mul_f32 v[40:41], v[58:59], v[40:41] op_sel_hi:[0,1]
	v_pk_fma_f32 v[40:41], v[48:49], v[40:41], v[20:21]
	v_cvt_pk_bf16_f32 v28, v80, v81
	v_add_co_u32_e32 v38, vcc, s21, v38
	v_cvt_pk_bf16_f32 v29, v40, v41
	s_nop 0
	v_addc_co_u32_e32 v39, vcc, 0, v39, vcc
	global_store_dwordx4 v[38:39], v[26:29], off
	s_nop 1
	v_mov_b32_e32 v26, v95
	v_mov_b32_e32 v27, v97
	v_pk_mul_f32 v[26:27], v[58:59], v[26:27] op_sel_hi:[0,1]
	v_mov_b32_e32 v28, v99
	v_mov_b32_e32 v29, v101
	s_waitcnt vmcnt(1)
	v_pk_fma_f32 v[26:27], v[50:51], v[26:27], v[34:35]
	v_mov_b32_e32 v95, v96
	v_mov_b32_e32 v99, v100
	v_pk_mul_f32 v[28:29], v[58:59], v[28:29] op_sel_hi:[0,1]
	v_pk_mul_f32 v[40:41], v[58:59], v[94:95] op_sel_hi:[0,1]
	v_pk_mul_f32 v[80:81], v[58:59], v[98:99] op_sel_hi:[0,1]
	v_pk_fma_f32 v[28:29], v[52:53], v[28:29], v[36:37]
	v_cvt_pk_bf16_f32 v26, v26, v27
	v_pk_fma_f32 v[40:41], v[54:55], v[40:41], v[30:31]
	v_cvt_pk_bf16_f32 v27, v28, v29
	v_pk_fma_f32 v[80:81], v[56:57], v[80:81], v[32:33]
	v_cvt_pk_bf16_f32 v28, v40, v41
	v_cvt_pk_bf16_f32 v29, v80, v81
	global_store_dwordx4 v[38:39], v[26:29], off offset:1024

.LBB0_1178:
	s_or_b64 exec, exec, s[16:17]
	s_waitcnt vmcnt(5)
	v_and_b32_e32 v91, 0xffff0000, v4
	v_and_b32_e32 v90, 0xffff0000, v2
	v_lshlrev_b32_e32 v81, 16, v4
	v_lshlrev_b32_e32 v80, 16, v2
	v_pk_mul_f32 v[96:97], v[90:91], v[90:91]
	s_waitcnt vmcnt(4)
	v_and_b32_e32 v101, 0xffff0000, v6
	v_and_b32_e32 v100, 0xffff0000, v8
	v_lshlrev_b32_e32 v93, 16, v5
	v_lshlrev_b32_e32 v92, 16, v3
	v_pk_fma_f32 v[96:97], v[80:81], v[80:81], v[96:97]
	v_lshlrev_b32_e32 v99, 16, v6
	v_lshlrev_b32_e32 v98, 16, v8
	v_pk_mul_f32 v[106:107], v[100:101], v[100:101]
	v_and_b32_e32 v95, 0xffff0000, v5
	v_and_b32_e32 v94, 0xffff0000, v3
	v_pk_fma_f32 v[96:97], v[92:93], v[92:93], v[96:97]
	v_lshlrev_b32_e32 v103, 16, v7
	v_lshlrev_b32_e32 v102, 16, v9
	v_pk_fma_f32 v[106:107], v[98:99], v[98:99], v[106:107]
	v_pk_fma_f32 v[96:97], v[94:95], v[94:95], v[96:97]
	v_and_b32_e32 v105, 0xffff0000, v7
	v_and_b32_e32 v104, 0xffff0000, v9
	v_pk_fma_f32 v[106:107], v[102:103], v[102:103], v[106:107]
	v_add_f32_e32 v58, v96, v97
	v_pk_fma_f32 v[106:107], v[104:105], v[104:105], v[106:107]
	v_mov_b32_e32 v109, v94
	v_add_f32_e32 v58, v107, v58
	v_add_f32_e32 v58, v106, v58
	ds_bpermute_b32 v88, v67, v58
	v_mov_b32_e32 v106, v80
	v_mov_b32_e32 v107, v90
	v_mov_b32_e32 v90, v81
	v_mov_b32_e32 v94, v93
	s_waitcnt lgkmcnt(0)
	v_add_f32_e32 v58, v58, v88
	ds_bpermute_b32 v88, v82, v58
	v_mov_b32_e32 v108, v92
	v_lshl_add_u64 v[96:97], v[74:75], 0, v[72:73]
	s_waitcnt lgkmcnt(0)
	v_add_f32_e32 v58, v58, v88
	ds_bpermute_b32 v88, v83, v58
	s_waitcnt lgkmcnt(0)
	v_add_f32_e32 v58, v58, v88
	ds_bpermute_b32 v88, v84, v58
	s_waitcnt lgkmcnt(0)
	v_add_f32_e32 v58, v58, v88
	ds_bpermute_b32 v88, v85, v58
	s_waitcnt lgkmcnt(0)
	v_add_f32_e32 v58, v58, v88
	ds_bpermute_b32 v88, v86, v58
	s_waitcnt lgkmcnt(0)
	v_add_f32_e32 v58, v58, v88
	v_fmamk_f32 v58, v58, 0x3a800000, v79
	v_mul_f32_e32 v80, 0x4b800000, v58
	v_cmp_gt_f32_e32 vcc, s3, v58
	s_nop 1
	v_cndmask_b32_e32 v58, v58, v80, vcc
	v_rsq_f32_e32 v58, v58
	s_nop 0
	v_mul_f32_e32 v80, 0x45800000, v58
	v_cndmask_b32_e32 v58, v58, v80, vcc
	v_pk_mul_f32 v[106:107], v[58:59], v[106:107] op_sel_hi:[0,1]
	s_waitcnt vmcnt(2)
	v_pk_fma_f32 v[106:107], v[42:43], v[106:107], v[22:23]
	v_pk_mul_f32 v[80:81], v[58:59], v[90:91] op_sel_hi:[0,1]
	v_pk_mul_f32 v[90:91], v[58:59], v[94:95] op_sel_hi:[0,1]
	v_pk_mul_f32 v[108:109], v[58:59], v[108:109] op_sel_hi:[0,1]
	v_pk_fma_f32 v[94:95], v[48:49], v[90:91], v[20:21]
	v_pk_fma_f32 v[108:109], v[44:45], v[108:109], v[24:25]
	v_cvt_pk_bf16_f32 v90, v106, v107
	v_pk_fma_f32 v[80:81], v[46:47], v[80:81], v[18:19]
	v_cvt_pk_bf16_f32 v91, v108, v109
	v_cvt_pk_bf16_f32 v92, v80, v81
	v_cvt_pk_bf16_f32 v93, v94, v95
	v_add_co_u32_e32 v80, vcc, s21, v96
	s_nop 1
	v_addc_co_u32_e32 v81, vcc, 0, v97, vcc
	global_store_dwordx4 v[80:81], v[90:93], off
	s_nop 1
	v_mov_b32_e32 v90, v99
	v_mov_b32_e32 v91, v101
	v_pk_mul_f32 v[90:91], v[58:59], v[90:91] op_sel_hi:[0,1]
	v_mov_b32_e32 v92, v103
	v_mov_b32_e32 v93, v105
	s_waitcnt vmcnt(1)
	v_pk_fma_f32 v[90:91], v[50:51], v[90:91], v[34:35]
	v_mov_b32_e32 v99, v100
	v_mov_b32_e32 v103, v104
	v_pk_mul_f32 v[92:93], v[58:59], v[92:93] op_sel_hi:[0,1]
	v_pk_mul_f32 v[94:95], v[58:59], v[98:99] op_sel_hi:[0,1]
	v_pk_mul_f32 v[96:97], v[58:59], v[102:103] op_sel_hi:[0,1]
	v_pk_fma_f32 v[92:93], v[52:53], v[92:93], v[36:37]
	v_cvt_pk_bf16_f32 v90, v90, v91
	v_pk_fma_f32 v[94:95], v[54:55], v[94:95], v[30:31]
	v_cvt_pk_bf16_f32 v91, v92, v93
	v_pk_fma_f32 v[96:97], v[56:57], v[96:97], v[32:33]
	v_cvt_pk_bf16_f32 v92, v94, v95
	v_cvt_pk_bf16_f32 v93, v96, v97
	global_store_dwordx4 v[80:81], v[90:93], off offset:1024
	v_add_u32_e32 v80, 1, v78
	v_cmp_lt_i32_e32 vcc, v80, v1
	v_add_u32_e32 v88, 3, v78
	s_and_saveexec_b64 s[16:17], vcc
	s_cbranch_execz .LBB0_1182
	v_add_u32_e32 v2, 3, v78
	v_min_i32_e32 v2, v2, v61
	v_ashrrev_i32_e32 v3, 31, v2
	v_cmp_gt_i32_e32 vcc, s0, v2
	v_add_u32_e32 v58, 0xfffff001, v78
	v_ashrrev_i32_e32 v58, 12, v58
	v_cndmask_b32_e32 v3, 0, v3, vcc
	v_lshlrev_b64 v[2:3], 11, v[2:3]
	v_lshl_add_u64 v[90:91], v[70:71], 0, v[2:3]
	global_load_dwordx4 v[2:5], v[90:91], off
	global_load_dwordx4 v[6:9], v[90:91], off offset:1024
	v_add_u32_e32 v58, 1, v58
	v_cmp_lt_i32_e32 vcc, s22, v78
	s_nop 1
	v_cndmask_b32_e32 v81, 0, v58, vcc
	v_cmp_ne_u32_e32 vcc, v81, v87
	s_and_saveexec_b64 s[18:19], vcc
	s_cbranch_execz .LBB0_1181
	v_add_u32_e32 v18, 5, v81
	v_mul_hi_i32_i24_e32 v19, 0x3000, v18
	v_mul_i32_i24_e32 v18, 0x3000, v18
	v_lshl_add_u64 v[18:19], s[10:11], 0, v[18:19]
	v_lshl_add_u64 v[20:21], v[18:19], 0, s[8:9]
	v_lshlrev_b32_e32 v58, 2, v60
	v_lshl_add_u64 v[22:23], v[20:21], 0, v[58:59]
	global_load_dwordx4 v[42:45], v[22:23], off
	global_load_dwordx4 v[46:49], v[22:23], off offset:16
	global_load_dwordx4 v[50:53], v[64:65], off offset:16
	global_load_dwordx4 v[54:57], v[64:65], off
	v_lshl_add_u64 v[106:107], v[18:19], 0, v[58:59]
	v_lshlrev_b32_e32 v58, 2, v66
	v_lshl_add_u64 v[108:109], v[20:21], 0, v[58:59]
	global_load_dwordx4 v[90:93], v[108:109], off
	global_load_dwordx4 v[94:97], v[108:109], off offset:16
	global_load_dwordx4 v[98:101], v[68:69], off
	global_load_dwordx4 v[102:105], v[68:69], off offset:16
	global_load_dwordx4 v[18:21], v[106:107], off offset:16
	global_load_dwordx4 v[22:25], v[106:107], off
	global_load_dwordx4 v[30:33], v[106:107], off offset:2064
	global_load_dwordx4 v[34:37], v[106:107], off offset:2048
	v_mov_b32_e32 v87, v81
	s_waitcnt vmcnt(11)
	v_pk_add_f32 v[44:45], v[44:45], 1.0 op_sel_hi:[1,0]
	v_pk_add_f32 v[42:43], v[42:43], 1.0 op_sel_hi:[1,0]
	s_waitcnt vmcnt(10)
	v_pk_add_f32 v[46:47], v[46:47], 1.0 op_sel_hi:[1,0]
	v_pk_add_f32 v[48:49], v[48:49], 1.0 op_sel_hi:[1,0]
	s_waitcnt vmcnt(8)
	v_pk_mul_f32 v[44:45], v[56:57], v[44:45]
	v_pk_mul_f32 v[42:43], v[54:55], v[42:43]
	v_pk_mul_f32 v[46:47], v[50:51], v[46:47]
	s_waitcnt vmcnt(7)
	v_pk_add_f32 v[50:51], v[92:93], 1.0 op_sel_hi:[1,0]
	v_pk_add_f32 v[54:55], v[90:91], 1.0 op_sel_hi:[1,0]
	s_waitcnt vmcnt(6)
	v_pk_add_f32 v[56:57], v[96:97], 1.0 op_sel_hi:[1,0]
	v_pk_add_f32 v[90:91], v[94:95], 1.0 op_sel_hi:[1,0]
	v_pk_mul_f32 v[48:49], v[52:53], v[48:49]
	s_waitcnt vmcnt(5)
	v_pk_mul_f32 v[52:53], v[100:101], v[50:51]
	v_pk_mul_f32 v[50:51], v[98:99], v[54:55]
	s_waitcnt vmcnt(4)
	v_pk_mul_f32 v[56:57], v[104:105], v[56:57]
	v_pk_mul_f32 v[54:55], v[102:103], v[90:91]
.LBB0_1181:
	s_or_b64 exec, exec, s[18:19]
	v_and_b32_e32 v93, 0xffff0000, v12
	v_and_b32_e32 v92, 0xffff0000, v10
	v_lshlrev_b32_e32 v91, 16, v12
	v_lshlrev_b32_e32 v90, 16, v10
	v_pk_mul_f32 v[98:99], v[92:93], v[92:93]
	v_and_b32_e32 v103, 0xffff0000, v14
	v_and_b32_e32 v102, 0xffff0000, v16
	v_lshlrev_b32_e32 v95, 16, v13
	v_lshlrev_b32_e32 v94, 16, v11
	v_pk_fma_f32 v[98:99], v[90:91], v[90:91], v[98:99]
	v_lshlrev_b32_e32 v101, 16, v14
	v_lshlrev_b32_e32 v100, 16, v16
	v_pk_mul_f32 v[108:109], v[102:103], v[102:103]
	v_and_b32_e32 v97, 0xffff0000, v13
	v_and_b32_e32 v96, 0xffff0000, v11
	v_pk_fma_f32 v[98:99], v[94:95], v[94:95], v[98:99]
	v_lshlrev_b32_e32 v105, 16, v15
	v_lshlrev_b32_e32 v104, 16, v17
	v_pk_fma_f32 v[108:109], v[100:101], v[100:101], v[108:109]
	v_pk_fma_f32 v[98:99], v[96:97], v[96:97], v[98:99]
	v_and_b32_e32 v107, 0xffff0000, v15
	v_and_b32_e32 v106, 0xffff0000, v17
	v_pk_fma_f32 v[108:109], v[104:105], v[104:105], v[108:109]
	v_add_f32_e32 v58, v98, v99
	v_pk_fma_f32 v[108:109], v[106:107], v[106:107], v[108:109]
	v_mov_b32_e32 v98, v90
	v_add_f32_e32 v58, v109, v58
	v_add_f32_e32 v58, v108, v58
	ds_bpermute_b32 v81, v67, v58
	v_mov_b32_e32 v99, v92
	v_mov_b32_e32 v109, v96
	v_mov_b32_e32 v92, v91
	v_mov_b32_e32 v96, v95
	s_waitcnt lgkmcnt(0)
	v_add_f32_e32 v58, v58, v81
	ds_bpermute_b32 v81, v82, v58
	s_waitcnt lgkmcnt(0)
	v_add_f32_e32 v58, v58, v81
	ds_bpermute_b32 v81, v83, v58
	s_waitcnt lgkmcnt(0)
	v_add_f32_e32 v58, v58, v81
	ds_bpermute_b32 v81, v84, v58
	s_waitcnt lgkmcnt(0)
	v_add_f32_e32 v58, v58, v81
	ds_bpermute_b32 v81, v85, v58
	s_waitcnt lgkmcnt(0)
	v_add_f32_e32 v58, v58, v81
	ds_bpermute_b32 v108, v86, v58
	v_ashrrev_i32_e32 v81, 31, v80
	v_lshlrev_b64 v[80:81], 11, v[80:81]
	v_lshl_add_u64 v[80:81], v[62:63], 0, v[80:81]
	s_waitcnt lgkmcnt(0)
	v_add_f32_e32 v58, v58, v108
	v_fmamk_f32 v58, v58, 0x3a800000, v79
	v_mul_f32_e32 v90, 0x4b800000, v58
	v_cmp_gt_f32_e32 vcc, s3, v58
	v_mov_b32_e32 v108, v94
	s_nop 0
	v_cndmask_b32_e32 v58, v58, v90, vcc
	v_rsq_f32_e32 v58, v58
	s_nop 0
	v_mul_f32_e32 v90, 0x45800000, v58
	v_cndmask_b32_e32 v58, v58, v90, vcc
	v_pk_mul_f32 v[98:99], v[58:59], v[98:99] op_sel_hi:[0,1]
	s_waitcnt vmcnt(2)
	v_pk_fma_f32 v[98:99], v[42:43], v[98:99], v[22:23]
	v_pk_mul_f32 v[90:91], v[58:59], v[92:93] op_sel_hi:[0,1]
	v_pk_mul_f32 v[92:93], v[58:59], v[96:97] op_sel_hi:[0,1]
	v_pk_fma_f32 v[94:95], v[48:49], v[92:93], v[20:21]
	v_pk_fma_f32 v[92:93], v[46:47], v[90:91], v[18:19]
	v_pk_mul_f32 v[108:109], v[58:59], v[108:109] op_sel_hi:[0,1]
	v_pk_fma_f32 v[108:109], v[44:45], v[108:109], v[24:25]
	v_cvt_pk_bf16_f32 v90, v98, v99
	v_cvt_pk_bf16_f32 v91, v108, v109
	v_cvt_pk_bf16_f32 v92, v92, v93
	v_cvt_pk_bf16_f32 v93, v94, v95
	global_store_dwordx4 v[80:81], v[90:93], off
	s_nop 1
	v_mov_b32_e32 v90, v101
	v_mov_b32_e32 v91, v103
	v_pk_mul_f32 v[90:91], v[58:59], v[90:91] op_sel_hi:[0,1]
	v_mov_b32_e32 v92, v105
	v_mov_b32_e32 v93, v107
	s_waitcnt vmcnt(1)
	v_pk_fma_f32 v[90:91], v[50:51], v[90:91], v[34:35]
	v_mov_b32_e32 v101, v102
	v_mov_b32_e32 v105, v106
	v_pk_mul_f32 v[92:93], v[58:59], v[92:93] op_sel_hi:[0,1]
	v_pk_mul_f32 v[94:95], v[58:59], v[100:101] op_sel_hi:[0,1]
	v_pk_mul_f32 v[96:97], v[58:59], v[104:105] op_sel_hi:[0,1]
	v_pk_fma_f32 v[92:93], v[52:53], v[92:93], v[36:37]
	v_cvt_pk_bf16_f32 v90, v90, v91
	v_pk_fma_f32 v[94:95], v[54:55], v[94:95], v[30:31]
	v_cvt_pk_bf16_f32 v91, v92, v93
	v_pk_fma_f32 v[96:97], v[56:57], v[96:97], v[32:33]
	v_cvt_pk_bf16_f32 v92, v94, v95
	v_cvt_pk_bf16_f32 v93, v96, v97
	global_store_dwordx4 v[80:81], v[90:93], off offset:1024

.LBB0_1280:
	s_or_b64 exec, exec, s[8:9]
	v_lshlrev_b32_e32 v102, 6, v1
	s_lshl_b32 s8, s20, 8
	v_add3_u32 v177, v176, s8, v102
	s_waitcnt lgkmcnt(0)
	v_cndmask_b32_e64 v103, v187, v143, s[6:7]
	v_cndmask_b32_e64 v102, v113, v142, s[6:7]
	v_cmp_eq_u32_e32 vcc, 15, v176
	s_waitcnt vmcnt(0)
	v_pk_mul_f32 v[102:103], v[98:99], v[102:103]
	v_cndmask_b32_e64 v105, v189, v145, s[6:7]
	v_cndmask_b32_e32 v113, v112, v190, vcc
	v_cndmask_b32_e32 v112, v110, v188, vcc
	v_pk_fma_f32 v[102:103], v[138:139], v[94:95], v[102:103]
	v_cndmask_b32_e64 v104, v186, v144, s[6:7]
	v_pk_fma_f32 v[102:103], v[82:83], v[112:113], v[102:103]
	v_pk_mul_f32 v[104:105], v[100:101], v[104:105]
	v_pk_add_f32 v[102:103], v[86:87], v[102:103]
	v_cndmask_b32_e32 v143, v185, v192, vcc
	v_cndmask_b32_e32 v142, v111, v191, vcc
	v_pk_fma_f32 v[104:105], v[140:141], v[96:97], v[104:105]
	v_pk_mul_f32 v[90:91], v[90:91], v[102:103]
	v_cmp_eq_u32_e64 s[8:9], 1, v1
	v_pk_fma_f32 v[104:105], v[84:85], v[142:143], v[104:105]
	v_pk_add_f32 v[104:105], v[88:89], v[104:105]
	v_pk_mul_f32 v[92:93], v[92:93], v[104:105]
	v_cvt_pk_bf16_f32 v90, v90, v91
	v_bfe_u32 v1, v92, 16, 1
	v_add3_u32 v1, v92, v1, s58
	v_bfe_u32 v91, v93, 16, 1
	v_pk_mul_f32 v[60:61], v[60:61], v[72:73]
	v_pk_mul_f32 v[56:57], v[56:57], v[68:69]
	v_pk_mul_f32 v[68:69], v[74:75], v[78:79]
	v_mov_b32_dpp v78, v106 row_ror:1 row_mask:0xf bank_mask:0xf bound_ctrl:1
	v_mov_b32_dpp v79, v107 row_ror:1 row_mask:0xf bank_mask:0xf bound_ctrl:1
	v_mov_b32_dpp v72, v138 row_ror:1 row_mask:0xf bank_mask:0xf bound_ctrl:1
	v_mov_b32_dpp v73, v139 row_ror:1 row_mask:0xf bank_mask:0xf bound_ctrl:1
	v_lshrrev_b32_e32 v1, 16, v1
	v_add3_u32 v91, v93, v91, s58
	v_cndmask_b32_e64 v73, v79, v73, s[6:7]
	v_cndmask_b32_e64 v72, v78, v72, s[6:7]
	v_and_or_b32 v91, v91, s59, v1
	v_mov_b32_dpp v1, v106 row_ror:15 row_mask:0xf bank_mask:0xf bound_ctrl:1
	v_mov_b32_dpp v74, v107 row_ror:15 row_mask:0xf bank_mask:0xf bound_ctrl:1
	v_mov_b32_dpp v102, v68 row_ror:15 row_mask:0xf bank_mask:0xf bound_ctrl:1
	v_mov_b32_dpp v103, v69 row_ror:15 row_mask:0xf bank_mask:0xf bound_ctrl:1
	v_pk_mul_f32 v[72:73], v[98:99], v[72:73]
	v_cndmask_b32_e32 v75, v74, v103, vcc
	v_pk_fma_f32 v[72:73], v[106:107], v[94:95], v[72:73]
	v_cndmask_b32_e32 v74, v1, v102, vcc
	v_mul_f32_e32 v1, 0xbfb8aa3b, v50
	v_pk_fma_f32 v[72:73], v[82:83], v[74:75], v[72:73]
	v_exp_f32_e32 v1, v1
	v_mul_f32_e32 v74, 0xbfb8aa3b, v51
	v_exp_f32_e32 v75, v74
	v_pk_mul_f32 v[58:59], v[58:59], v[70:71]
	v_pk_mul_f32 v[54:55], v[54:55], v[66:67]
	v_pk_mul_f32 v[66:67], v[76:77], v[80:81]
	v_mov_b32_dpp v80, v108 row_ror:1 row_mask:0xf bank_mask:0xf bound_ctrl:1
	v_mov_b32_dpp v81, v109 row_ror:1 row_mask:0xf bank_mask:0xf bound_ctrl:1
	v_mov_b32_dpp v70, v140 row_ror:1 row_mask:0xf bank_mask:0xf bound_ctrl:1
	v_mov_b32_dpp v71, v141 row_ror:1 row_mask:0xf bank_mask:0xf bound_ctrl:1
	v_cndmask_b32_e64 v71, v81, v71, s[6:7]
	v_cndmask_b32_e64 v70, v80, v70, s[6:7]
	v_mov_b32_dpp v76, v108 row_ror:15 row_mask:0xf bank_mask:0xf bound_ctrl:1
	v_mov_b32_dpp v77, v109 row_ror:15 row_mask:0xf bank_mask:0xf bound_ctrl:1
	v_mov_b32_dpp v104, v66 row_ror:15 row_mask:0xf bank_mask:0xf bound_ctrl:1
	v_mov_b32_dpp v105, v67 row_ror:15 row_mask:0xf bank_mask:0xf bound_ctrl:1
	v_pk_mul_f32 v[70:71], v[100:101], v[70:71]
	v_add_f32_e32 v1, 1.0, v1
	v_pk_fma_f32 v[70:71], v[108:109], v[96:97], v[70:71]
	v_cndmask_b32_e32 v77, v77, v105, vcc
	v_cndmask_b32_e32 v76, v76, v104, vcc
	v_rcp_f32_e32 v74, v1
	v_add_f32_e32 v1, 1.0, v75
	v_mul_f32_e32 v75, 0xbfb8aa3b, v52
	v_pk_fma_f32 v[70:71], v[84:85], v[76:77], v[70:71]
	v_exp_f32_e32 v76, v75
	v_mul_f32_e32 v75, 0xbfb8aa3b, v53
	v_exp_f32_e32 v77, v75
	v_rcp_f32_e32 v75, v1
	v_add_f32_e32 v1, 1.0, v76
	v_rcp_f32_e32 v76, v1
	v_add_f32_e32 v1, 1.0, v77
	v_rcp_f32_e32 v77, v1
	v_pk_add_f32 v[70:71], v[88:89], v[70:71]
	v_pk_mul_f32 v[50:51], v[50:51], v[74:75]
	v_pk_add_f32 v[72:73], v[86:87], v[72:73]
	v_pk_mul_f32 v[52:53], v[52:53], v[76:77]
	v_pk_mul_f32 v[50:51], v[62:63], v[50:51]
	v_pk_mul_f32 v[52:53], v[64:65], v[52:53]
	v_pk_mul_f32 v[50:51], v[50:51], v[72:73]
	v_pk_mul_f32 v[52:53], v[52:53], v[70:71]
	v_and_b32_e32 v154, 1, v154
	v_cvt_pk_bf16_f32 v93, v52, v53
	v_mul_f32_e32 v72, 0xbfb8aa3b, v44
	v_mul_f32_e32 v73, 0xbfb8aa3b, v45
	v_lshlrev_b32_e32 v76, 4, v154
	v_mul_f32_e32 v62, 0xbfb8aa3b, v42
	v_mul_f32_e32 v71, 0xbfb8aa3b, v43
	v_exp_f32_e32 v72, v72
	v_exp_f32_e32 v73, v73
	v_cvt_pk_bf16_f32 v92, v50, v51
	v_add_u32_e32 v50, v177, v76
	v_exp_f32_e32 v70, v62
	v_exp_f32_e32 v71, v71
	v_ashrrev_i32_e32 v51, 31, v50
	v_lshlrev_b64 v[50:51], 12, v[50:51]
	v_lshl_add_u64 v[52:53], v[156:157], 0, v[50:51]
	v_lshlrev_b64 v[50:51], 1, v[174:175]
	v_add_f32_e32 v72, 1.0, v72
	v_add_f32_e32 v73, 1.0, v73
	v_lshl_add_u64 v[52:53], v[52:53], 0, v[50:51]
	v_lshlrev_b32_e32 v1, 3, v154
	v_add_f32_e32 v70, 1.0, v70
	v_add_f32_e32 v71, 1.0, v71
	v_rcp_f32_e32 v72, v72
	v_rcp_f32_e32 v73, v73
	v_sub_co_u32_e64 v52, s[14:15], v52, v1
	v_rcp_f32_e32 v70, v70
	v_rcp_f32_e32 v71, v71
	v_permlane16_swap_b32_e32 v90, v92
	v_permlane16_swap_b32_e32 v91, v93
	v_subbrev_co_u32_e64 v53, s[14:15], 0, v53, s[14:15]
	global_store_dwordx4 v[52:53], v[90:93], off
	v_mov_b32_dpp v77, v68 row_ror:1 row_mask:0xf bank_mask:0xf bound_ctrl:1
	v_cndmask_b32_e64 v52, v77, v78, s[6:7]
	v_mov_b32_dpp v90, v69 row_ror:1 row_mask:0xf bank_mask:0xf bound_ctrl:1
	v_mov_b32_dpp v91, v66 row_ror:1 row_mask:0xf bank_mask:0xf bound_ctrl:1
	v_mov_b32_dpp v92, v67 row_ror:1 row_mask:0xf bank_mask:0xf bound_ctrl:1
	v_cndmask_b32_e64 v53, v90, v79, s[6:7]
	v_pk_mul_f32 v[44:45], v[44:45], v[72:73]
	v_mov_b32_dpp v93, v130 row_ror:15 row_mask:0xf bank_mask:0xf bound_ctrl:1
	v_mov_b32_dpp v106, v131 row_ror:15 row_mask:0xf bank_mask:0xf bound_ctrl:1
	v_cndmask_b32_e64 v63, v92, v81, s[6:7]
	v_cndmask_b32_e64 v62, v91, v80, s[6:7]
	v_pk_mul_f32 v[42:43], v[42:43], v[70:71]
	v_pk_mul_f32 v[44:45], v[48:49], v[44:45]
	v_pk_mul_f32 v[48:49], v[98:99], v[52:53]
	v_mov_b32_dpp v107, v132 row_ror:15 row_mask:0xf bank_mask:0xf bound_ctrl:1
	v_mov_b32_dpp v108, v133 row_ror:15 row_mask:0xf bank_mask:0xf bound_ctrl:1
	v_cndmask_b32_e32 v65, v103, v106, vcc
	v_cndmask_b32_e32 v64, v102, v93, vcc
	v_pk_mul_f32 v[42:43], v[46:47], v[42:43]
	v_pk_mul_f32 v[46:47], v[100:101], v[62:63]
	v_pk_fma_f32 v[48:49], v[68:69], v[94:95], v[48:49]
	v_cndmask_b32_e32 v75, v105, v108, vcc
	v_cndmask_b32_e32 v74, v104, v107, vcc
	v_pk_fma_f32 v[46:47], v[66:67], v[96:97], v[46:47]
	v_pk_fma_f32 v[48:49], v[82:83], v[64:65], v[48:49]
	v_pk_fma_f32 v[46:47], v[84:85], v[74:75], v[46:47]
	v_pk_add_f32 v[48:49], v[86:87], v[48:49]
	v_pk_add_f32 v[46:47], v[88:89], v[46:47]
	v_pk_mul_f32 v[42:43], v[42:43], v[48:49]
	v_pk_mul_f32 v[44:45], v[44:45], v[46:47]
	v_bfe_u32 v46, v42, 16, 1
	v_add3_u32 v42, v42, v46, s58
	v_bfe_u32 v46, v43, 16, 1
	v_add3_u32 v43, v43, v46, s58
	v_mov_b32_dpp v47, v131 row_ror:1 row_mask:0xf bank_mask:0xf bound_ctrl:1
	v_mov_b32_dpp v46, v130 row_ror:1 row_mask:0xf bank_mask:0xf bound_ctrl:1
	v_lshrrev_b32_e32 v42, 16, v42
	v_cndmask_b32_e64 v47, v47, v90, s[6:7]
	v_cndmask_b32_e64 v46, v46, v77, s[6:7]
	v_and_or_b32 v42, v43, s59, v42
	v_bfe_u32 v43, v44, 16, 1
	v_pk_mul_f32 v[46:47], v[98:99], v[46:47]
	v_add3_u32 v43, v44, v43, s58
	v_bfe_u32 v44, v45, 16, 1
	v_pk_fma_f32 v[46:47], v[130:131], v[94:95], v[46:47]
	v_cndmask_b32_e32 v53, v106, v135, vcc
	v_cndmask_b32_e32 v52, v93, v134, vcc
	v_lshrrev_b32_e32 v43, 16, v43
	v_add3_u32 v44, v45, v44, s58
	v_pk_fma_f32 v[46:47], v[82:83], v[52:53], v[46:47]
	v_mul_f32_e32 v52, 0xbfb8aa3b, v34
	v_mul_f32_e32 v53, 0xbfb8aa3b, v35
	v_and_or_b32 v43, v44, s59, v43
	v_mov_b32_dpp v44, v132 row_ror:1 row_mask:0xf bank_mask:0xf bound_ctrl:1
	v_mov_b32_dpp v45, v133 row_ror:1 row_mask:0xf bank_mask:0xf bound_ctrl:1
	v_exp_f32_e32 v52, v52
	v_exp_f32_e32 v53, v53
	v_cndmask_b32_e64 v45, v45, v92, s[6:7]
	v_cndmask_b32_e64 v44, v44, v91, s[6:7]
	v_pk_mul_f32 v[44:45], v[100:101], v[44:45]
	v_cndmask_b32_e32 v49, v108, v137, vcc
	v_pk_fma_f32 v[44:45], v[132:133], v[96:97], v[44:45]
	v_cndmask_b32_e32 v48, v107, v136, vcc
	v_pk_fma_f32 v[44:45], v[84:85], v[48:49], v[44:45]
	v_add_f32_e32 v48, 1.0, v52
	v_add_f32_e32 v49, 1.0, v53
	v_mul_f32_e32 v52, 0xbfb8aa3b, v36
	v_mul_f32_e32 v53, 0xbfb8aa3b, v37
	v_exp_f32_e32 v52, v52
	v_exp_f32_e32 v53, v53
	v_rcp_f32_e32 v48, v48
	v_rcp_f32_e32 v49, v49
	v_add_f32_e32 v52, 1.0, v52
	v_add_f32_e32 v53, 1.0, v53
	v_rcp_f32_e32 v52, v52
	v_rcp_f32_e32 v53, v53
	v_pk_add_f32 v[44:45], v[88:89], v[44:45]
	v_pk_mul_f32 v[34:35], v[34:35], v[48:49]
	v_pk_add_f32 v[46:47], v[86:87], v[46:47]
	v_pk_mul_f32 v[36:37], v[36:37], v[52:53]
	v_pk_mul_f32 v[34:35], v[38:39], v[34:35]
	v_pk_mul_f32 v[36:37], v[40:41], v[36:37]
	v_pk_mul_f32 v[34:35], v[34:35], v[46:47]
	v_pk_mul_f32 v[36:37], v[36:37], v[44:45]
	v_or_b32_e32 v46, 32, v76
	v_bfe_u32 v38, v37, 16, 1
	v_add3_u32 v37, v37, v38, s58
	v_bfe_u32 v38, v36, 16, 1
	v_add3_u32 v36, v36, v38, s58
	v_lshrrev_b32_e32 v36, 16, v36
	v_and_or_b32 v45, v37, s59, v36
	v_cvt_pk_bf16_f32 v44, v34, v35
	v_add_u32_e32 v34, v46, v177
	v_ashrrev_i32_e32 v35, 31, v34
	v_lshlrev_b64 v[34:35], 12, v[34:35]
	v_lshl_add_u64 v[34:35], v[156:157], 0, v[34:35]
	v_mul_f32_e32 v40, 0xbfb8aa3b, v26
	v_mul_f32_e32 v41, 0xbfb8aa3b, v27
	v_lshl_add_u64 v[34:35], v[34:35], 0, v[50:51]
	v_exp_f32_e32 v40, v40
	v_exp_f32_e32 v41, v41
	v_sub_co_u32_e64 v34, s[14:15], v34, v1
	v_permlane16_swap_b32_e32 v42, v44
	v_permlane16_swap_b32_e32 v43, v45
	v_subbrev_co_u32_e64 v35, s[14:15], 0, v35, s[14:15]
	global_store_dwordx4 v[34:35], v[42:45], off
	v_add_f32_e32 v40, 1.0, v40
	v_add_f32_e32 v41, 1.0, v41
	v_mul_f32_e32 v42, 0xbfb8aa3b, v28
	v_mul_f32_e32 v43, 0xbfb8aa3b, v29
	v_exp_f32_e32 v42, v42
	v_exp_f32_e32 v43, v43
	v_rcp_f32_e32 v40, v40
	v_rcp_f32_e32 v41, v41
	v_mov_b32_dpp v48, v122 row_ror:1 row_mask:0xf bank_mask:0xf bound_ctrl:1
	v_mov_b32_dpp v49, v123 row_ror:1 row_mask:0xf bank_mask:0xf bound_ctrl:1
	v_add_f32_e32 v42, 1.0, v42
	v_add_f32_e32 v43, 1.0, v43
	v_cndmask_b32_e64 v37, v49, v127, s[6:7]
	v_cndmask_b32_e64 v36, v48, v126, s[6:7]
	v_rcp_f32_e32 v42, v42
	v_rcp_f32_e32 v43, v43
	v_pk_mul_f32 v[26:27], v[26:27], v[40:41]
	v_mov_b32_dpp v38, v122 row_ror:15 row_mask:0xf bank_mask:0xf bound_ctrl:1
	v_mov_b32_dpp v39, v123 row_ror:15 row_mask:0xf bank_mask:0xf bound_ctrl:1
	v_mov_b32_dpp v62, v58 row_ror:15 row_mask:0xf bank_mask:0xf bound_ctrl:1
	v_mov_b32_dpp v63, v59 row_ror:15 row_mask:0xf bank_mask:0xf bound_ctrl:1
	v_pk_mul_f32 v[26:27], v[30:31], v[26:27]
	v_pk_mul_f32 v[30:31], v[98:99], v[36:37]
	v_cndmask_b32_e32 v39, v39, v63, vcc
	v_cndmask_b32_e32 v38, v38, v62, vcc
	v_pk_fma_f32 v[30:31], v[122:123], v[94:95], v[30:31]
	v_mov_b32_dpp v52, v124 row_ror:1 row_mask:0xf bank_mask:0xf bound_ctrl:1
	v_mov_b32_dpp v53, v125 row_ror:1 row_mask:0xf bank_mask:0xf bound_ctrl:1
	v_pk_fma_f32 v[30:31], v[82:83], v[38:39], v[30:31]
	v_cndmask_b32_e64 v35, v53, v129, s[6:7]
	v_cndmask_b32_e64 v34, v52, v128, s[6:7]
	v_pk_mul_f32 v[28:29], v[28:29], v[42:43]
	v_pk_add_f32 v[30:31], v[86:87], v[30:31]
	v_mov_b32_dpp v44, v124 row_ror:15 row_mask:0xf bank_mask:0xf bound_ctrl:1
	v_mov_b32_dpp v45, v125 row_ror:15 row_mask:0xf bank_mask:0xf bound_ctrl:1
	v_mov_b32_dpp v64, v60 row_ror:15 row_mask:0xf bank_mask:0xf bound_ctrl:1
	v_mov_b32_dpp v65, v61 row_ror:15 row_mask:0xf bank_mask:0xf bound_ctrl:1
	v_pk_mul_f32 v[28:29], v[32:33], v[28:29]
	v_pk_mul_f32 v[32:33], v[100:101], v[34:35]
	v_pk_mul_f32 v[26:27], v[26:27], v[30:31]
	v_cndmask_b32_e32 v45, v45, v65, vcc
	v_cndmask_b32_e32 v44, v44, v64, vcc
	v_pk_fma_f32 v[32:33], v[124:125], v[96:97], v[32:33]
	v_pk_fma_f32 v[32:33], v[84:85], v[44:45], v[32:33]
	v_mov_b32_dpp v36, v58 row_ror:1 row_mask:0xf bank_mask:0xf bound_ctrl:1
	v_mov_b32_dpp v37, v59 row_ror:1 row_mask:0xf bank_mask:0xf bound_ctrl:1
	v_pk_add_f32 v[32:33], v[88:89], v[32:33]
	v_cndmask_b32_e64 v31, v37, v49, s[6:7]
	v_cndmask_b32_e64 v30, v36, v48, s[6:7]
	v_pk_mul_f32 v[28:29], v[28:29], v[32:33]
	v_mov_b32_dpp v40, v54 row_ror:15 row_mask:0xf bank_mask:0xf bound_ctrl:1
	v_mov_b32_dpp v41, v55 row_ror:15 row_mask:0xf bank_mask:0xf bound_ctrl:1
	v_pk_mul_f32 v[30:31], v[98:99], v[30:31]
	v_cvt_pk_bf16_f32 v26, v26, v27
	v_pk_fma_f32 v[30:31], v[58:59], v[94:95], v[30:31]
	v_cndmask_b32_e32 v35, v63, v41, vcc
	v_cndmask_b32_e32 v34, v62, v40, vcc
	v_pk_fma_f32 v[30:31], v[82:83], v[34:35], v[30:31]
	v_mul_f32_e32 v34, 0xbfb8aa3b, v18
	v_mul_f32_e32 v35, 0xbfb8aa3b, v19
	v_mov_b32_dpp v38, v60 row_ror:1 row_mask:0xf bank_mask:0xf bound_ctrl:1
	v_mov_b32_dpp v39, v61 row_ror:1 row_mask:0xf bank_mask:0xf bound_ctrl:1
	v_exp_f32_e32 v34, v34
	v_exp_f32_e32 v35, v35
	v_cvt_pk_bf16_f32 v27, v28, v29
	v_cndmask_b32_e64 v29, v39, v53, s[6:7]
	v_cndmask_b32_e64 v28, v38, v52, s[6:7]
	v_mov_b32_dpp v42, v56 row_ror:15 row_mask:0xf bank_mask:0xf bound_ctrl:1
	v_mov_b32_dpp v43, v57 row_ror:15 row_mask:0xf bank_mask:0xf bound_ctrl:1
	v_pk_mul_f32 v[28:29], v[100:101], v[28:29]
	v_cndmask_b32_e32 v33, v65, v43, vcc
	v_pk_fma_f32 v[28:29], v[60:61], v[96:97], v[28:29]
	v_cndmask_b32_e32 v32, v64, v42, vcc
	v_pk_fma_f32 v[28:29], v[84:85], v[32:33], v[28:29]
	v_add_f32_e32 v32, 1.0, v34
	v_add_f32_e32 v33, 1.0, v35
	v_mul_f32_e32 v34, 0xbfb8aa3b, v20
	v_mul_f32_e32 v35, 0xbfb8aa3b, v21
	v_exp_f32_e32 v34, v34
	v_exp_f32_e32 v35, v35
	v_rcp_f32_e32 v32, v32
	v_rcp_f32_e32 v33, v33
	v_add_f32_e32 v34, 1.0, v34
	v_add_f32_e32 v35, 1.0, v35
	v_rcp_f32_e32 v34, v34
	v_rcp_f32_e32 v35, v35
	v_pk_add_f32 v[28:29], v[88:89], v[28:29]
	v_pk_mul_f32 v[18:19], v[18:19], v[32:33]
	v_pk_add_f32 v[30:31], v[86:87], v[30:31]
	v_pk_mul_f32 v[20:21], v[20:21], v[34:35]
	v_pk_mul_f32 v[18:19], v[22:23], v[18:19]
	v_pk_mul_f32 v[20:21], v[24:25], v[20:21]
	v_pk_mul_f32 v[18:19], v[18:19], v[30:31]
	v_pk_mul_f32 v[20:21], v[20:21], v[28:29]
	v_add_u32_e32 v47, 0x80, v177
	v_cvt_pk_bf16_f32 v29, v20, v21
	v_cvt_pk_bf16_f32 v28, v18, v19
	v_add_u32_e32 v18, v47, v76
	v_ashrrev_i32_e32 v19, 31, v18
	v_lshlrev_b64 v[18:19], 12, v[18:19]
	v_lshl_add_u64 v[18:19], v[156:157], 0, v[18:19]
	v_lshl_add_u64 v[18:19], v[18:19], 0, v[50:51]
	v_sub_co_u32_e64 v18, s[14:15], v18, v1
	v_permlane16_swap_b32_e32 v26, v28
	v_permlane16_swap_b32_e32 v27, v29
	v_subbrev_co_u32_e64 v19, s[14:15], 0, v19, s[14:15]
	global_store_dwordx4 v[18:19], v[26:29], off
	v_mul_f32_e32 v20, 0xbfb8aa3b, v10
	v_mul_f32_e32 v25, 0xbfb8aa3b, v11
	v_mul_f32_e32 v26, 0xbfb8aa3b, v12
	v_mul_f32_e32 v27, 0xbfb8aa3b, v13
	v_exp_f32_e32 v26, v26
	v_exp_f32_e32 v27, v27
	v_exp_f32_e32 v24, v20
	v_exp_f32_e32 v25, v25
	v_add_f32_e32 v26, 1.0, v26
	v_add_f32_e32 v27, 1.0, v27
	v_add_f32_e32 v24, 1.0, v24
	v_add_f32_e32 v25, 1.0, v25
	v_rcp_f32_e32 v26, v26
	v_rcp_f32_e32 v27, v27
	v_rcp_f32_e32 v24, v24
	v_rcp_f32_e32 v25, v25
	v_mov_b32_dpp v30, v54 row_ror:1 row_mask:0xf bank_mask:0xf bound_ctrl:1
	v_mov_b32_dpp v31, v55 row_ror:1 row_mask:0xf bank_mask:0xf bound_ctrl:1
	v_mov_b32_dpp v32, v56 row_ror:1 row_mask:0xf bank_mask:0xf bound_ctrl:1
	v_mov_b32_dpp v33, v57 row_ror:1 row_mask:0xf bank_mask:0xf bound_ctrl:1
	v_cndmask_b32_e64 v21, v31, v37, s[6:7]
	v_cndmask_b32_e64 v20, v30, v36, s[6:7]
	v_pk_mul_f32 v[12:13], v[12:13], v[26:27]
	v_mov_b32_dpp v34, v114 row_ror:15 row_mask:0xf bank_mask:0xf bound_ctrl:1
	v_mov_b32_dpp v35, v115 row_ror:15 row_mask:0xf bank_mask:0xf bound_ctrl:1
	v_cndmask_b32_e64 v19, v33, v39, s[6:7]
	v_cndmask_b32_e64 v18, v32, v38, s[6:7]
	v_pk_mul_f32 v[10:11], v[10:11], v[24:25]
	v_pk_mul_f32 v[12:13], v[16:17], v[12:13]
	v_pk_mul_f32 v[16:17], v[98:99], v[20:21]
	v_mov_b32_dpp v44, v116 row_ror:15 row_mask:0xf bank_mask:0xf bound_ctrl:1
	v_mov_b32_dpp v45, v117 row_ror:15 row_mask:0xf bank_mask:0xf bound_ctrl:1
	v_cndmask_b32_e32 v23, v41, v35, vcc
	v_cndmask_b32_e32 v22, v40, v34, vcc
	v_pk_mul_f32 v[10:11], v[14:15], v[10:11]
	v_pk_mul_f32 v[14:15], v[100:101], v[18:19]
	v_pk_fma_f32 v[16:17], v[54:55], v[94:95], v[16:17]
	v_cndmask_b32_e32 v29, v43, v45, vcc
	v_cndmask_b32_e32 v28, v42, v44, vcc
	v_pk_fma_f32 v[14:15], v[56:57], v[96:97], v[14:15]
	v_pk_fma_f32 v[16:17], v[82:83], v[22:23], v[16:17]
	v_pk_fma_f32 v[14:15], v[84:85], v[28:29], v[14:15]
	v_pk_add_f32 v[16:17], v[86:87], v[16:17]
	v_pk_add_f32 v[14:15], v[88:89], v[14:15]
	v_pk_mul_f32 v[10:11], v[10:11], v[16:17]
	v_pk_mul_f32 v[12:13], v[12:13], v[14:15]
	v_cvt_pk_bf16_f32 v10, v10, v11
	v_cvt_pk_bf16_f32 v11, v12, v13
	v_mul_f32_e32 v12, 0xbfb8aa3b, v2
	v_mul_f32_e32 v13, 0xbfb8aa3b, v3
	v_exp_f32_e32 v12, v12
	v_exp_f32_e32 v13, v13
	v_mul_f32_e32 v14, 0xbfb8aa3b, v4
	v_mul_f32_e32 v15, 0xbfb8aa3b, v5
	v_add_f32_e32 v12, 1.0, v12
	v_add_f32_e32 v13, 1.0, v13
	v_exp_f32_e32 v14, v14
	v_exp_f32_e32 v15, v15
	v_rcp_f32_e32 v12, v12
	v_rcp_f32_e32 v13, v13
	v_add_f32_e32 v14, 1.0, v14
	v_add_f32_e32 v15, 1.0, v15
	v_rcp_f32_e32 v14, v14
	v_rcp_f32_e32 v15, v15
	v_mov_b32_dpp v18, v116 row_ror:1 row_mask:0xf bank_mask:0xf bound_ctrl:1
	v_mov_b32_dpp v19, v117 row_ror:1 row_mask:0xf bank_mask:0xf bound_ctrl:1
	v_pk_mul_f32 v[2:3], v[2:3], v[12:13]
	v_cndmask_b32_e32 v13, v45, v121, vcc
	v_pk_mul_f32 v[2:3], v[6:7], v[2:3]
	v_cndmask_b32_e64 v7, v19, v33, s[6:7]
	v_cndmask_b32_e64 v6, v18, v32, s[6:7]
	v_pk_mul_f32 v[6:7], v[100:101], v[6:7]
	v_cndmask_b32_e32 v12, v44, v120, vcc
	v_pk_fma_f32 v[6:7], v[116:117], v[96:97], v[6:7]
	v_mov_b32_dpp v16, v114 row_ror:1 row_mask:0xf bank_mask:0xf bound_ctrl:1
	v_mov_b32_dpp v17, v115 row_ror:1 row_mask:0xf bank_mask:0xf bound_ctrl:1
	v_pk_mul_f32 v[4:5], v[4:5], v[14:15]
	v_pk_fma_f32 v[6:7], v[84:85], v[12:13], v[6:7]
	v_pk_mul_f32 v[4:5], v[8:9], v[4:5]
	v_cndmask_b32_e64 v9, v17, v31, s[6:7]
	v_cndmask_b32_e64 v8, v16, v30, s[6:7]
	v_pk_add_f32 v[6:7], v[88:89], v[6:7]
	v_pk_mul_f32 v[8:9], v[98:99], v[8:9]
	v_pk_mul_f32 v[6:7], v[4:5], v[6:7]
	v_pk_fma_f32 v[8:9], v[114:115], v[94:95], v[8:9]
	v_cndmask_b32_e32 v15, v35, v119, vcc
	v_cndmask_b32_e32 v14, v34, v118, vcc
	v_pk_fma_f32 v[8:9], v[82:83], v[14:15], v[8:9]
	v_pk_add_f32 v[8:9], v[86:87], v[8:9]
	v_pk_mul_f32 v[8:9], v[2:3], v[8:9]
	v_cvt_pk_bf16_f32 v13, v6, v7
	v_cvt_pk_bf16_f32 v12, v8, v9
	v_add_u32_e32 v6, v47, v46
	v_ashrrev_i32_e32 v7, 31, v6
	v_lshlrev_b64 v[6:7], 12, v[6:7]
	v_lshl_add_u64 v[6:7], v[156:157], 0, v[6:7]
	v_lshl_add_u64 v[6:7], v[6:7], 0, v[50:51]
	v_cmp_lt_i32_e64 s[10:11], 13, v176
	v_sub_co_u32_e64 v6, s[6:7], v6, v1
	v_permlane16_swap_b32_e32 v10, v12
	v_permlane16_swap_b32_e32 v11, v13
	v_subbrev_co_u32_e64 v7, s[6:7], 0, v7, s[6:7]
	s_and_b64 s[8:9], s[8:9], s[10:11]
	global_store_dwordx4 v[6:7], v[10:13], off
	s_and_saveexec_b64 s[6:7], s[8:9]
	s_cbranch_execz .LBB0_1283
	s_add_u32 s8, s48, 2
	s_addc_u32 s9, s49, 0
	v_add_u32_e32 v154, -14, v176
	v_lshl_add_u64 v[6:7], s[8:9], 0, v[154:155]
	v_lshlrev_b64 v[6:7], 13, v[6:7]
	v_lshl_add_u64 v[6:7], v[158:159], 0, v[6:7]
	v_lshl_add_u64 v[6:7], v[174:175], 2, v[6:7]
	global_store_dwordx4 v[6:7], v[114:117], off
	s_and_b64 exec, exec, vcc
	s_cbranch_execz .LBB0_1283
	v_mad_i64_i32 v[6:7], s[8:9], s20, v184, v[158:159]
	v_lshl_add_u64 v[6:7], v[174:175], 2, v[6:7]
	v_add_co_u32_e32 v6, vcc, 0xa000, v6
	s_nop 1
	v_addc_co_u32_e32 v7, vcc, 0, v7, vcc
	global_store_dwordx4 v[6:7], v[2:5], off

.LBB0_1355:
	s_or_b64 exec, exec, s[40:41]
	global_load_dwordx4 v[34:37], v[24:25], off
	s_nop 0
	global_load_dwordx4 v[24:27], v[26:27], off
	v_lshl_add_u64 v[30:31], v[22:23], 0, v[30:31]
	global_load_dwordx4 v[38:41], v[30:31], off
	v_lshl_add_u64 v[22:23], v[22:23], 0, v[28:29]
	global_load_dwordx4 v[28:31], v[22:23], off
	v_lshlrev_b64 v[22:23], 12, v[18:19]
	v_lshlrev_b32_e32 v18, 1, v33
	v_lshl_add_u64 v[22:23], s[12:13], 0, v[22:23]
	s_waitcnt vmcnt(3)
	v_pk_mul_f32 v[16:17], v[16:17], v[36:37]
	v_pk_mul_f32 v[14:15], v[14:15], v[34:35]
	s_waitcnt vmcnt(2)
	v_pk_fma_f32 v[12:13], v[12:13], v[26:27], v[16:17]
	v_pk_fma_f32 v[10:11], v[10:11], v[24:25], v[14:15]
	s_waitcnt vmcnt(1)
	v_pk_fma_f32 v[4:5], v[4:5], v[40:41], v[12:13]
	v_pk_fma_f32 v[2:3], v[2:3], v[38:39], v[10:11]
	v_pk_add_f32 v[4:5], v[8:9], v[4:5]
	v_pk_add_f32 v[2:3], v[6:7], v[2:3]
	s_waitcnt vmcnt(0)
	v_pk_mul_f32 v[4:5], v[30:31], v[4:5]
	v_pk_mul_f32 v[2:3], v[28:29], v[2:3]
	v_cvt_pk_bf16_f32 v2, v2, v3
	v_cvt_pk_bf16_f32 v3, v4, v5
	v_lshl_add_u64 v[4:5], v[22:23], 0, v[18:19]
	global_store_dwordx2 v[4:5], v[2:3], off
